# v92 + nt (streaming) loads for other once-read data: f32 inputs converted in P0 and the fillers, P4 chunk states, ssd_s3 B/C rows and hprev LDS-DMA, EpiLn residual rows
# baseline (speedup 1.0000x reference)
; template <bool BATCH>
; __device__ __forceinline__ void transpose_tile(const float* __restrict__ src, int ld, int N, int K, int k0, int n0, bfu* __restrict__ dst,
;                                                int blk, int stride, int off, float* tl  ) {
;     const int tid = threadIdx.x;
;     {
;         const int n4 = (tid & 31) * 4, kk = tid >> 5;
;         float4 v[4];
;         if (BATCH) {
;             const int ncl = (n0 + n4 < N) ? n0 + n4 : 0;
; #pragma unroll
;             for (int i = 0; i < 4; ++i) v[i] = *(const float4*)(src + (size_t)(k0 + kk + 16 * i) * ld + ncl);
;         } else {
; #pragma unroll
;             for (int i = 0; i < 4; ++i) v[i] = (n0 + n4 < N) ? *(const float4*)(src + (size_t)(k0 + kk + 16 * i) * ld + n0 + n4) : make_float4(0.f, 0.f, 0.f, 0.f);
;         }
; #pragma unroll
;         for (int i = 0; i < 4; ++i) { float* t = tl + (kk + 16 * i) * 129 + n4; t[0] = v[i].x; t[1] = v[i].y; t[2] = v[i].z; t[3] = v[i].w; }
;     }
;     __syncthreads();
;     {
;         const int k2 = (tid & 31) * 2, nn = tid >> 5;
; #pragma unroll
;         for (int i = 0; i < 8; ++i) {
;             const int nl = nn + 16 * i, ng = n0 + nl;
;             if (ng < N) { const int row = (ng / blk) * stride + (ng % blk) + off; *(unsigned*)(dst + (size_t)row * K + k0 + k2) = pk2(tl[k2 * 129 + nl], tl[(k2 + 1) * 129 + nl]); }
;         }
;     }
;     __syncthreads();
; }
; template <bool BATCH>
; __device__ __forceinline__ void weight_job(const Params& p, int job, float* ldsf) {
;     ...
;     int j = job;
;     if (j < J_IN) { transpose_tile<BATCH>(p.w_in, NIN, 6144, 1024, (j / 48) * 64, (j % 48) * 128, (bfu*)(ws + WS_WIN), BIG, 0, 0, ldsf); return; }
;     j -= J_IN;
;     if (j < J_DT) { transpose_tile<BATCH>(p.w_in + 6144, NIN, 16, 1024, j * 64, 0, (bfu*)(ws + WS_WDT), BIG, 0, 0, ldsf); return; }
;     j -= J_DT;
;     if (j < J_OUT) { transpose_tile<BATCH>(p.w_out, 1024, 1024, 2048, (j / 8) * 64, (j % 8) * 128, (bfu*)(ws + WS_WOUT), BIG, 0, 0, ldsf); return; }
;     j -= J_OUT;
;     if (j < J_G) { transpose_tile<BATCH>(p.w_gate, DFF, DFF, 1024, (j / 22) * 64, (j % 22) * 128, (bfu*)(ws + WS_WGU), 128, 256, 0, ldsf); return; }
;     j -= J_G;
;     if (j < J_U) { transpose_tile<BATCH>(p.w_up, DFF, DFF, 1024, (j / 22) * 64, (j % 22) * 128, (bfu*)(ws + WS_WGU), 128, 256, 128, ldsf); return; }
;     j -= J_U;
.LBB0_7:
	s_cmpk_gt_i32 s37, 0x2ff
	s_mov_b64 s[18:19], -1
	s_cbranch_scc0 .LBB0_34
	s_cmpk_gt_u32 s37, 0x30f
	s_cbranch_scc0 .LBB0_29
	s_cmpk_gt_u32 s37, 0x40f
	s_cbranch_scc0 .LBB0_24
	s_cmpk_gt_u32 s37, 0x56f
	s_cbranch_scc0 .LBB0_19
	s_cmpk_gt_u32 s37, 0x6cf
	s_cbranch_scc0 .LBB0_15
	s_load_dwordx2 s[18:19], s[8:9], 0x98
	s_and_b32 s10, s22, 0x7fffffc0
	s_and_b32 s15, s20, 0x380
	v_or_b32_e32 v17, s15, v2
	v_or_b32_e32 v16, s10, v1
	v_lshlrev_b32_e32 v18, 2, v17
	v_mov_b32_e32 v19, v5
	v_add_u32_e32 v42, 16, v16
	v_mov_b32_e32 v43, v5
	s_waitcnt lgkmcnt(0)
	v_lshl_add_u64 v[18:19], s[18:19], 0, v[18:19]
	v_mov_b32_e32 v17, v5
	v_lshlrev_b64 v[42:43], 12, v[42:43]
	v_lshlrev_b64 v[40:41], 12, v[16:17]
	v_lshl_add_u64 v[44:45], v[18:19], 0, v[42:43]
	v_or_b32_e32 v42, 32, v16
	v_mov_b32_e32 v43, v5
	v_lshl_add_u64 v[40:41], v[18:19], 0, v[40:41]
	v_lshlrev_b64 v[42:43], 12, v[42:43]
	v_lshl_add_u64 v[48:49], v[18:19], 0, v[42:43]
	global_load_dwordx4 v[40:43], v[40:41], off nt
	s_nop 0
	global_load_dwordx4 v[44:47], v[44:45], off nt
	v_add_u32_e32 v16, 48, v16
	v_lshlrev_b64 v[16:17], 12, v[16:17]
	global_load_dwordx4 v[48:51], v[48:49], off nt
	v_lshl_add_u64 v[16:17], v[18:19], 0, v[16:17]
	global_load_dwordx4 v[52:55], v[16:17], off nt
	v_or_b32_e32 v18, s15, v1
	s_lshl_b32 s10, s10, 1
	v_or_b32_e32 v39, s15, v20
	v_or_b32_e32 v56, s15, v21
	v_or_b32_e32 v58, s15, v22
	v_or_b32_e32 v60, s15, v24
	v_or_b32_e32 v62, s15, v25
	v_or_b32_e32 v64, s15, v26
	v_mul_u32_u24_e32 v18, 0xb00, v18
	v_mov_b32_e32 v19, v5
	v_lshl_add_u64 v[16:17], v[8:9], 0, s[10:11]
	v_mul_u32_u24_e32 v39, 0xb00, v39
	v_mul_u32_u24_e32 v66, 0xb00, v56
	v_mul_u32_u24_e32 v68, 0xb00, v58
	v_mul_u32_u24_e32 v69, 0xb00, v60
	v_mul_u32_u24_e32 v70, 0xb00, v62
	v_mul_u32_u24_e32 v71, 0xb00, v64
	v_lshlrev_b32_e32 v18, 1, v18
	v_mov_b32_e32 v57, v5
	v_mov_b32_e32 v59, v5
	v_mov_b32_e32 v61, v5
	v_mov_b32_e32 v63, v5
	v_mov_b32_e32 v65, v5
	v_mov_b32_e32 v67, v5
	v_lshlrev_b32_e32 v56, 1, v39
	v_lshlrev_b32_e32 v58, 1, v66
	v_lshlrev_b32_e32 v60, 1, v68
	v_lshlrev_b32_e32 v62, 1, v69
	v_lshlrev_b32_e32 v64, 1, v70
	v_lshlrev_b32_e32 v66, 1, v71
	v_lshl_add_u64 v[18:19], v[16:17], 0, v[18:19]
	v_lshl_add_u64 v[56:57], v[16:17], 0, v[56:57]
	v_lshl_add_u64 v[58:59], v[16:17], 0, v[58:59]
	v_lshl_add_u64 v[60:61], v[16:17], 0, v[60:61]
	v_lshl_add_u64 v[62:63], v[16:17], 0, v[62:63]
	v_lshl_add_u64 v[64:65], v[16:17], 0, v[64:65]
	s_waitcnt vmcnt(3)
	ds_write2_b32 v3, v40, v41 offset1:1
	ds_write2_b32 v3, v42, v43 offset0:2 offset1:3
	s_waitcnt vmcnt(2)
	ds_write2_b32 v32, v44, v45 offset1:1
	ds_write2_b32 v33, v46, v47 offset1:1
	s_waitcnt vmcnt(1)
	ds_write2_b32 v34, v48, v49 offset1:1
	ds_write2_b32 v35, v50, v51 offset1:1
	s_waitcnt vmcnt(0)
	ds_write2_b32 v36, v52, v53 offset1:1
	ds_write2_b32 v37, v54, v55 offset1:1
	s_waitcnt lgkmcnt(0)
	s_barrier
	ds_read2_b32 v[40:41], v23 offset1:16
	ds_read2_b32 v[42:43], v23 offset0:96 offset1:129
	ds_read2_b32 v[44:45], v23 offset0:145 offset1:161
	ds_read2_b32 v[46:47], v23 offset0:32 offset1:48
	ds_read2_b32 v[48:49], v23 offset0:177 offset1:193
	ds_read2_b32 v[50:51], v23 offset0:64 offset1:80
	ds_read2_b32 v[52:53], v23 offset0:209 offset1:225
	s_waitcnt lgkmcnt(5)
	v_cvt_pk_bf16_f32 v39, v40, v43
	s_waitcnt lgkmcnt(4)
	v_cvt_pk_bf16_f32 v40, v41, v44
	s_waitcnt lgkmcnt(3)
	v_cvt_pk_bf16_f32 v41, v46, v45
	s_waitcnt lgkmcnt(2)
	v_cvt_pk_bf16_f32 v43, v47, v48
	s_waitcnt lgkmcnt(1)
	v_cvt_pk_bf16_f32 v44, v50, v49
	s_waitcnt lgkmcnt(0)
	v_cvt_pk_bf16_f32 v45, v51, v52
	v_cvt_pk_bf16_f32 v42, v42, v53
	global_store_dword v[18:19], v39, off
	global_store_dword v[56:57], v40, off
	global_store_dword v[58:59], v41, off
	global_store_dword v[60:61], v43, off
	global_store_dword v[62:63], v44, off
	global_store_dword v[64:65], v45, off
	v_lshl_add_u64 v[18:19], v[16:17], 0, v[66:67]
	global_store_dword v[18:19], v42, off
	v_add_u32_e32 v18, s15, v27
	v_cmp_gt_u32_e32 vcc, s26, v18
	s_and_saveexec_b64 s[18:19], vcc
	s_cbranch_execz .LBB0_14
	ds_read2_b32 v[40:41], v23 offset0:112 offset1:241
	v_mul_u32_u24_e32 v18, 0xb00, v18
	v_mov_b32_e32 v19, v5
	v_lshlrev_b32_e32 v18, 1, v18
	v_lshl_add_u64 v[16:17], v[16:17], 0, v[18:19]
	s_waitcnt lgkmcnt(0)
	v_cvt_pk_bf16_f32 v39, v40, v41
	global_store_dword v[16:17], v39, off

; __device__ __forceinline__ unsigned pk2(float lo, float hi) { f32x2_t v = {lo, hi}; bf16x2_t b = __builtin_convertvector(v, bf16x2_t); return __builtin_bit_cast(unsigned, b); }
; template <bool BATCH>
; __device__ __forceinline__ void transpose_tile(const float* __restrict__ src, int ld, int N, int K, int k0, int n0, bfu* __restrict__ dst,
;                                                int blk, int stride, int off, float* tl  ) {
;     const int tid = threadIdx.x;
;     {
;         const int n4 = (tid & 31) * 4, kk = tid >> 5;
;         float4 v[4];
;         if (BATCH) {
;             const int ncl = (n0 + n4 < N) ? n0 + n4 : 0;
; #pragma unroll
;             for (int i = 0; i < 4; ++i) v[i] = *(const float4*)(src + (size_t)(k0 + kk + 16 * i) * ld + ncl);
;         } else {
; #pragma unroll
;             for (int i = 0; i < 4; ++i) v[i] = (n0 + n4 < N) ? *(const float4*)(src + (size_t)(k0 + kk + 16 * i) * ld + n0 + n4) : make_float4(0.f, 0.f, 0.f, 0.f);
;         }
; #pragma unroll
;         for (int i = 0; i < 4; ++i) { float* t = tl + (kk + 16 * i) * 129 + n4; t[0] = v[i].x; t[1] = v[i].y; t[2] = v[i].z; t[3] = v[i].w; }
;     }
;     __syncthreads();
;     {
;         const int k2 = (tid & 31) * 2, nn = tid >> 5;
; #pragma unroll
;         for (int i = 0; i < 8; ++i) {
;             const int nl = nn + 16 * i, ng = n0 + nl;
;             if (ng < N) { const int row = (ng / blk) * stride + (ng % blk) + off; *(unsigned*)(dst + (size_t)row * K + k0 + k2) = pk2(tl[k2 * 129 + nl], tl[(k2 + 1) * 129 + nl]); }
;         }
;     }
;     __syncthreads();
; }
; template <bool BATCH>
; __device__ __forceinline__ void weight_job(const Params& p, int job, float* ldsf) {
;     ...
;     if (j < J_G) { transpose_tile<BATCH>(p.w_gate, DFF, DFF, 1024, (j / 22) * 64, (j % 22) * 128, (bfu*)(ws + WS_WGU), 128, 256, 0, ldsf); return; }
;     j -= J_G;
;     if (j < J_U) { transpose_tile<BATCH>(p.w_up, DFF, DFF, 1024, (j / 22) * 64, (j % 22) * 128, (bfu*)(ws + WS_WGU), 128, 256, 128, ldsf); return; }
.LBB0_15:
	s_and_b64 vcc, exec, s[18:19]
	s_cbranch_vccz .LBB0_37
	s_add_i32 s10, s37, 0xfa90
	s_and_b32 s15, s10, 0xffff
	s_mul_i32 s15, s15, 0xba2f
	s_lshr_b32 s15, s15, 20
	s_mul_i32 s38, s15, 22
	s_load_dwordx2 s[18:19], s[8:9], 0x90
	s_sub_i32 s38, s10, s38
	s_lshl_b32 s10, s38, 7
	s_and_b32 s39, s10, 0xff80
	v_or_b32_e32 v16, s39, v2
	v_lshl_or_b32 v18, s15, 6, v1
	v_lshlrev_b32_e32 v16, 2, v16
	v_mov_b32_e32 v17, v5
	v_mul_u32_u24_e32 v18, 0xb00, v18
	s_waitcnt lgkmcnt(0)
	v_lshl_add_u64 v[16:17], s[18:19], 0, v[16:17]
	v_lshlrev_b32_e32 v18, 2, v18
	v_mov_b32_e32 v19, v5
	v_lshl_add_u64 v[16:17], v[16:17], 0, v[18:19]
	v_add_co_u32_e32 v18, vcc, s27, v16
	s_lshl_b32 s10, s15, 7
	s_nop 0
	v_addc_co_u32_e32 v19, vcc, 0, v17, vcc
	global_load_dwordx4 v[40:43], v[16:17], off nt
	global_load_dwordx4 v[44:47], v[18:19], off nt
	v_add_co_u32_e32 v18, vcc, s28, v16
	v_mov_b32_e32 v57, v5
	s_nop 0
	v_addc_co_u32_e32 v19, vcc, 0, v17, vcc
	global_load_dwordx4 v[48:51], v[18:19], off nt
	v_add_co_u32_e32 v16, vcc, s29, v16
	v_mov_b32_e32 v59, v5
	s_nop 0
	v_addc_co_u32_e32 v17, vcc, 0, v17, vcc
	global_load_dwordx4 v[52:55], v[16:17], off nt
	v_lshl_add_u64 v[16:17], v[10:11], 0, s[10:11]
	s_lshl_b32 s10, s38, 8
	s_and_b32 s10, s10, 0xff00
	v_or_b32_e32 v18, s10, v1
	v_mov_b32_e32 v19, v5
	v_lshlrev_b32_e32 v18, 11, v18
	v_lshl_add_u64 v[18:19], v[16:17], 0, v[18:19]
	v_add_co_u32_e32 v62, vcc, s30, v18
	v_or_b32_e32 v39, s10, v28
	s_nop 0
	v_addc_co_u32_e32 v63, vcc, 0, v19, vcc
	v_add_co_u32_e32 v64, vcc, s31, v18
	v_or_b32_e32 v58, s10, v29
	s_nop 0
	v_addc_co_u32_e32 v65, vcc, 0, v19, vcc
	v_add_co_u32_e32 v66, vcc, s33, v18
	v_or_b32_e32 v60, s10, v30
	s_nop 0
	v_addc_co_u32_e32 v67, vcc, 0, v19, vcc
	v_add_co_u32_e32 v18, vcc, 0x70000, v18
	v_mov_b32_e32 v61, v5
	v_lshlrev_b32_e32 v56, 11, v39
	v_lshlrev_b32_e32 v58, 11, v58
	v_lshlrev_b32_e32 v60, 11, v60
	v_addc_co_u32_e32 v19, vcc, 0, v19, vcc
	v_lshl_add_u64 v[56:57], v[16:17], 0, v[56:57]
	v_lshl_add_u64 v[58:59], v[16:17], 0, v[58:59]
	v_lshl_add_u64 v[60:61], v[16:17], 0, v[60:61]
	s_waitcnt vmcnt(3)
	ds_write2_b32 v3, v40, v41 offset1:1
	ds_write2_b32 v3, v42, v43 offset0:2 offset1:3
	s_waitcnt vmcnt(2)
	ds_write2_b32 v32, v44, v45 offset1:1
	ds_write2_b32 v33, v46, v47 offset1:1
	s_waitcnt vmcnt(1)
	ds_write2_b32 v34, v48, v49 offset1:1
	ds_write2_b32 v35, v50, v51 offset1:1
	s_waitcnt vmcnt(0)
	ds_write2_b32 v36, v52, v53 offset1:1
	ds_write2_b32 v37, v54, v55 offset1:1
	s_waitcnt lgkmcnt(0)
	s_barrier
	ds_read2_b32 v[40:41], v23 offset1:16
	ds_read2_b32 v[42:43], v23 offset0:96 offset1:129
	ds_read2_b32 v[44:45], v23 offset0:145 offset1:161
	ds_read2_b32 v[46:47], v23 offset0:32 offset1:48
	ds_read2_b32 v[48:49], v23 offset0:177 offset1:193
	ds_read2_b32 v[50:51], v23 offset0:64 offset1:80
	ds_read2_b32 v[52:53], v23 offset0:209 offset1:225
	s_waitcnt lgkmcnt(5)
	v_cvt_pk_bf16_f32 v39, v40, v43
	s_waitcnt lgkmcnt(4)
	v_cvt_pk_bf16_f32 v40, v41, v44
	s_waitcnt lgkmcnt(3)
	v_cvt_pk_bf16_f32 v41, v46, v45
	s_waitcnt lgkmcnt(2)
	v_cvt_pk_bf16_f32 v43, v47, v48
	s_waitcnt lgkmcnt(0)
	v_cvt_pk_bf16_f32 v42, v42, v53
	v_cvt_pk_bf16_f32 v44, v50, v49
	v_cvt_pk_bf16_f32 v45, v51, v52
	global_store_dword v[62:63], v39, off
	global_store_dword v[56:57], v40, off
	global_store_dword v[64:65], v41, off
	global_store_dword v[58:59], v43, off
	global_store_dword v[66:67], v44, off
	global_store_dword v[60:61], v45, off
	global_store_dword v[18:19], v42, off
	v_add_u32_e32 v18, s39, v27
	v_cmp_gt_u32_e32 vcc, s25, v18
	s_and_saveexec_b64 s[18:19], vcc
	s_cbranch_execz .LBB0_18
	ds_read2_b32 v[40:41], v23 offset0:112 offset1:241
	v_lshlrev_b32_e32 v18, 1, v18
	v_and_or_b32 v18, v18, s34, v27
	v_mov_b32_e32 v19, v5
	v_lshl_or_b32 v18, v18, 11, v38
	s_waitcnt lgkmcnt(0)
	v_cvt_pk_bf16_f32 v39, v40, v41
	v_lshl_add_u64 v[16:17], v[16:17], 0, v[18:19]
	global_store_dword v[16:17], v39, off

; __device__ __forceinline__ unsigned pk2(float lo, float hi) { f32x2_t v = {lo, hi}; bf16x2_t b = __builtin_convertvector(v, bf16x2_t); return __builtin_bit_cast(unsigned, b); }
; template <bool BATCH>
; __device__ __forceinline__ void transpose_tile(const float* __restrict__ src, int ld, int N, int K, int k0, int n0, bfu* __restrict__ dst,
;                                                int blk, int stride, int off, float* tl  ) {
;     const int tid = threadIdx.x;
;     {
;         const int n4 = (tid & 31) * 4, kk = tid >> 5;
;         float4 v[4];
;         if (BATCH) {
;             const int ncl = (n0 + n4 < N) ? n0 + n4 : 0;
; #pragma unroll
;             for (int i = 0; i < 4; ++i) v[i] = *(const float4*)(src + (size_t)(k0 + kk + 16 * i) * ld + ncl);
;         } else {
; #pragma unroll
;             for (int i = 0; i < 4; ++i) v[i] = (n0 + n4 < N) ? *(const float4*)(src + (size_t)(k0 + kk + 16 * i) * ld + n0 + n4) : make_float4(0.f, 0.f, 0.f, 0.f);
;         }
; #pragma unroll
;         for (int i = 0; i < 4; ++i) { float* t = tl + (kk + 16 * i) * 129 + n4; t[0] = v[i].x; t[1] = v[i].y; t[2] = v[i].z; t[3] = v[i].w; }
;     }
;     __syncthreads();
;     {
;         const int k2 = (tid & 31) * 2, nn = tid >> 5;
; #pragma unroll
;         for (int i = 0; i < 8; ++i) {
;             const int nl = nn + 16 * i, ng = n0 + nl;
;             if (ng < N) { const int row = (ng / blk) * stride + (ng % blk) + off; *(unsigned*)(dst + (size_t)row * K + k0 + k2) = pk2(tl[k2 * 129 + nl], tl[(k2 + 1) * 129 + nl]); }
;         }
;     }
;     __syncthreads();
; }
; template <bool BATCH>
; __device__ __forceinline__ void weight_job(const Params& p, int job, float* ldsf) {
;     ...
;     if (j < J_G) { transpose_tile<BATCH>(p.w_gate, DFF, DFF, 1024, (j / 22) * 64, (j % 22) * 128, (bfu*)(ws + WS_WGU), 128, 256, 0, ldsf); return; }
.LBB0_20:
	s_add_i32 s10, s37, 0xfbf0
	s_and_b32 s15, s10, 0xffff
	s_mul_i32 s15, s15, 0xba2f
	s_lshr_b32 s15, s15, 20
	s_mul_i32 s38, s15, 22
	s_load_dwordx2 s[18:19], s[8:9], 0x88
	s_sub_i32 s38, s10, s38
	s_lshl_b32 s10, s38, 7
	s_and_b32 s39, s10, 0xff80
	v_or_b32_e32 v16, s39, v2
	v_lshl_or_b32 v18, s15, 6, v1
	v_lshlrev_b32_e32 v16, 2, v16
	v_mov_b32_e32 v17, v5
	v_mul_u32_u24_e32 v18, 0xb00, v18
	s_waitcnt lgkmcnt(0)
	v_lshl_add_u64 v[16:17], s[18:19], 0, v[16:17]
	v_lshlrev_b32_e32 v18, 2, v18
	v_mov_b32_e32 v19, v5
	v_lshl_add_u64 v[16:17], v[16:17], 0, v[18:19]
	v_add_co_u32_e32 v18, vcc, s27, v16
	s_lshl_b32 s10, s15, 7
	s_nop 0
	v_addc_co_u32_e32 v19, vcc, 0, v17, vcc
	global_load_dwordx4 v[40:43], v[16:17], off nt
	global_load_dwordx4 v[44:47], v[18:19], off nt
	v_add_co_u32_e32 v18, vcc, s28, v16
	v_mov_b32_e32 v57, v5
	s_nop 0
	v_addc_co_u32_e32 v19, vcc, 0, v17, vcc
	global_load_dwordx4 v[48:51], v[18:19], off nt
	v_add_co_u32_e32 v16, vcc, s29, v16
	v_mov_b32_e32 v59, v5
	s_nop 0
	v_addc_co_u32_e32 v17, vcc, 0, v17, vcc
	global_load_dwordx4 v[52:55], v[16:17], off nt
	v_lshl_add_u64 v[16:17], v[10:11], 0, s[10:11]
	s_lshl_b32 s10, s38, 8
	s_and_b32 s10, s10, 0xff00
	v_or_b32_e32 v19, s10, v1
	v_or_b32_e32 v39, s10, v20
	v_or_b32_e32 v60, s10, v21
	v_or_b32_e32 v62, s10, v22
	v_or_b32_e32 v64, s10, v24
	v_or_b32_e32 v66, s10, v25
	v_or_b32_e32 v68, s10, v26
	v_add_u32_e32 v18, s39, v27
	v_lshlrev_b32_e32 v56, 11, v19
	v_mov_b32_e32 v61, v5
	v_mov_b32_e32 v63, v5
	v_mov_b32_e32 v65, v5
	v_mov_b32_e32 v67, v5
	v_mov_b32_e32 v69, v5
	v_lshlrev_b32_e32 v58, 11, v39
	v_lshlrev_b32_e32 v60, 11, v60
	v_lshlrev_b32_e32 v62, 11, v62
	v_lshlrev_b32_e32 v64, 11, v64
	v_lshlrev_b32_e32 v66, 11, v66
	v_lshlrev_b32_e32 v68, 11, v68
	v_lshl_add_u64 v[56:57], v[16:17], 0, v[56:57]
	v_cmp_gt_u32_e32 vcc, s25, v18
	v_lshl_add_u64 v[58:59], v[16:17], 0, v[58:59]
	v_lshl_add_u64 v[60:61], v[16:17], 0, v[60:61]
	v_lshl_add_u64 v[62:63], v[16:17], 0, v[62:63]
	v_lshl_add_u64 v[64:65], v[16:17], 0, v[64:65]
	v_lshl_add_u64 v[66:67], v[16:17], 0, v[66:67]
	v_lshl_add_u64 v[68:69], v[16:17], 0, v[68:69]
	s_waitcnt vmcnt(3)
	ds_write2_b32 v3, v40, v41 offset1:1
	ds_write2_b32 v3, v42, v43 offset0:2 offset1:3
	s_waitcnt vmcnt(2)
	ds_write2_b32 v32, v44, v45 offset1:1
	ds_write2_b32 v33, v46, v47 offset1:1
	s_waitcnt vmcnt(1)
	ds_write2_b32 v34, v48, v49 offset1:1
	ds_write2_b32 v35, v50, v51 offset1:1
	s_waitcnt vmcnt(0)
	ds_write2_b32 v36, v52, v53 offset1:1
	ds_write2_b32 v37, v54, v55 offset1:1
	s_waitcnt lgkmcnt(0)
	s_barrier
	ds_read2_b32 v[40:41], v23 offset1:16
	ds_read2_b32 v[42:43], v23 offset0:96 offset1:129
	ds_read2_b32 v[44:45], v23 offset0:145 offset1:161
	ds_read2_b32 v[46:47], v23 offset0:32 offset1:48
	ds_read2_b32 v[48:49], v23 offset0:177 offset1:193
	ds_read2_b32 v[50:51], v23 offset0:64 offset1:80
	ds_read2_b32 v[52:53], v23 offset0:209 offset1:225
	s_waitcnt lgkmcnt(5)
	v_cvt_pk_bf16_f32 v19, v40, v43
	s_waitcnt lgkmcnt(4)
	v_cvt_pk_bf16_f32 v39, v41, v44
	s_waitcnt lgkmcnt(3)
	v_cvt_pk_bf16_f32 v40, v46, v45
	s_waitcnt lgkmcnt(2)
	v_cvt_pk_bf16_f32 v41, v47, v48
	s_waitcnt lgkmcnt(1)
	v_cvt_pk_bf16_f32 v43, v50, v49
	s_waitcnt lgkmcnt(0)
	v_cvt_pk_bf16_f32 v44, v51, v52
	v_cvt_pk_bf16_f32 v42, v42, v53
	global_store_dword v[56:57], v19, off
	global_store_dword v[58:59], v39, off
	global_store_dword v[60:61], v40, off
	global_store_dword v[62:63], v41, off
	global_store_dword v[64:65], v43, off
	global_store_dword v[66:67], v44, off
	global_store_dword v[68:69], v42, off
	s_and_saveexec_b64 s[18:19], vcc
	s_cbranch_execz .LBB0_22
	ds_read2_b32 v[40:41], v23 offset0:112 offset1:241
	v_lshlrev_b32_e32 v18, 1, v18
	v_and_or_b32 v18, v18, s34, v31
	v_mov_b32_e32 v19, v5
	v_lshlrev_b32_e32 v18, 11, v18
	s_waitcnt lgkmcnt(0)
	v_cvt_pk_bf16_f32 v39, v40, v41
	v_lshl_add_u64 v[16:17], v[16:17], 0, v[18:19]
	global_store_dword v[16:17], v39, off

; __device__ __forceinline__ unsigned pk2(float lo, float hi) { f32x2_t v = {lo, hi}; bf16x2_t b = __builtin_convertvector(v, bf16x2_t); return __builtin_bit_cast(unsigned, b); }
; template <bool BATCH>
; __device__ __forceinline__ void transpose_tile(const float* __restrict__ src, int ld, int N, int K, int k0, int n0, bfu* __restrict__ dst,
;                                                int blk, int stride, int off, float* tl  ) {
;     ...
;     {
;         const int n4 = (tid & 31) * 4, kk = tid >> 5;
;         float4 v[4];
;         if (BATCH) {
;             const int ncl = (n0 + n4 < N) ? n0 + n4 : 0;
; #pragma unroll
;             for (int i = 0; i < 4; ++i) v[i] = *(const float4*)(src + (size_t)(k0 + kk + 16 * i) * ld + ncl);
;         } else {
; #pragma unroll
;             for (int i = 0; i < 4; ++i) v[i] = (n0 + n4 < N) ? *(const float4*)(src + (size_t)(k0 + kk + 16 * i) * ld + n0 + n4) : make_float4(0.f, 0.f, 0.f, 0.f);
;         }
; #pragma unroll
;         for (int i = 0; i < 4; ++i) { float* t = tl + (kk + 16 * i) * 129 + n4; t[0] = v[i].x; t[1] = v[i].y; t[2] = v[i].z; t[3] = v[i].w; }
;     }
;     __syncthreads();
;     {
;         const int k2 = (tid & 31) * 2, nn = tid >> 5;
; #pragma unroll
;         for (int i = 0; i < 8; ++i) {
;             const int nl = nn + 16 * i, ng = n0 + nl;
;             if (ng < N) { const int row = (ng / blk) * stride + (ng % blk) + off; *(unsigned*)(dst + (size_t)row * K + k0 + k2) = pk2(tl[k2 * 129 + nl], tl[(k2 + 1) * 129 + nl]); }
;         }
;     }
; template <bool BATCH>
; __device__ __forceinline__ void weight_job(const Params& p, int job, float* ldsf) {
;     ...
;     if (j < J_OUT) { transpose_tile<BATCH>(p.w_out, 1024, 1024, 2048, (j / 8) * 64, (j % 8) * 128, (bfu*)(ws + WS_WOUT), BIG, 0, 0, ldsf); return; }
.LBB0_24:
	s_andn2_b64 vcc, exec, s[18:19]
	s_cbranch_vccnz .LBB0_28
	s_load_dwordx2 s[18:19], s[8:9], 0x70
	s_add_i32 s10, s22, 0x1e00
	s_and_b32 s10, s10, 0x7fffffc0
	s_and_b32 s15, s20, 0x380
	v_or_b32_e32 v17, s15, v2
	v_or_b32_e32 v16, s10, v1
	v_lshlrev_b32_e32 v18, 2, v17
	v_mov_b32_e32 v19, v5
	v_add_u32_e32 v42, 16, v16
	v_mov_b32_e32 v43, v5
	s_waitcnt lgkmcnt(0)
	v_lshl_add_u64 v[18:19], s[18:19], 0, v[18:19]
	v_mov_b32_e32 v17, v5
	v_lshlrev_b64 v[42:43], 12, v[42:43]
	v_lshlrev_b64 v[40:41], 12, v[16:17]
	v_lshl_add_u64 v[44:45], v[18:19], 0, v[42:43]
	v_or_b32_e32 v42, 32, v16
	v_mov_b32_e32 v43, v5
	v_lshl_add_u64 v[40:41], v[18:19], 0, v[40:41]
	v_lshlrev_b64 v[42:43], 12, v[42:43]
	v_lshl_add_u64 v[48:49], v[18:19], 0, v[42:43]
	global_load_dwordx4 v[40:43], v[40:41], off nt
	s_nop 0
	global_load_dwordx4 v[44:47], v[44:45], off nt
	v_add_u32_e32 v16, 48, v16
	v_lshlrev_b64 v[16:17], 12, v[16:17]
	global_load_dwordx4 v[48:51], v[48:49], off nt
	v_lshl_add_u64 v[16:17], v[18:19], 0, v[16:17]
	global_load_dwordx4 v[52:55], v[16:17], off nt
	v_or_b32_e32 v16, s15, v1
	v_or_b32_e32 v17, s15, v20
	s_lshl_b32 s10, s10, 1
	v_mov_b32_e32 v57, v5
	v_or_b32_e32 v19, s15, v21
	v_or_b32_e32 v39, s15, v22
	v_or_b32_e32 v64, s15, v24
	v_or_b32_e32 v66, s15, v25
	v_or_b32_e32 v68, s15, v26
	v_add_u32_e32 v18, s15, v27
	v_lshlrev_b32_e32 v56, 12, v16
	v_lshlrev_b32_e32 v58, 12, v17
	v_lshl_add_u64 v[16:17], v[12:13], 0, s[10:11]
	v_mov_b32_e32 v59, v5
	v_mov_b32_e32 v61, v5
	v_mov_b32_e32 v63, v5
	v_mov_b32_e32 v65, v5
	v_mov_b32_e32 v67, v5
	v_mov_b32_e32 v69, v5
	v_lshlrev_b32_e32 v60, 12, v19
	v_lshlrev_b32_e32 v62, 12, v39
	v_lshlrev_b32_e32 v64, 12, v64
	v_lshlrev_b32_e32 v66, 12, v66
	v_lshlrev_b32_e32 v68, 12, v68
	v_lshl_add_u64 v[56:57], v[16:17], 0, v[56:57]
	v_cmp_gt_u32_e32 vcc, s26, v18
	v_lshl_add_u64 v[58:59], v[16:17], 0, v[58:59]
	v_lshl_add_u64 v[60:61], v[16:17], 0, v[60:61]
	v_lshl_add_u64 v[62:63], v[16:17], 0, v[62:63]
	v_lshl_add_u64 v[64:65], v[16:17], 0, v[64:65]
	v_lshl_add_u64 v[66:67], v[16:17], 0, v[66:67]
	v_lshl_add_u64 v[68:69], v[16:17], 0, v[68:69]
	s_waitcnt vmcnt(3)
	ds_write2_b32 v3, v40, v41 offset1:1
	ds_write2_b32 v3, v42, v43 offset0:2 offset1:3
	s_waitcnt vmcnt(2)
	ds_write2_b32 v32, v44, v45 offset1:1
	ds_write2_b32 v33, v46, v47 offset1:1
	s_waitcnt vmcnt(1)
	ds_write2_b32 v34, v48, v49 offset1:1
	ds_write2_b32 v35, v50, v51 offset1:1
	s_waitcnt vmcnt(0)
	ds_write2_b32 v36, v52, v53 offset1:1
	ds_write2_b32 v37, v54, v55 offset1:1
	s_waitcnt lgkmcnt(0)
	s_barrier
	ds_read2_b32 v[40:41], v23 offset1:16
	ds_read2_b32 v[42:43], v23 offset0:96 offset1:129
	ds_read2_b32 v[44:45], v23 offset0:145 offset1:161
	ds_read2_b32 v[46:47], v23 offset0:32 offset1:48
	ds_read2_b32 v[48:49], v23 offset0:177 offset1:193
	ds_read2_b32 v[50:51], v23 offset0:64 offset1:80
	ds_read2_b32 v[52:53], v23 offset0:209 offset1:225
	s_waitcnt lgkmcnt(5)
	v_cvt_pk_bf16_f32 v19, v40, v43
	s_waitcnt lgkmcnt(4)
	v_cvt_pk_bf16_f32 v39, v41, v44
	s_waitcnt lgkmcnt(3)
	v_cvt_pk_bf16_f32 v40, v46, v45
	s_waitcnt lgkmcnt(2)
	v_cvt_pk_bf16_f32 v41, v47, v48
	s_waitcnt lgkmcnt(1)
	v_cvt_pk_bf16_f32 v43, v50, v49
	s_waitcnt lgkmcnt(0)
	v_cvt_pk_bf16_f32 v44, v51, v52
	v_cvt_pk_bf16_f32 v42, v42, v53
	global_store_dword v[56:57], v19, off
	global_store_dword v[58:59], v39, off
	global_store_dword v[60:61], v40, off
	global_store_dword v[62:63], v41, off
	global_store_dword v[64:65], v43, off
	global_store_dword v[66:67], v44, off
	global_store_dword v[68:69], v42, off
	s_and_saveexec_b64 s[18:19], vcc
	s_cbranch_execz .LBB0_27
	ds_read2_b32 v[40:41], v23 offset0:112 offset1:241
	v_lshlrev_b32_e32 v18, 12, v18
	v_mov_b32_e32 v19, v5
	v_lshl_add_u64 v[16:17], v[16:17], 0, v[18:19]
	s_waitcnt lgkmcnt(0)
	v_cvt_pk_bf16_f32 v39, v40, v41
	global_store_dword v[16:17], v39, off

; __device__ __forceinline__ unsigned pk2(float lo, float hi) { f32x2_t v = {lo, hi}; bf16x2_t b = __builtin_convertvector(v, bf16x2_t); return __builtin_bit_cast(unsigned, b); }
; template <bool BATCH>
; __device__ __forceinline__ void transpose_tile(const float* __restrict__ src, int ld, int N, int K, int k0, int n0, bfu* __restrict__ dst,
;                                                int blk, int stride, int off, float* tl  ) {
;     ...
;     {
;         const int n4 = (tid & 31) * 4, kk = tid >> 5;
;         float4 v[4];
;         if (BATCH) {
;             const int ncl = (n0 + n4 < N) ? n0 + n4 : 0;
; #pragma unroll
;             for (int i = 0; i < 4; ++i) v[i] = *(const float4*)(src + (size_t)(k0 + kk + 16 * i) * ld + ncl);
;         } else {
; #pragma unroll
;             for (int i = 0; i < 4; ++i) v[i] = (n0 + n4 < N) ? *(const float4*)(src + (size_t)(k0 + kk + 16 * i) * ld + n0 + n4) : make_float4(0.f, 0.f, 0.f, 0.f);
;         }
; #pragma unroll
;         for (int i = 0; i < 4; ++i) { float* t = tl + (kk + 16 * i) * 129 + n4; t[0] = v[i].x; t[1] = v[i].y; t[2] = v[i].z; t[3] = v[i].w; }
;     }
;     __syncthreads();
;     {
;         const int k2 = (tid & 31) * 2, nn = tid >> 5;
; #pragma unroll
;         for (int i = 0; i < 8; ++i) {
;             const int nl = nn + 16 * i, ng = n0 + nl;
;             if (ng < N) { const int row = (ng / blk) * stride + (ng % blk) + off; *(unsigned*)(dst + (size_t)row * K + k0 + k2) = pk2(tl[k2 * 129 + nl], tl[(k2 + 1) * 129 + nl]); }
;         }
;     }
; template <bool BATCH>
; __device__ __forceinline__ void weight_job(const Params& p, int job, float* ldsf) {
;     ...
;     if (j < J_DT) { transpose_tile<BATCH>(p.w_in + 6144, NIN, 16, 1024, j * 64, 0, (bfu*)(ws + WS_WDT), BIG, 0, 0, ldsf); return; }
.LBB0_29:
	s_andn2_b64 vcc, exec, s[18:19]
	s_cbranch_vccnz .LBB0_33
	s_load_dwordx2 s[18:19], s[8:9], 0x30
	v_add_u32_e32 v39, s14, v1
	v_add_u32_e32 v18, 16, v39
	s_waitcnt lgkmcnt(0)
	v_lshl_add_u64 v[16:17], s[18:19], 0, v[4:5]
	v_lshl_add_u64 v[48:49], v[16:17], 0, s[16:17]
	v_mad_u64_u32 v[16:17], s[18:19], v39, s35, v[48:49]
	v_mad_u64_u32 v[50:51], s[18:19], v18, s35, v[48:49]
	v_add_u32_e32 v18, 32, v39
	v_mad_u64_u32 v[52:53], s[18:19], v18, s35, v[48:49]
	global_load_dwordx4 v[16:19], v[16:17], off nt
	s_nop 0
	global_load_dwordx4 v[40:43], v[50:51], off nt
	global_load_dwordx4 v[44:47], v[52:53], off nt
	v_add_u32_e32 v39, 48, v39
	v_mad_u64_u32 v[48:49], s[18:19], v39, s35, v[48:49]
	global_load_dwordx4 v[48:51], v[48:49], off nt
	s_waitcnt vmcnt(3)
	ds_write2_b32 v3, v16, v17 offset1:1
	ds_write2_b32 v3, v18, v19 offset0:2 offset1:3
	s_waitcnt vmcnt(2)
	ds_write2_b32 v32, v40, v41 offset1:1
	ds_write2_b32 v33, v42, v43 offset1:1
	s_waitcnt vmcnt(1)
	ds_write2_b32 v34, v44, v45 offset1:1
	ds_write2_b32 v35, v46, v47 offset1:1
	s_waitcnt vmcnt(0)
	ds_write2_b32 v36, v48, v49 offset1:1
	ds_write2_b32 v37, v50, v51 offset1:1
	s_waitcnt lgkmcnt(0)
	s_barrier
	s_and_saveexec_b64 s[18:19], s[4:5]
	s_cbranch_execz .LBB0_32
	ds_read2_b32 v[16:17], v23 offset1:129
	s_mov_b32 s15, s11
	s_waitcnt lgkmcnt(0)
	v_cvt_pk_bf16_f32 v18, v16, v17
	v_lshl_add_u64 v[16:17], s[14:15], 1, v[14:15]
	global_store_dword v[16:17], v18, off

; __device__ __forceinline__ unsigned pk2(float lo, float hi) { f32x2_t v = {lo, hi}; bf16x2_t b = __builtin_convertvector(v, bf16x2_t); return __builtin_bit_cast(unsigned, b); }
; template <bool BATCH>
; __device__ __forceinline__ void transpose_tile(const float* __restrict__ src, int ld, int N, int K, int k0, int n0, bfu* __restrict__ dst,
;                                                int blk, int stride, int off, float* tl  ) {
;     ...
;     {
;         const int n4 = (tid & 31) * 4, kk = tid >> 5;
;         float4 v[4];
;         if (BATCH) {
;             const int ncl = (n0 + n4 < N) ? n0 + n4 : 0;
; #pragma unroll
;             for (int i = 0; i < 4; ++i) v[i] = *(const float4*)(src + (size_t)(k0 + kk + 16 * i) * ld + ncl);
;         } else {
; #pragma unroll
;             for (int i = 0; i < 4; ++i) v[i] = (n0 + n4 < N) ? *(const float4*)(src + (size_t)(k0 + kk + 16 * i) * ld + n0 + n4) : make_float4(0.f, 0.f, 0.f, 0.f);
;         }
; #pragma unroll
;         for (int i = 0; i < 4; ++i) { float* t = tl + (kk + 16 * i) * 129 + n4; t[0] = v[i].x; t[1] = v[i].y; t[2] = v[i].z; t[3] = v[i].w; }
;     }
;     __syncthreads();
;     {
;         const int k2 = (tid & 31) * 2, nn = tid >> 5;
; #pragma unroll
;         for (int i = 0; i < 8; ++i) {
;             const int nl = nn + 16 * i, ng = n0 + nl;
;             if (ng < N) { const int row = (ng / blk) * stride + (ng % blk) + off; *(unsigned*)(dst + (size_t)row * K + k0 + k2) = pk2(tl[k2 * 129 + nl], tl[(k2 + 1) * 129 + nl]); }
;         }
;     }
; template <bool BATCH>
; __device__ __forceinline__ void weight_job(const Params& p, int job, float* ldsf) {
;     ...
;     if (j < J_IN) { transpose_tile<BATCH>(p.w_in, NIN, 6144, 1024, (j / 48) * 64, (j % 48) * 128, (bfu*)(ws + WS_WIN), BIG, 0, 0, ldsf); return; }
.LBB0_34:
	s_andn2_b64 vcc, exec, s[18:19]
	s_cbranch_vccnz .LBB0_6
	s_mul_hi_i32 s10, s37, 0x2aaaaaab
	s_lshr_b32 s15, s10, 31
	s_ashr_i32 s10, s10, 3
	s_load_dwordx2 s[18:19], s[8:9], 0x30
	s_add_i32 s10, s10, s15
	s_lshl_b32 s38, s10, 6
	s_mulk_i32 s10, 0xe800
	s_add_i32 s10, s10, s20
	v_add_u32_e32 v16, s10, v2
	v_or_b32_e32 v39, s38, v1
	v_ashrrev_i32_e32 v17, 31, v16
	s_waitcnt lgkmcnt(0)
	v_lshl_add_u64 v[16:17], v[16:17], 2, s[18:19]
	v_add_u32_e32 v40, 16, v39
	v_mad_i64_i32 v[18:19], s[18:19], v39, s35, v[16:17]
	v_mad_i64_i32 v[52:53], s[18:19], v40, s35, v[16:17]
	v_or_b32_e32 v40, 32, v39
	v_mad_i64_i32 v[54:55], s[18:19], v40, s35, v[16:17]
	global_load_dwordx4 v[40:43], v[18:19], off nt
	global_load_dwordx4 v[44:47], v[52:53], off nt
	global_load_dwordx4 v[48:51], v[54:55], off nt
	v_add_u32_e32 v18, 48, v39
	v_mad_i64_i32 v[16:17], s[18:19], v18, s35, v[16:17]
	global_load_dwordx4 v[52:55], v[16:17], off nt
	v_add_u32_e32 v56, s10, v1
	s_ashr_i32 s39, s38, 31
	v_ashrrev_i32_e32 v57, 31, v56
	v_add_u32_e32 v58, 16, v56
	v_add_u32_e32 v60, 32, v56
	v_add_u32_e32 v62, 48, v56
	v_add_u32_e32 v64, 64, v56
	v_add_u32_e32 v66, 0x50, v56
	v_add_u32_e32 v68, 0x60, v56
	v_lshl_add_u64 v[16:17], s[38:39], 1, v[6:7]
	v_add_u32_e32 v18, 0x70, v56
	v_lshlrev_b64 v[56:57], 11, v[56:57]
	v_ashrrev_i32_e32 v59, 31, v58
	v_ashrrev_i32_e32 v61, 31, v60
	v_ashrrev_i32_e32 v63, 31, v62
	v_ashrrev_i32_e32 v65, 31, v64
	v_ashrrev_i32_e32 v67, 31, v66
	v_ashrrev_i32_e32 v69, 31, v68
	v_lshl_add_u64 v[56:57], v[16:17], 0, v[56:57]
	v_lshlrev_b64 v[58:59], 11, v[58:59]
	v_lshlrev_b64 v[60:61], 11, v[60:61]
	v_lshlrev_b64 v[62:63], 11, v[62:63]
	v_lshlrev_b64 v[64:65], 11, v[64:65]
	v_lshlrev_b64 v[66:67], 11, v[66:67]
	v_lshlrev_b64 v[68:69], 11, v[68:69]
	v_cmp_gt_i32_e32 vcc, s36, v18
	v_lshl_add_u64 v[58:59], v[16:17], 0, v[58:59]
	v_lshl_add_u64 v[60:61], v[16:17], 0, v[60:61]
	v_lshl_add_u64 v[62:63], v[16:17], 0, v[62:63]
	v_lshl_add_u64 v[64:65], v[16:17], 0, v[64:65]
	v_lshl_add_u64 v[66:67], v[16:17], 0, v[66:67]
	v_lshl_add_u64 v[68:69], v[16:17], 0, v[68:69]
	s_waitcnt vmcnt(3)
	ds_write2_b32 v3, v40, v41 offset1:1
	ds_write2_b32 v3, v42, v43 offset0:2 offset1:3
	s_waitcnt vmcnt(2)
	ds_write2_b32 v32, v44, v45 offset1:1
	ds_write2_b32 v33, v46, v47 offset1:1
	s_waitcnt vmcnt(1)
	ds_write2_b32 v34, v48, v49 offset1:1
	ds_write2_b32 v35, v50, v51 offset1:1
	s_waitcnt vmcnt(0)
	ds_write2_b32 v36, v52, v53 offset1:1
	ds_write2_b32 v37, v54, v55 offset1:1
	s_waitcnt lgkmcnt(0)
	s_barrier
	ds_read2_b32 v[40:41], v23 offset1:16
	ds_read2_b32 v[42:43], v23 offset0:96 offset1:129
	ds_read2_b32 v[44:45], v23 offset0:145 offset1:161
	ds_read2_b32 v[46:47], v23 offset0:32 offset1:48
	ds_read2_b32 v[48:49], v23 offset0:177 offset1:193
	ds_read2_b32 v[50:51], v23 offset0:64 offset1:80
	ds_read2_b32 v[52:53], v23 offset0:209 offset1:225
	s_waitcnt lgkmcnt(5)
	v_cvt_pk_bf16_f32 v19, v40, v43
	s_waitcnt lgkmcnt(4)
	v_cvt_pk_bf16_f32 v39, v41, v44
	s_waitcnt lgkmcnt(3)
	v_cvt_pk_bf16_f32 v40, v46, v45
	s_waitcnt lgkmcnt(2)
	v_cvt_pk_bf16_f32 v41, v47, v48
	s_waitcnt lgkmcnt(1)
	v_cvt_pk_bf16_f32 v43, v50, v49
	s_waitcnt lgkmcnt(0)
	v_cvt_pk_bf16_f32 v44, v51, v52
	v_cvt_pk_bf16_f32 v42, v42, v53
	global_store_dword v[56:57], v19, off
	global_store_dword v[58:59], v39, off
	global_store_dword v[60:61], v40, off
	global_store_dword v[62:63], v41, off
	global_store_dword v[64:65], v43, off
	global_store_dword v[66:67], v44, off
	global_store_dword v[68:69], v42, off
	s_and_saveexec_b64 s[18:19], vcc
	s_cbranch_execz .LBB0_5
	ds_read2_b32 v[40:41], v23 offset0:112 offset1:241
	v_ashrrev_i32_e32 v19, 31, v18
	v_lshlrev_b64 v[18:19], 11, v[18:19]
	v_lshl_add_u64 v[16:17], v[16:17], 0, v[18:19]
	s_waitcnt lgkmcnt(0)
	v_cvt_pk_bf16_f32 v39, v40, v41
	global_store_dword v[16:17], v39, off
	s_branch .LBB0_5

; __device__ __forceinline__ unsigned pk2(float lo, float hi) { f32x2_t v = {lo, hi}; bf16x2_t b = __builtin_convertvector(v, bf16x2_t); return __builtin_bit_cast(unsigned, b); }
; __device__ __forceinline__ void phase0(const Params& p, float* ldsf, int bid, int G) {
;     ...
;         const float4* src = (const float4*)p.x_prompt; constexpr int N4 = MP * 256;
; #pragma unroll 1
;         for (int i0 = gt; i0 < N4; i0 += 8 * NT) {
;             float4 v[8];
; #pragma unroll
;             for (int k = 0; k < 8; ++k) { const int i = i0 + k * NT; v[k] = src[i < N4 ? i : N4 - 1]; }
; #pragma unroll
;             for (int k = 0; k < 8; ++k) { const int i = i0 + k * NT; if (i < N4) { uint2 o; o.x = pk2(v[k].x, v[k].y); o.y = pk2(v[k].z, v[k].w); *(uint2*)(xb + (size_t)i * 4) = o; } }
;         }
.LBB0_41:
	v_add_u32_e32 v42, s40, v44
	v_min_i32_e32 v2, 0x3fffff, v42
	v_add_u32_e32 v40, s20, v44
	v_ashrrev_i32_e32 v3, 31, v2
	v_min_i32_e32 v4, 0x3fffff, v40
	v_lshl_add_u64 v[2:3], v[2:3], 4, s[14:15]
	v_ashrrev_i32_e32 v5, 31, v4
	v_add_u32_e32 v38, s21, v44
	v_lshl_add_u64 v[4:5], v[4:5], 4, s[14:15]
	global_load_dwordx4 v[26:29], v[2:3], off nt
	global_load_dwordx4 v[22:25], v[4:5], off nt
	v_min_i32_e32 v2, 0x3fffff, v38
	v_add_u32_e32 v36, s22, v44
	v_ashrrev_i32_e32 v3, 31, v2
	v_min_i32_e32 v4, 0x3fffff, v36
	v_lshl_add_u64 v[2:3], v[2:3], 4, s[14:15]
	v_ashrrev_i32_e32 v5, 31, v4
	v_add_u32_e32 v34, s23, v44
	v_lshl_add_u64 v[4:5], v[4:5], 4, s[14:15]
	global_load_dwordx4 v[18:21], v[2:3], off nt
	global_load_dwordx4 v[10:13], v[4:5], off nt
	v_min_i32_e32 v2, 0x3fffff, v34
	v_ashrrev_i32_e32 v3, 31, v2
	v_add_u32_e32 v30, s25, v44
	v_lshl_add_u64 v[50:51], v[2:3], 4, s[14:15]
	v_min_i32_e32 v2, 0x3fffff, v30
	v_add_u32_e32 v32, s24, v44
	v_ashrrev_i32_e32 v3, 31, v2
	s_waitcnt vmcnt(5)
	v_min_i32_e32 v6, 0x3fffff, v32
	v_lshl_add_u64 v[8:9], v[2:3], 4, s[14:15]
	v_ashrrev_i32_e32 v45, 31, v44
	v_lshl_add_u64 v[14:15], v[44:45], 4, s[14:15]
	global_load_dwordx4 v[2:5], v[8:9], off nt
	global_load_dwordx4 v[46:49], v[14:15], off nt
	v_ashrrev_i32_e32 v7, 31, v6
	v_lshl_add_u64 v[52:53], v[6:7], 4, s[14:15]
	global_load_dwordx4 v[14:17], v[50:51], off nt
	global_load_dwordx4 v[6:9], v[52:53], off nt
	v_lshl_add_u64 v[44:45], v[44:45], 3, s[10:11]
	v_cmp_gt_i32_e32 vcc, s3, v42
	s_waitcnt vmcnt(2)
	v_cvt_pk_bf16_f32 v46, v46, v47
	v_cvt_pk_bf16_f32 v47, v48, v49
	global_store_dwordx2 v[44:45], v[46:47], off
	s_and_saveexec_b64 s[18:19], vcc
	s_cbranch_execz .LBB0_43
	v_ashrrev_i32_e32 v43, 31, v42
	v_cvt_pk_bf16_f32 v26, v26, v27
	v_cvt_pk_bf16_f32 v27, v28, v29
	v_lshl_add_u64 v[28:29], v[42:43], 3, s[10:11]
	global_store_dwordx2 v[28:29], v[26:27], off

; __device__ __forceinline__ unsigned pk2(float lo, float hi) { f32x2_t v = {lo, hi}; bf16x2_t b = __builtin_convertvector(v, bf16x2_t); return __builtin_bit_cast(unsigned, b); }
; __device__ __forceinline__ void phase0(const Params& p, float* ldsf, int bid, int G) {
;     ...
;         const float4* src = (const float4*)p.x_sample; constexpr int N4 = (MT - MP) * 256;
;         for (int i = gt; i < N4; i += NT) { const float4 v = src[i]; uint2 o; o.x = pk2(v.x, v.y); o.y = pk2(v.z, v.w); *(uint2*)(xb + (size_t)(MP * 256 + i) * 4) = o; }
.LBB0_57:
	global_load_dwordx4 v[6:9], v[4:5], off offset:-8 nt
	v_add_u32_e32 v1, s40, v1
	v_cmp_lt_i32_e32 vcc, s3, v1
	v_lshl_add_u64 v[4:5], v[4:5], 0, s[8:9]
	s_or_b64 s[10:11], vcc, s[10:11]
	s_waitcnt vmcnt(0)
	v_cvt_pk_bf16_f32 v6, v6, v7
	v_cvt_pk_bf16_f32 v7, v8, v9
	global_store_dwordx2 v[2:3], v[6:7], off
	v_lshl_add_u64 v[2:3], v[2:3], 0, s[6:7]
	s_andn2_b64 exec, exec, s[10:11]
	s_cbranch_execnz .LBB0_57

; __device__ __forceinline__ unsigned pk2(float lo, float hi) { f32x2_t v = {lo, hi}; bf16x2_t b = __builtin_convertvector(v, bf16x2_t); return __builtin_bit_cast(unsigned, b); }
; template <bool BATCH>
; __device__ __forceinline__ void transpose_tile(const float* __restrict__ src, int ld, int N, int K, int k0, int n0, bfu* __restrict__ dst,
;                                                int blk, int stride, int off, float* tl  ) {
;     ...
;         } else {
; #pragma unroll
;             for (int i = 0; i < 4; ++i) v[i] = (n0 + n4 < N) ? *(const float4*)(src + (size_t)(k0 + kk + 16 * i) * ld + n0 + n4) : make_float4(0.f, 0.f, 0.f, 0.f);
;         }
; #pragma unroll
;         for (int i = 0; i < 4; ++i) { float* t = tl + (kk + 16 * i) * 129 + n4; t[0] = v[i].x; t[1] = v[i].y; t[2] = v[i].z; t[3] = v[i].w; }
;     }
;     __syncthreads();
;     {
;         const int k2 = (tid & 31) * 2, nn = tid >> 5;
; #pragma unroll
;         for (int i = 0; i < 8; ++i) {
;             const int nl = nn + 16 * i, ng = n0 + nl;
;             if (ng < N) { const int row = (ng / blk) * stride + (ng % blk) + off; *(unsigned*)(dst + (size_t)row * K + k0 + k2) = pk2(tl[k2 * 129 + nl], tl[(k2 + 1) * 129 + nl]); }
;         }
;     }
; template <bool BATCH>
; __device__ __forceinline__ void weight_job(const Params& p, int job, float* ldsf) {
;     ...
;     if (j < J_U) { transpose_tile<BATCH>(p.w_up, DFF, DFF, 1024, (j / 22) * 64, (j % 22) * 128, (bfu*)(ws + WS_WGU), 128, 256, 128, ldsf); return; }
.LBB0_165:
	s_cmpk_gt_u32 s3, 0x40f
	s_mov_b64 s[6:7], -1
	s_cbranch_scc0 .LBB0_174
	s_cmpk_gt_u32 s3, 0x56f
	s_cbranch_scc0 .LBB0_170
	s_add_i32 s4, s3, 0xfa90
	s_and_b32 s24, s4, 0xffff
	s_mul_i32 s24, s24, 0xba2f
	s_lshr_b32 s24, s24, 20
	s_load_dwordx2 s[6:7], s[0:1], 0x90
	s_mul_i32 s25, s24, 22
	s_sub_i32 s25, s4, s25
	s_lshl_b32 s4, s25, 7
	s_and_b32 s26, s4, 0xff80
	s_lshl_b32 s4, s26, 2
	v_lshl_or_b32 v29, s24, 6, v8
	s_waitcnt lgkmcnt(0)
	s_add_u32 s6, s6, s4
	s_addc_u32 s7, s7, 0
	v_mul_u32_u24_e32 v29, 0xb00, v29
	v_lshl_add_u64 v[6:7], s[6:7], 0, v[0:1]
	v_lshlrev_b32_e32 v30, 2, v29
	v_mov_b32_e32 v31, v1
	v_lshl_add_u64 v[6:7], v[6:7], 0, v[30:31]
	v_add_co_u32_e32 v38, vcc, s11, v6
	s_lshl_b32 s4, s24, 7
	s_nop 0
	v_addc_co_u32_e32 v39, vcc, 0, v7, vcc
	global_load_dwordx4 v[30:33], v[6:7], off nt
	global_load_dwordx4 v[34:37], v[38:39], off nt
	v_add_co_u32_e32 v38, vcc, s14, v6
	s_lshl_b32 s6, s25, 8
	s_nop 0
	v_addc_co_u32_e32 v39, vcc, 0, v7, vcc
	global_load_dwordx4 v[38:41], v[38:39], off nt
	v_add_co_u32_e32 v6, vcc, s15, v6
	v_mov_b32_e32 v47, v1
	s_nop 0
	v_addc_co_u32_e32 v7, vcc, 0, v7, vcc
	global_load_dwordx4 v[42:45], v[6:7], off nt
	v_lshl_add_u64 v[6:7], v[2:3], 0, s[4:5]
	s_and_b32 s4, s6, 0xff00
	v_or_b32_e32 v29, s4, v8
	v_lshlrev_b32_e32 v46, 11, v29
	v_lshl_add_u64 v[46:47], v[6:7], 0, v[46:47]
	v_add_co_u32_e32 v54, vcc, s16, v46
	v_or_b32_e32 v48, s4, v13
	s_nop 0
	v_addc_co_u32_e32 v55, vcc, 0, v47, vcc
	v_add_co_u32_e32 v56, vcc, s17, v46
	v_or_b32_e32 v50, s4, v14
	s_nop 0
	v_addc_co_u32_e32 v57, vcc, 0, v47, vcc
	v_add_co_u32_e32 v58, vcc, s18, v46
	v_or_b32_e32 v52, s4, v17
	s_nop 0
	v_addc_co_u32_e32 v59, vcc, 0, v47, vcc
	v_mov_b32_e32 v49, v1
	v_mov_b32_e32 v51, v1
	v_mov_b32_e32 v53, v1
	v_lshlrev_b32_e32 v48, 11, v48
	v_lshlrev_b32_e32 v50, 11, v50
	v_lshlrev_b32_e32 v52, 11, v52
	v_add_co_u32_e32 v46, vcc, 0x70000, v46
	v_lshl_add_u64 v[48:49], v[6:7], 0, v[48:49]
	v_lshl_add_u64 v[50:51], v[6:7], 0, v[50:51]
	v_lshl_add_u64 v[52:53], v[6:7], 0, v[52:53]
	v_addc_co_u32_e32 v47, vcc, 0, v47, vcc
	s_waitcnt vmcnt(0)
	ds_write2_b32 v21, v30, v31 offset1:1
	ds_write2_b32 v21, v32, v33 offset0:2 offset1:3
	ds_write2_b32 v22, v34, v35 offset1:1
	ds_write2_b32 v23, v36, v37 offset1:1
	ds_write2_b32 v24, v38, v39 offset1:1
	ds_write2_b32 v25, v40, v41 offset1:1
	ds_write2_b32 v26, v42, v43 offset1:1
	ds_write2_b32 v27, v44, v45 offset1:1
	s_waitcnt lgkmcnt(0)
	s_barrier
	ds_read2_b32 v[30:31], v12 offset1:16
	ds_read2_b32 v[32:33], v12 offset0:96 offset1:129
	ds_read2_b32 v[34:35], v12 offset0:145 offset1:161
	ds_read2_b32 v[36:37], v12 offset0:32 offset1:48
	ds_read2_b32 v[38:39], v12 offset0:177 offset1:193
	ds_read2_b32 v[40:41], v12 offset0:64 offset1:80
	ds_read2_b32 v[42:43], v12 offset0:209 offset1:225
	s_waitcnt lgkmcnt(5)
	v_cvt_pk_bf16_f32 v29, v30, v33
	s_waitcnt lgkmcnt(4)
	v_cvt_pk_bf16_f32 v30, v31, v34
	s_waitcnt lgkmcnt(3)
	v_cvt_pk_bf16_f32 v31, v36, v35
	s_waitcnt lgkmcnt(2)
	v_cvt_pk_bf16_f32 v33, v37, v38
	s_waitcnt lgkmcnt(1)
	v_cvt_pk_bf16_f32 v34, v40, v39
	s_waitcnt lgkmcnt(0)
	v_cvt_pk_bf16_f32 v35, v41, v42
	global_store_dword v[54:55], v29, off
	global_store_dword v[48:49], v30, off
	global_store_dword v[56:57], v31, off
	global_store_dword v[50:51], v33, off
	global_store_dword v[58:59], v34, off
	global_store_dword v[52:53], v35, off
	v_add_u32_e32 v29, s26, v19
	v_cvt_pk_bf16_f32 v32, v32, v43
	v_cmp_gt_u32_e32 vcc, s10, v29
	global_store_dword v[46:47], v32, off
	s_and_saveexec_b64 s[6:7], vcc
	s_cbranch_execz .LBB0_169
	ds_read2_b32 v[30:31], v12 offset0:112 offset1:241
	v_lshlrev_b32_e32 v29, 1, v29
	v_and_or_b32 v29, v29, s19, v19
	v_mov_b32_e32 v33, v1
	v_lshl_or_b32 v32, v29, 11, v28
	s_waitcnt lgkmcnt(0)
	v_cvt_pk_bf16_f32 v29, v30, v31
	v_lshl_add_u64 v[6:7], v[6:7], 0, v[32:33]
	global_store_dword v[6:7], v29, off

; __device__ __forceinline__ unsigned pk2(float lo, float hi) { f32x2_t v = {lo, hi}; bf16x2_t b = __builtin_convertvector(v, bf16x2_t); return __builtin_bit_cast(unsigned, b); }
; template <bool BATCH>
; __device__ __forceinline__ void transpose_tile(const float* __restrict__ src, int ld, int N, int K, int k0, int n0, bfu* __restrict__ dst,
;                                                int blk, int stride, int off, float* tl  ) {
;     ...
;         } else {
; #pragma unroll
;             for (int i = 0; i < 4; ++i) v[i] = (n0 + n4 < N) ? *(const float4*)(src + (size_t)(k0 + kk + 16 * i) * ld + n0 + n4) : make_float4(0.f, 0.f, 0.f, 0.f);
;         }
; #pragma unroll
;         for (int i = 0; i < 4; ++i) { float* t = tl + (kk + 16 * i) * 129 + n4; t[0] = v[i].x; t[1] = v[i].y; t[2] = v[i].z; t[3] = v[i].w; }
;     }
;     __syncthreads();
;     {
;         const int k2 = (tid & 31) * 2, nn = tid >> 5;
; #pragma unroll
;         for (int i = 0; i < 8; ++i) {
;             const int nl = nn + 16 * i, ng = n0 + nl;
;             if (ng < N) { const int row = (ng / blk) * stride + (ng % blk) + off; *(unsigned*)(dst + (size_t)row * K + k0 + k2) = pk2(tl[k2 * 129 + nl], tl[(k2 + 1) * 129 + nl]); }
;         }
;     }
; template <bool BATCH>
; __device__ __forceinline__ void weight_job(const Params& p, int job, float* ldsf) {
;     ...
;     if (j < J_G) { transpose_tile<BATCH>(p.w_gate, DFF, DFF, 1024, (j / 22) * 64, (j % 22) * 128, (bfu*)(ws + WS_WGU), 128, 256, 0, ldsf); return; }
.LBB0_170:
	s_and_b64 vcc, exec, s[6:7]
	s_cbranch_vccz .LBB0_177
	s_add_i32 s4, s3, 0xfbf0
	s_and_b32 s24, s4, 0xffff
	s_mul_i32 s24, s24, 0xba2f
	s_lshr_b32 s24, s24, 20
	s_load_dwordx2 s[6:7], s[0:1], 0x88
	s_mul_i32 s25, s24, 22
	s_sub_i32 s25, s4, s25
	s_lshl_b32 s4, s25, 7
	s_and_b32 s4, s4, 0xff80
	s_lshl_b32 s26, s4, 2
	v_lshl_or_b32 v29, s24, 6, v8
	s_waitcnt lgkmcnt(0)
	s_add_u32 s6, s6, s26
	s_addc_u32 s7, s7, 0
	v_mul_u32_u24_e32 v29, 0xb00, v29
	v_lshl_add_u64 v[6:7], s[6:7], 0, v[0:1]
	v_lshlrev_b32_e32 v30, 2, v29
	v_mov_b32_e32 v31, v1
	v_lshl_add_u64 v[6:7], v[6:7], 0, v[30:31]
	v_add_co_u32_e32 v38, vcc, s11, v6
	v_add_u32_e32 v29, s4, v19
	s_nop 0
	v_addc_co_u32_e32 v39, vcc, 0, v7, vcc
	global_load_dwordx4 v[30:33], v[6:7], off nt
	global_load_dwordx4 v[34:37], v[38:39], off nt
	v_add_co_u32_e32 v38, vcc, s14, v6
	s_lshl_b32 s4, s24, 7
	s_nop 0
	v_addc_co_u32_e32 v39, vcc, 0, v7, vcc
	global_load_dwordx4 v[38:41], v[38:39], off nt
	v_add_co_u32_e32 v6, vcc, s15, v6
	s_lshl_b32 s6, s25, 8
	s_nop 0
	v_addc_co_u32_e32 v7, vcc, 0, v7, vcc
	global_load_dwordx4 v[42:45], v[6:7], off nt
	v_lshl_add_u64 v[6:7], v[2:3], 0, s[4:5]
	s_and_b32 s4, s6, 0xff00
	v_or_b32_e32 v46, s4, v8
	v_mov_b32_e32 v47, v1
	v_or_b32_e32 v48, s4, v9
	v_or_b32_e32 v50, s4, v10
	v_or_b32_e32 v52, s4, v11
	v_or_b32_e32 v54, s4, v15
	v_or_b32_e32 v56, s4, v16
	v_or_b32_e32 v58, s4, v18
	v_lshlrev_b32_e32 v46, 11, v46
	v_mov_b32_e32 v49, v1
	v_mov_b32_e32 v51, v1
	v_mov_b32_e32 v53, v1
	v_mov_b32_e32 v55, v1
	v_mov_b32_e32 v57, v1
	v_mov_b32_e32 v59, v1
	v_lshlrev_b32_e32 v48, 11, v48
	v_lshlrev_b32_e32 v50, 11, v50
	v_lshlrev_b32_e32 v52, 11, v52
	v_lshlrev_b32_e32 v54, 11, v54
	v_lshlrev_b32_e32 v56, 11, v56
	v_lshlrev_b32_e32 v58, 11, v58
	v_lshl_add_u64 v[46:47], v[6:7], 0, v[46:47]
	v_cmp_gt_u32_e32 vcc, s10, v29
	v_lshl_add_u64 v[48:49], v[6:7], 0, v[48:49]
	v_lshl_add_u64 v[50:51], v[6:7], 0, v[50:51]
	v_lshl_add_u64 v[52:53], v[6:7], 0, v[52:53]
	v_lshl_add_u64 v[54:55], v[6:7], 0, v[54:55]
	v_lshl_add_u64 v[56:57], v[6:7], 0, v[56:57]
	v_lshl_add_u64 v[58:59], v[6:7], 0, v[58:59]
	s_waitcnt vmcnt(0)
	ds_write2_b32 v21, v30, v31 offset1:1
	ds_write2_b32 v21, v32, v33 offset0:2 offset1:3
	ds_write2_b32 v22, v34, v35 offset1:1
	ds_write2_b32 v23, v36, v37 offset1:1
	ds_write2_b32 v24, v38, v39 offset1:1
	ds_write2_b32 v25, v40, v41 offset1:1
	ds_write2_b32 v26, v42, v43 offset1:1
	ds_write2_b32 v27, v44, v45 offset1:1
	s_waitcnt lgkmcnt(0)
	s_barrier
	ds_read2_b32 v[30:31], v12 offset1:16
	ds_read2_b32 v[32:33], v12 offset0:96 offset1:129
	ds_read2_b32 v[34:35], v12 offset0:145 offset1:161
	ds_read2_b32 v[36:37], v12 offset0:32 offset1:48
	ds_read2_b32 v[38:39], v12 offset0:177 offset1:193
	ds_read2_b32 v[40:41], v12 offset0:64 offset1:80
	ds_read2_b32 v[42:43], v12 offset0:209 offset1:225
	s_waitcnt lgkmcnt(5)
	v_cvt_pk_bf16_f32 v30, v30, v33
	s_waitcnt lgkmcnt(4)
	v_cvt_pk_bf16_f32 v31, v31, v34
	s_waitcnt lgkmcnt(3)
	v_cvt_pk_bf16_f32 v33, v36, v35
	s_waitcnt lgkmcnt(2)
	v_cvt_pk_bf16_f32 v34, v37, v38
	s_waitcnt lgkmcnt(1)
	v_cvt_pk_bf16_f32 v35, v40, v39
	s_waitcnt lgkmcnt(0)
	v_cvt_pk_bf16_f32 v36, v41, v42
	v_cvt_pk_bf16_f32 v32, v32, v43
	global_store_dword v[46:47], v30, off
	global_store_dword v[48:49], v31, off
	global_store_dword v[50:51], v33, off
	global_store_dword v[52:53], v34, off
	global_store_dword v[54:55], v35, off
	global_store_dword v[56:57], v36, off
	global_store_dword v[58:59], v32, off
	s_and_saveexec_b64 s[6:7], vcc
	s_cbranch_execz .LBB0_173
	ds_read2_b32 v[30:31], v12 offset0:112 offset1:241
	v_lshlrev_b32_e32 v29, 1, v29
	v_and_or_b32 v29, v29, s19, v20
	v_mov_b32_e32 v33, v1
	v_lshlrev_b32_e32 v32, 11, v29
	s_waitcnt lgkmcnt(0)
	v_cvt_pk_bf16_f32 v29, v30, v31
	v_lshl_add_u64 v[6:7], v[6:7], 0, v[32:33]
	global_store_dword v[6:7], v29, off

; __device__ __forceinline__ unsigned pk2(float lo, float hi) { f32x2_t v = {lo, hi}; bf16x2_t b = __builtin_convertvector(v, bf16x2_t); return __builtin_bit_cast(unsigned, b); }
; template <bool BATCH>
; __device__ __forceinline__ void transpose_tile(const float* __restrict__ src, int ld, int N, int K, int k0, int n0, bfu* __restrict__ dst,
;                                                int blk, int stride, int off, float* tl  ) {
;     ...
;         } else {
; #pragma unroll
;             for (int i = 0; i < 4; ++i) v[i] = (n0 + n4 < N) ? *(const float4*)(src + (size_t)(k0 + kk + 16 * i) * ld + n0 + n4) : make_float4(0.f, 0.f, 0.f, 0.f);
;         }
; #pragma unroll
;         for (int i = 0; i < 4; ++i) { float* t = tl + (kk + 16 * i) * 129 + n4; t[0] = v[i].x; t[1] = v[i].y; t[2] = v[i].z; t[3] = v[i].w; }
;     }
;     __syncthreads();
;     {
;         const int k2 = (tid & 31) * 2, nn = tid >> 5;
; #pragma unroll
;         for (int i = 0; i < 8; ++i) {
;             const int nl = nn + 16 * i, ng = n0 + nl;
;             if (ng < N) { const int row = (ng / blk) * stride + (ng % blk) + off; *(unsigned*)(dst + (size_t)row * K + k0 + k2) = pk2(tl[k2 * 129 + nl], tl[(k2 + 1) * 129 + nl]); }
;         }
;     }
; template <bool BATCH>
; __device__ __forceinline__ void weight_job(const Params& p, int job, float* ldsf) {
;     ...
;     if (j < J_OUT) { transpose_tile<BATCH>(p.w_out, 1024, 1024, 2048, (j / 8) * 64, (j % 8) * 128, (bfu*)(ws + WS_WOUT), BIG, 0, 0, ldsf); return; }
.LBB0_175:
	s_load_dwordx2 s[6:7], s[0:1], 0x70
	s_and_b32 s24, s9, 0x380
	s_and_b32 s4, s8, 0x7fffffc0
	s_lshl_b32 s25, s24, 2
	v_or_b32_e32 v29, s4, v8
	s_waitcnt lgkmcnt(0)
	s_add_u32 s6, s6, s25
	s_addc_u32 s7, s7, 0
	v_lshl_add_u64 v[6:7], s[6:7], 0, v[0:1]
	v_lshlrev_b32_e32 v30, 10, v29
	v_mov_b32_e32 v31, v1
	v_lshl_add_u64 v[6:7], v[30:31], 2, v[6:7]
	v_add_co_u32_e32 v38, vcc, s20, v6
	s_lshl_b32 s4, s4, 1
	s_nop 0
	v_addc_co_u32_e32 v39, vcc, 0, v7, vcc
	global_load_dwordx4 v[30:33], v[6:7], off nt
	global_load_dwordx4 v[34:37], v[38:39], off nt
	v_add_co_u32_e32 v38, vcc, s21, v6
	v_mov_b32_e32 v47, v1
	s_nop 0
	v_addc_co_u32_e32 v39, vcc, 0, v7, vcc
	global_load_dwordx4 v[38:41], v[38:39], off nt
	v_add_co_u32_e32 v6, vcc, s22, v6
	v_or_b32_e32 v50, s24, v10
	s_nop 0
	v_addc_co_u32_e32 v7, vcc, 0, v7, vcc
	global_load_dwordx4 v[42:45], v[6:7], off nt
	v_or_b32_e32 v6, s24, v8
	v_or_b32_e32 v7, s24, v9
	v_or_b32_e32 v52, s24, v11
	v_or_b32_e32 v54, s24, v15
	v_or_b32_e32 v56, s24, v16
	v_or_b32_e32 v58, s24, v18
	v_add_u32_e32 v29, s24, v19
	v_lshlrev_b32_e32 v46, 12, v6
	v_lshlrev_b32_e32 v48, 12, v7
	v_lshl_add_u64 v[6:7], v[4:5], 0, s[4:5]
	v_mov_b32_e32 v49, v1
	v_mov_b32_e32 v51, v1
	v_mov_b32_e32 v53, v1
	v_mov_b32_e32 v55, v1
	v_mov_b32_e32 v57, v1
	v_mov_b32_e32 v59, v1
	v_lshlrev_b32_e32 v50, 12, v50
	v_lshlrev_b32_e32 v52, 12, v52
	v_lshlrev_b32_e32 v54, 12, v54
	v_lshlrev_b32_e32 v56, 12, v56
	v_lshlrev_b32_e32 v58, 12, v58
	v_lshl_add_u64 v[46:47], v[6:7], 0, v[46:47]
	v_cmp_gt_u32_e32 vcc, s23, v29
	v_lshl_add_u64 v[48:49], v[6:7], 0, v[48:49]
	v_lshl_add_u64 v[50:51], v[6:7], 0, v[50:51]
	v_lshl_add_u64 v[52:53], v[6:7], 0, v[52:53]
	v_lshl_add_u64 v[54:55], v[6:7], 0, v[54:55]
	v_lshl_add_u64 v[56:57], v[6:7], 0, v[56:57]
	v_lshl_add_u64 v[58:59], v[6:7], 0, v[58:59]
	s_waitcnt vmcnt(0)
	ds_write2_b32 v21, v30, v31 offset1:1
	ds_write2_b32 v21, v32, v33 offset0:2 offset1:3
	ds_write2_b32 v22, v34, v35 offset1:1
	ds_write2_b32 v23, v36, v37 offset1:1
	ds_write2_b32 v24, v38, v39 offset1:1
	ds_write2_b32 v25, v40, v41 offset1:1
	ds_write2_b32 v26, v42, v43 offset1:1
	ds_write2_b32 v27, v44, v45 offset1:1
	s_waitcnt lgkmcnt(0)
	s_barrier
	ds_read2_b32 v[30:31], v12 offset1:16
	ds_read2_b32 v[32:33], v12 offset0:96 offset1:129
	ds_read2_b32 v[34:35], v12 offset0:145 offset1:161
	ds_read2_b32 v[36:37], v12 offset0:32 offset1:48
	ds_read2_b32 v[38:39], v12 offset0:177 offset1:193
	ds_read2_b32 v[40:41], v12 offset0:64 offset1:80
	ds_read2_b32 v[42:43], v12 offset0:209 offset1:225
	s_waitcnt lgkmcnt(5)
	v_cvt_pk_bf16_f32 v30, v30, v33
	s_waitcnt lgkmcnt(4)
	v_cvt_pk_bf16_f32 v31, v31, v34
	s_waitcnt lgkmcnt(3)
	v_cvt_pk_bf16_f32 v33, v36, v35
	s_waitcnt lgkmcnt(2)
	v_cvt_pk_bf16_f32 v34, v37, v38
	s_waitcnt lgkmcnt(1)
	v_cvt_pk_bf16_f32 v35, v40, v39
	s_waitcnt lgkmcnt(0)
	v_cvt_pk_bf16_f32 v36, v41, v42
	v_cvt_pk_bf16_f32 v32, v32, v43
	global_store_dword v[46:47], v30, off
	global_store_dword v[48:49], v31, off
	global_store_dword v[50:51], v33, off
	global_store_dword v[52:53], v34, off
	global_store_dword v[54:55], v35, off
	global_store_dword v[56:57], v36, off
	global_store_dword v[58:59], v32, off
	s_and_saveexec_b64 s[6:7], vcc
	s_cbranch_execz .LBB0_163
	ds_read2_b32 v[30:31], v12 offset0:112 offset1:241
	v_lshlrev_b32_e32 v32, 12, v29
	v_mov_b32_e32 v33, v1
	v_lshl_add_u64 v[6:7], v[6:7], 0, v[32:33]
	s_waitcnt lgkmcnt(0)
	v_cvt_pk_bf16_f32 v29, v30, v31
	global_store_dword v[6:7], v29, off
	s_branch .LBB0_163

; __device__ __forceinline__ unsigned pk2(float lo, float hi) { f32x2_t v = {lo, hi}; bf16x2_t b = __builtin_convertvector(v, bf16x2_t); return __builtin_bit_cast(unsigned, b); }
; __device__ __forceinline__ float bflo(unsigned u) { return __uint_as_float(u << 16); }
; __device__ __forceinline__ float bfhi(unsigned u) { return __uint_as_float(u & 0xffff0000u); }
; __device__ __forceinline__ void phase4_scan(const Params& p, int bid, int G) {
;     ...
;         for (int c = 0; c < 32; ++c) {
;             const float dec = decay[(b * 32 + c) * 16 + h];
;             const size_t off = ((size_t)((b * 32 + c) * 16 + h) * 64 + pp) * 128 + n;
;             const uint2 su = *(const uint2*)(states + off);
;             const float4 st = make_float4(bflo(su.x), bfhi(su.x), bflo(su.y), bfhi(su.y));
;             uint2 o; o.x = pk2(hc.x, hc.y); o.y = pk2(hc.z, hc.w);
;             *(uint2*)(hprev + off) = o;
;             hc.x = hc.x * dec + st.x; hc.y = hc.y * dec + st.y; hc.z = hc.z * dec + st.z; hc.w = hc.w * dec + st.w;
;         }
.LBB0_468:
	v_lshl_add_u64 v[78:79], s[10:11], 0, v[70:71]
	v_add_co_u32_e32 v116, vcc, s16, v78
	v_lshl_add_u64 v[72:73], s[10:11], 0, v[68:69]
	s_nop 0
	v_addc_co_u32_e32 v117, vcc, 0, v79, vcc
	v_add_co_u32_e32 v78, vcc, s17, v78
	v_lshl_add_u64 v[82:83], s[10:11], 0, v[64:65]
	s_nop 0
	v_addc_co_u32_e32 v79, vcc, 0, v79, vcc
	v_cvt_pk_bf16_f32 v74, v0, v1
	v_cvt_pk_bf16_f32 v75, v2, v3
	v_add_co_u32_e32 v118, vcc, s16, v82
	global_load_dword v72, v[72:73], off
	s_nop 0
	global_load_dwordx2 v[116:117], v[116:117], off nt
	v_lshl_add_u64 v[76:77], s[10:11], 0, v[66:67]
	v_addc_co_u32_e32 v119, vcc, 0, v83, vcc
	global_store_dwordx2 v[78:79], v[74:75], off
	global_load_dwordx2 v[74:75], v[118:119], off nt
	s_nop 0
	global_load_dword v76, v[76:77], off
	v_add_co_u32_e32 v82, vcc, s17, v82
	v_lshl_add_u64 v[86:87], s[10:11], 0, v[60:61]
	s_nop 0
	v_addc_co_u32_e32 v83, vcc, 0, v83, vcc
	v_add_co_u32_e32 v120, vcc, s16, v86
	v_lshl_add_u64 v[90:91], s[10:11], 0, v[56:57]
	s_nop 0
	v_addc_co_u32_e32 v121, vcc, 0, v87, vcc
	v_add_co_u32_e32 v86, vcc, s17, v86
	v_lshl_add_u64 v[84:85], s[10:11], 0, v[62:63]
	s_nop 0
	v_addc_co_u32_e32 v87, vcc, 0, v87, vcc
	v_add_co_u32_e32 v122, vcc, s16, v90
	v_lshl_add_u64 v[88:89], s[10:11], 0, v[58:59]
	s_nop 0
	v_addc_co_u32_e32 v123, vcc, 0, v91, vcc
	v_add_co_u32_e32 v90, vcc, s17, v90
	v_lshl_add_u64 v[94:95], s[10:11], 0, v[52:53]
	s_nop 0
	v_addc_co_u32_e32 v91, vcc, 0, v91, vcc
	v_add_co_u32_e32 v124, vcc, s16, v94
	v_lshl_add_u64 v[98:99], s[10:11], 0, v[48:49]
	s_nop 0
	v_addc_co_u32_e32 v125, vcc, 0, v95, vcc
	v_add_co_u32_e32 v94, vcc, s17, v94
	v_lshl_add_u64 v[92:93], s[10:11], 0, v[54:55]
	s_nop 0
	v_addc_co_u32_e32 v95, vcc, 0, v95, vcc
	v_add_co_u32_e32 v126, vcc, s16, v98
	v_lshl_add_u64 v[96:97], s[10:11], 0, v[50:51]
	s_nop 0
	v_addc_co_u32_e32 v127, vcc, 0, v99, vcc
	v_add_co_u32_e32 v98, vcc, s17, v98
	v_lshl_add_u64 v[102:103], s[10:11], 0, v[44:45]
	s_nop 0
	v_addc_co_u32_e32 v99, vcc, 0, v99, vcc
	v_add_co_u32_e32 v128, vcc, s16, v102
	v_lshl_add_u64 v[106:107], s[10:11], 0, v[40:41]
	s_nop 0
	v_addc_co_u32_e32 v129, vcc, 0, v103, vcc
	v_add_co_u32_e32 v102, vcc, s17, v102
	v_lshl_add_u64 v[100:101], s[10:11], 0, v[46:47]
	s_nop 0
	v_addc_co_u32_e32 v103, vcc, 0, v103, vcc
	v_add_co_u32_e32 v130, vcc, s16, v106
	v_lshl_add_u64 v[104:105], s[10:11], 0, v[42:43]
	s_nop 0
	v_addc_co_u32_e32 v131, vcc, 0, v107, vcc
	v_lshl_add_u64 v[110:111], s[10:11], 0, v[36:37]
	v_lshl_add_u64 v[114:115], s[10:11], 0, v[32:33]
	v_lshl_add_u64 v[108:109], s[10:11], 0, v[38:39]
	v_lshl_add_u64 v[112:113], s[10:11], 0, v[34:35]
	s_add_i32 s19, s19, -16
	v_lshl_add_u64 v[32:33], v[32:33], 0, s[12:13]
	v_lshl_add_u64 v[34:35], v[34:35], 0, s[14:15]
	v_lshl_add_u64 v[36:37], v[36:37], 0, s[12:13]
	v_lshl_add_u64 v[38:39], v[38:39], 0, s[14:15]
	v_lshl_add_u64 v[40:41], v[40:41], 0, s[12:13]
	v_lshl_add_u64 v[42:43], v[42:43], 0, s[14:15]
	v_lshl_add_u64 v[44:45], v[44:45], 0, s[12:13]
	v_lshl_add_u64 v[46:47], v[46:47], 0, s[14:15]
	v_lshl_add_u64 v[48:49], v[48:49], 0, s[12:13]
	s_waitcnt vmcnt(3)
	v_lshlrev_b32_e32 v78, 16, v116
	v_and_b32_e32 v79, 0xffff0000, v116
	v_lshlrev_b32_e32 v116, 16, v117
	v_and_b32_e32 v117, 0xffff0000, v117
	v_pk_fma_f32 v[0:1], v[0:1], v[72:73], v[78:79] op_sel_hi:[1,0,1]
	v_pk_fma_f32 v[2:3], v[2:3], v[72:73], v[116:117] op_sel_hi:[1,0,1]
	s_waitcnt vmcnt(1)
	v_lshlrev_b32_e32 v72, 16, v74
	v_and_b32_e32 v73, 0xffff0000, v74
	v_lshlrev_b32_e32 v74, 16, v75
	v_and_b32_e32 v75, 0xffff0000, v75
	v_cvt_pk_bf16_f32 v78, v0, v1
	v_cvt_pk_bf16_f32 v79, v2, v3
	s_waitcnt vmcnt(0)
	v_pk_fma_f32 v[0:1], v[0:1], v[76:77], v[72:73] op_sel_hi:[1,0,1]
	v_pk_fma_f32 v[2:3], v[2:3], v[76:77], v[74:75] op_sel_hi:[1,0,1]
	global_store_dwordx2 v[82:83], v[78:79], off
	v_cvt_pk_bf16_f32 v72, v0, v1
	v_cvt_pk_bf16_f32 v73, v2, v3
	global_load_dwordx2 v[74:75], v[120:121], off nt
	global_load_dword v76, v[84:85], off
	v_lshl_add_u64 v[50:51], v[50:51], 0, s[14:15]
	global_store_dwordx2 v[86:87], v[72:73], off
	global_load_dwordx2 v[72:73], v[122:123], off nt
	s_nop 0
	global_load_dword v78, v[88:89], off
	v_lshl_add_u64 v[52:53], v[52:53], 0, s[12:13]
	v_lshl_add_u64 v[54:55], v[54:55], 0, s[14:15]
	v_lshl_add_u64 v[56:57], v[56:57], 0, s[12:13]
	v_lshl_add_u64 v[58:59], v[58:59], 0, s[14:15]
	v_lshl_add_u64 v[60:61], v[60:61], 0, s[12:13]
	v_lshl_add_u64 v[62:63], v[62:63], 0, s[14:15]
	v_lshl_add_u64 v[64:65], v[64:65], 0, s[12:13]
	v_lshl_add_u64 v[66:67], v[66:67], 0, s[14:15]
	v_lshl_add_u64 v[68:69], v[68:69], 0, s[14:15]
	v_lshl_add_u64 v[70:71], v[70:71], 0, s[12:13]
	s_cmp_eq_u32 s19, 0
	s_waitcnt vmcnt(4)
	v_lshlrev_b32_e32 v82, 16, v74
	v_and_b32_e32 v83, 0xffff0000, v74
	v_lshlrev_b32_e32 v74, 16, v75
	v_and_b32_e32 v75, 0xffff0000, v75
	s_waitcnt vmcnt(3)
	v_pk_fma_f32 v[0:1], v[0:1], v[76:77], v[82:83] op_sel_hi:[1,0,1]
	v_pk_fma_f32 v[2:3], v[2:3], v[76:77], v[74:75] op_sel_hi:[1,0,1]
	s_waitcnt vmcnt(1)
	v_lshlrev_b32_e32 v74, 16, v72
	v_and_b32_e32 v75, 0xffff0000, v72
	v_lshlrev_b32_e32 v72, 16, v73
	v_and_b32_e32 v73, 0xffff0000, v73
	v_cvt_pk_bf16_f32 v76, v0, v1
	v_cvt_pk_bf16_f32 v77, v2, v3
	s_waitcnt vmcnt(0)
	v_pk_fma_f32 v[0:1], v[0:1], v[78:79], v[74:75] op_sel_hi:[1,0,1]
	v_pk_fma_f32 v[2:3], v[2:3], v[78:79], v[72:73] op_sel_hi:[1,0,1]
	global_store_dwordx2 v[90:91], v[76:77], off
	v_cvt_pk_bf16_f32 v72, v0, v1
	v_cvt_pk_bf16_f32 v73, v2, v3
	global_load_dwordx2 v[74:75], v[124:125], off nt
	global_load_dword v76, v[92:93], off
	v_add_co_u32_e32 v82, vcc, s17, v106
	global_store_dwordx2 v[94:95], v[72:73], off
	global_load_dwordx2 v[72:73], v[126:127], off nt
	s_nop 0
	global_load_dword v78, v[96:97], off
	v_addc_co_u32_e32 v83, vcc, 0, v107, vcc
	s_waitcnt vmcnt(4)
; __device__ __forceinline__ unsigned pk2(float lo, float hi) { f32x2_t v = {lo, hi}; bf16x2_t b = __builtin_convertvector(v, bf16x2_t); return __builtin_bit_cast(unsigned, b); }
; __device__ __forceinline__ float bflo(unsigned u) { return __uint_as_float(u << 16); }
; __device__ __forceinline__ float bfhi(unsigned u) { return __uint_as_float(u & 0xffff0000u); }
; __device__ __forceinline__ void phase4_scan(const Params& p, int bid, int G) {
;     ...
;         for (int c = 0; c < 32; ++c) {
;             const float dec = decay[(b * 32 + c) * 16 + h];
;             const size_t off = ((size_t)((b * 32 + c) * 16 + h) * 64 + pp) * 128 + n;
;             const uint2 su = *(const uint2*)(states + off);
;             const float4 st = make_float4(bflo(su.x), bfhi(su.x), bflo(su.y), bfhi(su.y));
;             uint2 o; o.x = pk2(hc.x, hc.y); o.y = pk2(hc.z, hc.w);
;             *(uint2*)(hprev + off) = o;
;             hc.x = hc.x * dec + st.x; hc.y = hc.y * dec + st.y; hc.z = hc.z * dec + st.z; hc.w = hc.w * dec + st.w;
;         }
	v_lshlrev_b32_e32 v84, 16, v74
	v_and_b32_e32 v85, 0xffff0000, v74
	v_lshlrev_b32_e32 v74, 16, v75
	v_and_b32_e32 v75, 0xffff0000, v75
	s_waitcnt vmcnt(3)
	v_pk_fma_f32 v[0:1], v[0:1], v[76:77], v[84:85] op_sel_hi:[1,0,1]
	v_pk_fma_f32 v[2:3], v[2:3], v[76:77], v[74:75] op_sel_hi:[1,0,1]
	s_waitcnt vmcnt(1)
	v_lshlrev_b32_e32 v74, 16, v72
	v_and_b32_e32 v75, 0xffff0000, v72
	v_lshlrev_b32_e32 v72, 16, v73
	v_and_b32_e32 v73, 0xffff0000, v73
	v_cvt_pk_bf16_f32 v76, v0, v1
	v_cvt_pk_bf16_f32 v77, v2, v3
	s_waitcnt vmcnt(0)
	v_pk_fma_f32 v[0:1], v[0:1], v[78:79], v[74:75] op_sel_hi:[1,0,1]
	v_pk_fma_f32 v[2:3], v[2:3], v[78:79], v[72:73] op_sel_hi:[1,0,1]
	global_store_dwordx2 v[98:99], v[76:77], off
	v_cvt_pk_bf16_f32 v72, v0, v1
	v_cvt_pk_bf16_f32 v73, v2, v3
	global_load_dwordx2 v[74:75], v[128:129], off nt
	global_load_dword v76, v[100:101], off
	v_add_co_u32_e32 v84, vcc, s16, v110
	global_store_dwordx2 v[102:103], v[72:73], off
	global_load_dwordx2 v[72:73], v[130:131], off nt
	s_nop 0
	global_load_dword v78, v[104:105], off
	v_addc_co_u32_e32 v85, vcc, 0, v111, vcc
	v_add_co_u32_e32 v86, vcc, s17, v110
	s_waitcnt vmcnt(4)
	v_lshlrev_b32_e32 v90, 16, v74
	v_and_b32_e32 v91, 0xffff0000, v74
	v_lshlrev_b32_e32 v74, 16, v75
	v_and_b32_e32 v75, 0xffff0000, v75
	s_waitcnt vmcnt(3)
	v_pk_fma_f32 v[0:1], v[0:1], v[76:77], v[90:91] op_sel_hi:[1,0,1]
	v_pk_fma_f32 v[2:3], v[2:3], v[76:77], v[74:75] op_sel_hi:[1,0,1]
	s_waitcnt vmcnt(1)
	v_lshlrev_b32_e32 v74, 16, v72
	v_and_b32_e32 v75, 0xffff0000, v72
	v_lshlrev_b32_e32 v72, 16, v73
	v_and_b32_e32 v73, 0xffff0000, v73
	v_addc_co_u32_e32 v87, vcc, 0, v111, vcc
	v_cvt_pk_bf16_f32 v76, v0, v1
	v_cvt_pk_bf16_f32 v77, v2, v3
	s_waitcnt vmcnt(0)
	v_pk_fma_f32 v[0:1], v[0:1], v[78:79], v[74:75] op_sel_hi:[1,0,1]
	v_pk_fma_f32 v[2:3], v[2:3], v[78:79], v[72:73] op_sel_hi:[1,0,1]
	v_add_co_u32_e32 v88, vcc, s16, v114
	global_store_dwordx2 v[82:83], v[76:77], off
	v_cvt_pk_bf16_f32 v72, v0, v1
	v_cvt_pk_bf16_f32 v73, v2, v3
	v_addc_co_u32_e32 v89, vcc, 0, v115, vcc
	global_load_dwordx2 v[74:75], v[84:85], off nt
	global_load_dword v76, v[108:109], off
	v_add_co_u32_e32 v90, vcc, s17, v114
	global_store_dwordx2 v[86:87], v[72:73], off
	global_load_dwordx2 v[72:73], v[88:89], off nt
	s_nop 0
	global_load_dword v78, v[112:113], off
	v_lshl_add_u64 v[84:85], s[10:11], 0, v[28:29]
	v_addc_co_u32_e32 v91, vcc, 0, v115, vcc
	v_add_co_u32_e32 v92, vcc, s16, v84
	v_lshl_add_u64 v[88:89], s[10:11], 0, v[24:25]
	s_nop 0
	v_addc_co_u32_e32 v93, vcc, 0, v85, vcc
	v_add_co_u32_e32 v84, vcc, s17, v84
	v_lshl_add_u64 v[82:83], s[10:11], 0, v[30:31]
	s_nop 0
	v_addc_co_u32_e32 v85, vcc, 0, v85, vcc
	v_add_co_u32_e32 v94, vcc, s16, v88
	v_lshl_add_u64 v[86:87], s[10:11], 0, v[26:27]
	s_nop 0
	v_addc_co_u32_e32 v95, vcc, 0, v89, vcc
	v_add_co_u32_e32 v88, vcc, s17, v88
	v_lshl_add_u64 v[24:25], v[24:25], 0, s[12:13]
	s_nop 0
	v_addc_co_u32_e32 v89, vcc, 0, v89, vcc
	v_lshl_add_u64 v[26:27], v[26:27], 0, s[14:15]
	v_lshl_add_u64 v[28:29], v[28:29], 0, s[12:13]
	v_lshl_add_u64 v[30:31], v[30:31], 0, s[14:15]
	s_waitcnt vmcnt(4)
	v_lshlrev_b32_e32 v96, 16, v74
	v_and_b32_e32 v97, 0xffff0000, v74
	v_lshlrev_b32_e32 v74, 16, v75
	v_and_b32_e32 v75, 0xffff0000, v75
	s_waitcnt vmcnt(3)
	v_pk_fma_f32 v[0:1], v[0:1], v[76:77], v[96:97] op_sel_hi:[1,0,1]
	v_pk_fma_f32 v[2:3], v[2:3], v[76:77], v[74:75] op_sel_hi:[1,0,1]
	s_waitcnt vmcnt(1)
	v_lshlrev_b32_e32 v74, 16, v72
	v_and_b32_e32 v75, 0xffff0000, v72
	v_lshlrev_b32_e32 v72, 16, v73
	v_and_b32_e32 v73, 0xffff0000, v73
	v_cvt_pk_bf16_f32 v76, v0, v1
	v_cvt_pk_bf16_f32 v77, v2, v3
	s_waitcnt vmcnt(0)
	v_pk_fma_f32 v[0:1], v[0:1], v[78:79], v[74:75] op_sel_hi:[1,0,1]
	v_pk_fma_f32 v[2:3], v[2:3], v[78:79], v[72:73] op_sel_hi:[1,0,1]
	global_store_dwordx2 v[90:91], v[76:77], off
	v_cvt_pk_bf16_f32 v72, v0, v1
	v_cvt_pk_bf16_f32 v73, v2, v3
	global_load_dwordx2 v[74:75], v[92:93], off nt
	global_load_dword v76, v[82:83], off
	v_lshl_add_u64 v[90:91], s[10:11], 0, v[16:17]
	global_store_dwordx2 v[84:85], v[72:73], off
	global_load_dwordx2 v[72:73], v[94:95], off nt
	s_nop 0
	global_load_dword v78, v[86:87], off
	v_lshl_add_u64 v[84:85], s[10:11], 0, v[20:21]
	v_add_co_u32_e32 v92, vcc, s16, v84
	v_lshl_add_u64 v[82:83], s[10:11], 0, v[22:23]
	s_nop 0
	v_addc_co_u32_e32 v93, vcc, 0, v85, vcc
	v_add_co_u32_e32 v84, vcc, s17, v84
	v_lshl_add_u64 v[86:87], s[10:11], 0, v[18:19]
	s_nop 0
	v_addc_co_u32_e32 v85, vcc, 0, v85, vcc
	v_add_co_u32_e32 v94, vcc, s16, v90
	v_lshl_add_u64 v[16:17], v[16:17], 0, s[12:13]
	s_nop 0
	v_addc_co_u32_e32 v95, vcc, 0, v91, vcc
	v_add_co_u32_e32 v90, vcc, s17, v90
	v_lshl_add_u64 v[18:19], v[18:19], 0, s[14:15]
	s_nop 0
	v_addc_co_u32_e32 v91, vcc, 0, v91, vcc
	v_lshl_add_u64 v[20:21], v[20:21], 0, s[12:13]
	v_lshl_add_u64 v[22:23], v[22:23], 0, s[14:15]
	s_waitcnt vmcnt(4)
; __device__ __forceinline__ unsigned pk2(float lo, float hi) { f32x2_t v = {lo, hi}; bf16x2_t b = __builtin_convertvector(v, bf16x2_t); return __builtin_bit_cast(unsigned, b); }
; __device__ __forceinline__ float bflo(unsigned u) { return __uint_as_float(u << 16); }
; __device__ __forceinline__ float bfhi(unsigned u) { return __uint_as_float(u & 0xffff0000u); }
; __device__ __forceinline__ void phase4_scan(const Params& p, int bid, int G) {
;     ...
;     for (int i = bid * 512 + threadIdx.x; i < 131072; i += G * 512) {
;         const int e = i * 4, n = e & 127, pp = (e >> 7) & 63, h = (e >> 13) & 15, b = e >> 17;
;         float4 hc = make_float4(0.f, 0.f, 0.f, 0.f);
; #pragma unroll 16
;         for (int c = 0; c < 32; ++c) {
;             const float dec = decay[(b * 32 + c) * 16 + h];
;             const size_t off = ((size_t)((b * 32 + c) * 16 + h) * 64 + pp) * 128 + n;
;             const uint2 su = *(const uint2*)(states + off);
;             const float4 st = make_float4(bflo(su.x), bfhi(su.x), bflo(su.y), bfhi(su.y));
;             uint2 o; o.x = pk2(hc.x, hc.y); o.y = pk2(hc.z, hc.w);
;             *(uint2*)(hprev + off) = o;
;             hc.x = hc.x * dec + st.x; hc.y = hc.y * dec + st.y; hc.z = hc.z * dec + st.z; hc.w = hc.w * dec + st.w;
;         }
;         *(float4*)(p.out + O_SP + ((size_t)(b * 16 + h) * 64 + pp) * 128 + n) = hc;
;     }
	v_lshlrev_b32_e32 v96, 16, v74
	v_and_b32_e32 v97, 0xffff0000, v74
	v_lshlrev_b32_e32 v74, 16, v75
	v_and_b32_e32 v75, 0xffff0000, v75
	s_waitcnt vmcnt(3)
	v_pk_fma_f32 v[0:1], v[0:1], v[76:77], v[96:97] op_sel_hi:[1,0,1]
	v_pk_fma_f32 v[2:3], v[2:3], v[76:77], v[74:75] op_sel_hi:[1,0,1]
	s_waitcnt vmcnt(1)
	v_lshlrev_b32_e32 v74, 16, v72
	v_and_b32_e32 v75, 0xffff0000, v72
	v_lshlrev_b32_e32 v72, 16, v73
	v_and_b32_e32 v73, 0xffff0000, v73
	v_cvt_pk_bf16_f32 v76, v0, v1
	v_cvt_pk_bf16_f32 v77, v2, v3
	s_waitcnt vmcnt(0)
	v_pk_fma_f32 v[0:1], v[0:1], v[78:79], v[74:75] op_sel_hi:[1,0,1]
	v_pk_fma_f32 v[2:3], v[2:3], v[78:79], v[72:73] op_sel_hi:[1,0,1]
	global_store_dwordx2 v[88:89], v[76:77], off
	v_cvt_pk_bf16_f32 v72, v0, v1
	v_cvt_pk_bf16_f32 v73, v2, v3
	global_load_dwordx2 v[74:75], v[92:93], off nt
	global_load_dword v76, v[82:83], off
	v_lshl_add_u64 v[88:89], s[10:11], 0, v[8:9]
	global_store_dwordx2 v[84:85], v[72:73], off
	global_load_dwordx2 v[72:73], v[94:95], off nt
	s_nop 0
	global_load_dword v78, v[86:87], off
	v_lshl_add_u64 v[84:85], s[10:11], 0, v[12:13]
	v_add_co_u32_e32 v92, vcc, s16, v84
	v_lshl_add_u64 v[82:83], s[10:11], 0, v[14:15]
	s_nop 0
	v_addc_co_u32_e32 v93, vcc, 0, v85, vcc
	v_add_co_u32_e32 v84, vcc, s17, v84
	v_lshl_add_u64 v[86:87], s[10:11], 0, v[10:11]
	s_nop 0
	v_addc_co_u32_e32 v85, vcc, 0, v85, vcc
	v_add_co_u32_e32 v94, vcc, s16, v88
	v_lshl_add_u64 v[8:9], v[8:9], 0, s[12:13]
	s_nop 0
	v_addc_co_u32_e32 v95, vcc, 0, v89, vcc
	v_lshl_add_u64 v[10:11], v[10:11], 0, s[14:15]
	v_lshl_add_u64 v[12:13], v[12:13], 0, s[12:13]
	v_lshl_add_u64 v[14:15], v[14:15], 0, s[14:15]
	s_waitcnt vmcnt(4)
	v_lshlrev_b32_e32 v96, 16, v74
	v_and_b32_e32 v97, 0xffff0000, v74
	v_lshlrev_b32_e32 v74, 16, v75
	v_and_b32_e32 v75, 0xffff0000, v75
	s_waitcnt vmcnt(3)
	v_pk_fma_f32 v[0:1], v[0:1], v[76:77], v[96:97] op_sel_hi:[1,0,1]
	v_pk_fma_f32 v[2:3], v[2:3], v[76:77], v[74:75] op_sel_hi:[1,0,1]
	s_waitcnt vmcnt(1)
	v_lshlrev_b32_e32 v74, 16, v72
	v_and_b32_e32 v75, 0xffff0000, v72
	v_lshlrev_b32_e32 v72, 16, v73
	v_and_b32_e32 v73, 0xffff0000, v73
	v_cvt_pk_bf16_f32 v76, v0, v1
	v_cvt_pk_bf16_f32 v77, v2, v3
	s_waitcnt vmcnt(0)
	v_pk_fma_f32 v[0:1], v[0:1], v[78:79], v[74:75] op_sel_hi:[1,0,1]
	v_pk_fma_f32 v[2:3], v[2:3], v[78:79], v[72:73] op_sel_hi:[1,0,1]
	global_store_dwordx2 v[90:91], v[76:77], off
	v_cvt_pk_bf16_f32 v72, v0, v1
	v_cvt_pk_bf16_f32 v73, v2, v3
	global_load_dwordx2 v[74:75], v[92:93], off nt
	global_load_dword v76, v[82:83], off
	v_add_co_u32_e32 v82, vcc, s17, v88
	global_store_dwordx2 v[84:85], v[72:73], off
	global_load_dwordx2 v[72:73], v[94:95], off nt
	s_nop 0
	global_load_dword v78, v[86:87], off
	v_addc_co_u32_e32 v83, vcc, 0, v89, vcc
	s_waitcnt vmcnt(4)
	v_lshlrev_b32_e32 v84, 16, v74
	v_and_b32_e32 v85, 0xffff0000, v74
	v_lshlrev_b32_e32 v74, 16, v75
	v_and_b32_e32 v75, 0xffff0000, v75
	s_waitcnt vmcnt(3)
	v_pk_fma_f32 v[0:1], v[0:1], v[76:77], v[84:85] op_sel_hi:[1,0,1]
	v_pk_fma_f32 v[2:3], v[2:3], v[76:77], v[74:75] op_sel_hi:[1,0,1]
	s_waitcnt vmcnt(1)
	v_lshlrev_b32_e32 v74, 16, v72
	v_and_b32_e32 v75, 0xffff0000, v72
	v_lshlrev_b32_e32 v72, 16, v73
	v_and_b32_e32 v73, 0xffff0000, v73
	v_cvt_pk_bf16_f32 v76, v0, v1
	v_cvt_pk_bf16_f32 v77, v2, v3
	s_waitcnt vmcnt(0)
	v_pk_fma_f32 v[0:1], v[0:1], v[78:79], v[74:75] op_sel_hi:[1,0,1]
	v_pk_fma_f32 v[2:3], v[2:3], v[78:79], v[72:73] op_sel_hi:[1,0,1]
	global_store_dwordx2 v[82:83], v[76:77], off
	s_cbranch_scc0 .LBB0_468
	v_and_b32_e32 v6, 15, v6
	v_lshl_or_b32 v8, v81, 4, v6
	v_ashrrev_i32_e32 v9, 31, v8
	v_lshlrev_b64 v[8:9], 15, v[8:9]
	v_lshlrev_b32_e32 v10, 4, v178
	v_lshl_add_u64 v[8:9], s[8:9], 0, v[8:9]
	v_and_b32_e32 v6, 0x7e00, v10
	v_add_u32_e32 v178, s40, v178
	v_lshl_add_u64 v[8:9], v[8:9], 0, v[6:7]
	v_and_b32_e32 v6, 0x1f0, v10
	v_cmp_lt_i32_e32 vcc, s18, v178
	v_lshl_add_u64 v[8:9], v[8:9], 0, v[6:7]
	s_or_b64 s[4:5], vcc, s[4:5]
	v_add_u32_e32 v80, s3, v80
	global_store_dwordx4 v[8:9], v[0:3], off
	s_andn2_b64 exec, exec, s[4:5]
	s_cbranch_execnz .LBB0_467

; __device__ __forceinline__ void ssd_cumsum(const Params& p, int row0, int g, float* csb, float* dtb) {
;     ...
;     const float dt = ((const float*)(p.ws + WS_DT))[(size_t)(row0 + l) * 16 + h];
;     const float a = -__expf(p.a_log[h]);
;     float v = dt * a;
; #pragma unroll
;     for (int off = 1; off < 64; off <<= 1) { const float t = __shfl_up(v, off); if (lane >= off) v += t; }
;     dtb[tid] = dt; csb[tid] = v;
;     __syncthreads();
;     if (l >= 64) { v += csb[hh * 128 + 63]; }
; __device__ __forceinline__ void ssd_s3_unit(const Params& p, int unit, unsigned char* ldsb) {
;     ...
;     for (int i = 0; i < 4; ++i) {
;         const int e = tid + 512 * i, l = e >> 4, n8 = (e & 15) * 8;
;         *(uint4*)(Bs + l * 136 + n8) = *(const uint4*)(xbc + (size_t)(row0 + l) * 2048 + 1024 + g * 128 + n8);
;         *(uint4*)(Cs + l * 136 + n8) = *(const uint4*)(xbc + (size_t)(row0 + l) * 2048 + 1536 + g * 128 + n8);
;     }
; #pragma unroll
;     for (int i = 0; i < 8; ++i) {
;         const int e = tid + 512 * i, l = e & 127, p8 = (e >> 7) * 8;
;         const uint4 v = *(const uint4*)(xbc + (size_t)(row0 + l) * 2048 + g * 256 + p8);
;         bfu* tp = XT4 + p8 * 136 + l;
;         tp[0] = (bfu)(v.x & 0xffff); tp[136] = (bfu)(v.x >> 16); tp[2 * 136] = (bfu)(v.y & 0xffff); tp[3 * 136] = (bfu)(v.y >> 16);
;         tp[4 * 136] = (bfu)(v.z & 0xffff); tp[5 * 136] = (bfu)(v.z >> 16); tp[6 * 136] = (bfu)(v.w & 0xffff); tp[7 * 136] = (bfu)(v.w >> 16);
;     }
.LBB0_525:
	v_readlane_b32 s90, v252, 1
	v_readlane_b32 s91, v252, 2
	s_ashr_i32 s6, s87, 7
	s_lshl_b32 s0, s87, 5
	s_lshl_b32 s7, s6, 12
	s_and_b32 s0, s0, 0xf80
	s_or_b32 s21, s0, s7
	s_load_dwordx2 s[88:89], s[90:91], 0xb8
	s_load_dwordx2 s[0:1], s[90:91], 0x50
	s_and_b32 s20, s87, 3
	s_lshl_b32 s8, s20, 2
	v_or_b32_e32 v0, s21, v113
	v_ashrrev_i32_e32 v1, 31, v0
	v_add_lshl_u32 v52, s8, v196, 2
	v_lshlrev_b64 v[2:3], 6, v[0:1]
	s_waitcnt lgkmcnt(0)
	global_load_dword v4, v52, s[0:1]
	v_lshl_add_u64 v[2:3], s[88:89], 0, v[2:3]
	v_lshl_add_u64 v[2:3], v[2:3], 0, v[52:53]
	s_mov_b32 s0, 0x16600000
	v_add_co_u32_e32 v2, vcc, s0, v2
	v_add_u32_e32 v5, -1, v155
	s_nop 0
	v_addc_co_u32_e32 v3, vcc, 0, v3, vcc
	global_load_dword v2, v[2:3], off
	s_add_u32 s10, s88, 0x16800000
	s_addc_u32 s11, s89, 0
	s_lshl_b32 s12, s20, 8
	s_lshl_b32 s14, s20, 9
	v_or_b32_e32 v182, s21, v112
	v_lshlrev_b32_e32 v182, 12, v182
	v_add3_u32 v182, v182, s12, v84
	v_mov_b32_e32 v183, 0
	v_lshl_add_u64 v[182:183], s[10:11], 0, v[182:183]
	global_load_dwordx4 v[182:185], v[182:183], off offset:2048 nt
	v_or_b32_e32 v186, s21, v112
	v_lshlrev_b32_e32 v186, 12, v186
	v_add3_u32 v186, v186, s12, v84
	v_mov_b32_e32 v187, 0
	v_lshl_add_u64 v[186:187], s[10:11], 0, v[186:187]
	global_load_dwordx4 v[186:189], v[186:187], off offset:3072 nt
	v_or_b32_e32 v190, s21, v118
	v_lshlrev_b32_e32 v190, 12, v190
	v_add3_u32 v190, v190, s12, v84
	v_mov_b32_e32 v191, 0
	v_lshl_add_u64 v[190:191], s[10:11], 0, v[190:191]
	global_load_dwordx4 v[190:193], v[190:191], off offset:2048 nt
	v_or_b32_e32 v198, s21, v118
	v_lshlrev_b32_e32 v198, 12, v198
	v_add3_u32 v198, v198, s12, v84
	v_mov_b32_e32 v199, 0
	v_lshl_add_u64 v[198:199], s[10:11], 0, v[198:199]
	global_load_dwordx4 v[198:201], v[198:199], off offset:3072 nt
	v_or_b32_e32 v202, 64, v112
	v_or_b32_e32 v202, s21, v202
	v_lshlrev_b32_e32 v202, 12, v202
	v_add3_u32 v202, v202, s12, v84
	v_mov_b32_e32 v203, 0
	v_lshl_add_u64 v[202:203], s[10:11], 0, v[202:203]
	global_load_dwordx4 v[202:205], v[202:203], off offset:2048 nt
	v_or_b32_e32 v206, 64, v112
	v_or_b32_e32 v206, s21, v206
	v_lshlrev_b32_e32 v206, 12, v206
	v_add3_u32 v206, v206, s12, v84
	v_mov_b32_e32 v207, 0
	v_lshl_add_u64 v[206:207], s[10:11], 0, v[206:207]
	global_load_dwordx4 v[206:209], v[206:207], off offset:3072 nt
	v_add_u32_e32 v210, s21, v120
	v_lshlrev_b32_e32 v210, 12, v210
	v_add3_u32 v210, v210, s12, v84
	v_mov_b32_e32 v211, 0
	v_lshl_add_u64 v[210:211], s[10:11], 0, v[210:211]
	global_load_dwordx4 v[210:213], v[210:211], off offset:2048 nt
	v_add_u32_e32 v214, s21, v120
	v_lshlrev_b32_e32 v214, 12, v214
	v_add3_u32 v214, v214, s12, v84
	v_mov_b32_e32 v215, 0
	v_lshl_add_u64 v[214:215], s[10:11], 0, v[214:215]
	global_load_dwordx4 v[214:217], v[214:215], off offset:3072 nt
	v_or_b32_e32 v218, s21, v113
	v_lshlrev_b32_e32 v218, 12, v218
	v_add3_u32 v218, v218, s14, v86
	v_mov_b32_e32 v219, 0
	v_lshl_add_u64 v[218:219], s[10:11], 0, v[218:219]
	global_load_dwordx4 v[218:221], v[218:219], off
	v_or_b32_e32 v222, s21, v113
	v_lshlrev_b32_e32 v222, 12, v222
	v_add3_u32 v222, v222, s14, v88
	v_mov_b32_e32 v223, 0
	v_lshl_add_u64 v[222:223], s[10:11], 0, v[222:223]
	global_load_dwordx4 v[222:225], v[222:223], off
	v_or_b32_e32 v226, s21, v113
	v_lshlrev_b32_e32 v226, 12, v226
	v_add3_u32 v226, v226, s14, v90
	v_mov_b32_e32 v227, 0
	v_lshl_add_u64 v[226:227], s[10:11], 0, v[226:227]
	global_load_dwordx4 v[226:229], v[226:227], off
	v_or_b32_e32 v230, s21, v113
	v_lshlrev_b32_e32 v230, 12, v230
	v_add3_u32 v230, v230, s14, v92
	v_mov_b32_e32 v231, 0
	v_lshl_add_u64 v[230:231], s[10:11], 0, v[230:231]
	global_load_dwordx4 v[230:233], v[230:231], off
	v_or_b32_e32 v234, s21, v113
	v_lshlrev_b32_e32 v234, 12, v234
	v_add3_u32 v234, v234, s14, v86
	v_mov_b32_e32 v235, 0
	v_lshl_add_u64 v[234:235], s[10:11], 0, v[234:235]
	global_load_dwordx4 v[234:237], v[234:235], off offset:256
	v_or_b32_e32 v238, s21, v113
	v_lshlrev_b32_e32 v238, 12, v238
	v_add3_u32 v238, v238, s14, v94
	v_mov_b32_e32 v239, 0
	v_lshl_add_u64 v[238:239], s[10:11], 0, v[238:239]
	global_load_dwordx4 v[238:241], v[238:239], off
	v_or_b32_e32 v242, s21, v113
	v_lshlrev_b32_e32 v242, 12, v242
	v_add3_u32 v242, v242, s14, v86
	v_mov_b32_e32 v243, 0
	v_lshl_add_u64 v[242:243], s[10:11], 0, v[242:243]
	global_load_dwordx4 v[242:245], v[242:243], off offset:384
	v_or_b32_e32 v246, s21, v113
	v_lshlrev_b32_e32 v246, 12, v246
	v_add3_u32 v246, v246, s14, v96
	v_mov_b32_e32 v247, 0
	v_lshl_add_u64 v[246:247], s[10:11], 0, v[246:247]
	global_load_dwordx4 v[246:249], v[246:247], off
	v_and_b32_e32 v3, 64, v155
	v_cmp_lt_i32_e32 vcc, v5, v3
	v_add_u32_e32 v7, -2, v155
	v_readlane_b32 s0, v252, 12
	v_cndmask_b32_e32 v5, v5, v155, vcc
	v_lshlrev_b32_e32 v5, 2, v5
	v_cmp_lt_i32_e32 vcc, v7, v3
	v_readlane_b32 s1, v252, 13
	s_waitcnt vmcnt(17)
	v_mul_f32_e32 v4, 0x3fb8aa3b, v4
	v_exp_f32_e32 v4, v4
	v_cndmask_b32_e32 v7, v7, v155, vcc
	v_lshlrev_b32_e32 v7, 2, v7
	s_waitcnt vmcnt(16)
	v_mul_f32_e64 v6, v2, -v4
	ds_bpermute_b32 v5, v5, v6
	ds_write_b32 v114, v2
	s_waitcnt lgkmcnt(1)
	v_fma_f32 v4, v2, -v4, v5
	v_cndmask_b32_e64 v4, v4, v6, s[0:1]
	ds_bpermute_b32 v5, v7, v4
	v_add_u32_e32 v6, -4, v155
	v_cmp_lt_i32_e32 vcc, v6, v3
	v_readlane_b32 s0, v252, 14
	v_readlane_b32 s1, v252, 15
	v_cndmask_b32_e32 v6, v6, v155, vcc
	s_waitcnt lgkmcnt(0)
	v_add_f32_e32 v5, v4, v5
	v_lshlrev_b32_e32 v6, 2, v6
	v_cndmask_b32_e64 v4, v5, v4, s[0:1]
	ds_bpermute_b32 v5, v6, v4
	v_add_u32_e32 v6, -8, v155
	v_cmp_lt_i32_e32 vcc, v6, v3
	v_readlane_b32 s0, v252, 16
	v_readlane_b32 s1, v252, 17
	v_cndmask_b32_e32 v6, v6, v155, vcc
	s_waitcnt lgkmcnt(0)
	v_add_f32_e32 v5, v4, v5
	v_lshlrev_b32_e32 v6, 2, v6
	v_cndmask_b32_e64 v4, v5, v4, s[0:1]
	ds_bpermute_b32 v5, v6, v4
	v_add_u32_e32 v6, -16, v155
	v_cmp_lt_i32_e32 vcc, v6, v3
	v_readlane_b32 s0, v252, 18
	v_readlane_b32 s1, v252, 19
	v_cndmask_b32_e32 v6, v6, v155, vcc
	s_waitcnt lgkmcnt(0)
	v_add_f32_e32 v5, v4, v5
	v_lshlrev_b32_e32 v6, 2, v6
	v_cndmask_b32_e64 v4, v5, v4, s[0:1]
	ds_bpermute_b32 v5, v6, v4
	v_subrev_u32_e32 v6, 32, v155
	v_cmp_lt_i32_e32 vcc, v6, v3
	v_readlane_b32 s0, v252, 20
	v_readlane_b32 s1, v252, 21
	v_cndmask_b32_e32 v3, v6, v155, vcc
	s_waitcnt lgkmcnt(0)
	v_add_f32_e32 v5, v4, v5
	v_lshlrev_b32_e32 v3, 2, v3
	v_cndmask_b32_e64 v4, v5, v4, s[0:1]
	ds_bpermute_b32 v3, v3, v4
	v_readfirstlane_b32 vcc_lo, v172
	s_waitcnt lgkmcnt(0)
	v_add_f32_e32 v2, v4, v3
	v_cndmask_b32_e64 v2, v2, v4, s[16:17]
	ds_write_b32 v115, v2
	s_waitcnt lgkmcnt(0)
	s_barrier
	s_and_saveexec_b64 s[0:1], s[18:19]
	s_cbranch_execz .LBB0_527
	ds_read_b32 v3, v116 offset:252
	s_waitcnt lgkmcnt(0)
	v_add_f32_e32 v2, v2, v3

; __device__ __forceinline__ void ssd_s3_unit(const Params& p, int unit, unsigned char* ldsb) {
;     ...
;     const int lrow = wave * 16 + l15;
;     for (int hh = 0; hh < 4; ++hh) {
;         const int h = g * 4 + hh;
;         const bfu* XT = XT4 + hh * 64 * 136;
;         const float csl = csb[hh * 128 + lrow];
;         f32x4 acc[4];
; #pragma unroll
;         for (int mt = 0; mt < 4; ++mt) acc[mt] = (f32x4){0.f, 0.f, 0.f, 0.f};
;         const bfu* hp = (const bfu*)(p.ws + WS_HPREV) + ((size_t)((b * 32 + c) * 16 + h) * 64) * 128;
;         bf16x8 hf[16];
; #pragma unroll
;         for (int i = 0; i < 16; ++i) hf[i] = ld8g(hp + (size_t)((i & 3) * 16 + l15) * 128 + (i >> 2) * 32 + quad * 8);
;         __builtin_amdgcn_sched_barrier(0);
.LBB0_541:
	s_lshr_b32 s8, s87, 2
	s_and_b32 s8, s8, 31
	s_lshl_b32 s9, s8, 4
	s_and_b32 s20, s86, 3
	s_lshl_b32 s6, s6, 9
	s_load_dwordx2 s[90:91], s[90:91], 0x58
	s_lshl_b32 s96, s20, 2
	s_lshl_b32 s11, s8, 7
	s_lshl_b32 s8, s20, 8
	s_or_b32 s6, s6, s9
	v_or_b32_e32 v32, s8, v180
	v_or_b32_e32 v35, s8, v64
	v_or_b32_e32 v36, s8, v60
	v_or_b32_e32 v37, s8, v56
	s_or_b32 s8, s6, s96
	s_ashr_i32 s9, s8, 31
	s_lshl_b32 s10, s20, 4
	s_lshl_b64 s[8:9], s[8:9], 14
	v_lshlrev_b32_e32 v34, 1, v32
	v_lshl_or_b32 v32, v174, 8, v176
	s_waitcnt lgkmcnt(0)
	s_add_u32 s96, s90, s10
	v_or_b32_e32 v98, s8, v32
	s_addc_u32 s6, s91, 0
	s_add_i32 s8, vcc_hi, s11
	s_add_i32 s8, s8, s7
	v_add_u32_e32 v32, s8, v174
	v_ashrrev_i32_e32 v33, 31, v32
	s_movk_i32 s7, 0x3000
	v_mov_b32_e32 v99, s9
	v_lshlrev_b64 v[100:101], 11, v[32:33]
	s_andn2_b32 vcc_lo, vcc_lo, 63
	v_mad_i64_i32 v[102:103], s[8:9], v32, s7, 0
	v_lshlrev_b64 v[110:111], 12, v[32:33]
	v_cmp_gt_u32_e64 s[20:21], v180, v48
	v_cmp_lt_u32_e64 s[22:23], v180, v48
	v_cmp_gt_u32_e64 s[24:25], v55, v48
	v_cmp_gt_u32_e64 s[26:27], v54, v48
	v_cmp_gt_u32_e64 s[28:29], v57, v48
	v_cmp_gt_u32_e64 s[30:31], v56, v48
	v_cmp_gt_u32_e64 s[34:35], v59, v48
	v_cmp_gt_u32_e64 s[36:37], v58, v48
	v_cmp_gt_u32_e64 s[38:39], v61, v48
	v_cmp_gt_u32_e64 s[40:41], v60, v48
	v_cmp_gt_u32_e64 s[42:43], v63, v48
	v_cmp_gt_u32_e64 s[44:45], v62, v48
	v_cmp_gt_u32_e64 s[46:47], v65, v48
	v_cmp_gt_u32_e64 s[48:49], v64, v48
	v_cmp_gt_u32_e64 s[50:51], v67, v48
	v_cmp_gt_u32_e64 s[52:53], v66, v48
	v_cmp_gt_u32_e64 s[54:55], v69, v48
	v_cmp_gt_u32_e64 s[56:57], v68, v48
	v_cmp_gt_u32_e64 s[58:59], v71, v48
	v_cmp_gt_u32_e64 s[60:61], v70, v48
	v_cmp_gt_u32_e64 s[62:63], v73, v48
	v_cmp_gt_u32_e64 s[64:65], v72, v48
	v_cmp_gt_u32_e64 s[66:67], v75, v48
	v_cmp_gt_u32_e64 s[68:69], v74, v48
	v_cmp_gt_u32_e64 s[70:71], v77, v48
	v_cmp_gt_u32_e64 s[72:73], v76, v48
	v_cmp_gt_u32_e64 s[74:75], v79, v48
	v_cmp_gt_u32_e64 s[76:77], v78, v48
	v_cmp_gt_u32_e64 s[78:79], v81, v48
	v_cmp_gt_u32_e64 s[80:81], v80, v48
	v_cmp_gt_u32_e64 s[82:83], v83, v48
	v_cmp_gt_u32_e64 s[84:85], v82, v48
	v_or_b32_e32 v100, v100, v34
	v_add_u32_e32 v87, vcc_lo, v154
	v_lshl_or_b32 v104, v35, 1, v102
	v_mov_b32_e32 v105, v103
	v_lshl_or_b32 v106, v36, 1, v102
	v_mov_b32_e32 v107, v103
	v_lshl_or_b32 v108, v37, 1, v102
	v_mov_b32_e32 v109, v103
	v_or_b32_e32 v110, v110, v34
	v_or_b32_e32 v102, v102, v34
	s_mov_b64 s[90:91], 0
	v_mov_b32_e32 v89, v176
	v_mov_b32_e32 v91, v153
	v_mov_b32_e32 v93, v152
	v_mov_b32_e32 v95, v151
	v_mov_b32_e32 v97, v150
	v_mov_b32_e32 v163, v149
	v_mov_b32_e32 v164, v148
	v_mov_b32_e32 v165, v147
	v_mov_b32_e32 v166, v146
	v_mov_b32_e32 v167, v145
	v_mov_b32_e32 v168, v144
	v_mov_b32_e32 v169, v143
	v_mov_b32_e32 v170, v142
	v_mov_b32_e32 v171, v141
	v_mov_b32_e32 v178, v140
	v_mov_b32_e32 v181, v139
	v_mov_b32_e32 v182, v138
	v_mov_b32_e32 v183, v137
	v_mov_b32_e32 v184, v136
	v_mov_b32_e32 v185, v135
	v_mov_b32_e32 v186, v134
	v_mov_b32_e32 v187, v133
	v_mov_b32_e32 v188, v132
	v_mov_b32_e32 v189, v131
	v_mov_b32_e32 v190, v130
	v_mov_b32_e32 v191, v129
	v_mov_b32_e32 v192, v128
	v_mov_b32_e32 v193, v127
	v_mov_b32_e32 v197, v126
	v_mov_b32_e32 v198, v125
	v_mov_b32_e32 v199, v124
	v_mov_b32_e32 v200, v123
	v_mov_b32_e32 v201, v122
	v_add_u32_e32 v202, 0x12100, v122
	s_barrier
	s_lshr_b32 s10, vcc_lo, 7
	s_lshl_b32 s10, s10, 12
	s_and_b32 s11, vcc_lo, 64
	s_lshl_b32 s11, s11, 1
	s_add_i32 s10, s10, s11
	s_add_i32 s10, s10, 0x20a00000
	s_mov_b32 s11, 0
	s_lshl_b32 s32, vcc_lo, 5
	v_lshl_add_u64 v[254:255], s[88:89], 0, v[98:99]
	v_mbcnt_lo_u32_b32 v253, -1, 0
	v_lshl_add_u64 v[254:255], v[254:255], 0, s[10:11]
	v_mbcnt_hi_u32_b32 v253, -1, v253
	v_lshlrev_b32_e32 v253, 4, v253
	v_add_u32_e32 v253, 0x8800, v253
	s_add_i32 s10, s32, 0x8800
	s_mov_b32 m0, s10
	s_nop 0
	global_load_lds_dwordx4 v[254:255], off nt
	s_add_i32 s10, s10, 0x3c0
	s_mov_b32 m0, s10
	s_nop 0
	global_load_lds_dwordx4 v[254:255], off offset:64 nt
	s_xor_b32 s32, s32, 0x4000
	s_mov_b64 s[10:11], 0x4000
	v_lshl_add_u64 v[254:255], v[254:255], 0, s[10:11]
	s_waitcnt vmcnt(0)
	s_branch .LBB0_543

; __device__ __forceinline__ unsigned pk2(float lo, float hi) { f32x2_t v = {lo, hi}; bf16x2_t b = __builtin_convertvector(v, bf16x2_t); return __builtin_bit_cast(unsigned, b); }
; __device__ __forceinline__ void ssd_s3_unit(const Params& p, int unit, unsigned char* ldsb) {
;     ...
;     for (int hh = 0; hh < 4; ++hh) {
;         const int h = g * 4 + hh;
;         const bfu* XT = XT4 + hh * 64 * 136;
;         const float csl = csb[hh * 128 + lrow];
;         f32x4 acc[4];
; #pragma unroll
;         for (int mt = 0; mt < 4; ++mt) acc[mt] = (f32x4){0.f, 0.f, 0.f, 0.f};
;         const bfu* hp = (const bfu*)(p.ws + WS_HPREV) + ((size_t)((b * 32 + c) * 16 + h) * 64) * 128;
;         bf16x8 hf[16];
; #pragma unroll
;         for (int i = 0; i < 16; ++i) hf[i] = ld8g(hp + (size_t)((i & 3) * 16 + l15) * 128 + (i >> 2) * 32 + quad * 8);
;         __builtin_amdgcn_sched_barrier(0);
; #pragma unroll
;         for (int ks = 0; ks < 4; ++ks) {
;             const bf16x8 bfr = *(const bf16x8*)(Cs + lrow * 136 + ks * 32 + quad * 8);
; #pragma unroll
;             for (int mt = 0; mt < 4; ++mt) acc[mt] = MFMA16(hf[ks * 4 + mt], bfr, acc[mt]);
;         }
;         const float el = __expf(csl);
; #pragma unroll
;         for (int mt = 0; mt < 4; ++mt) { acc[mt][0] *= el; acc[mt][1] *= el; acc[mt][2] *= el; acc[mt][3] *= el; }
; #pragma unroll
;         for (int kk = 0; kk < 4; ++kk) {
;             if (2 * kk <= wave) {
;                 float mv[8];
; #pragma unroll
;                 for (int j = 0; j < 8; ++j) {
;                     const int tile = 2 * kk + (j >> 2), s = tile * 16 + quad * 4 + (j & 3);
;                     const float cbv = cbt[tile][j & 3];
;                     const float e = __expf(csl - csb[hh * 128 + s]) * dtb[hh * 128 + s];
;                     mv[j] = (s <= lrow) ? cbv * e : 0.f;
;                 }
;                 uint4 pu; pu.x = pk2(mv[0], mv[1]); pu.y = pk2(mv[2], mv[3]); pu.z = pk2(mv[4], mv[5]); pu.w = pk2(mv[6], mv[7]);
;                 const bf16x8 pf = __builtin_bit_cast(bf16x8, pu);
; #pragma unroll
;                 for (int mt = 0; mt < 4; ++mt) {
;                     const bfu* xp = XT + (mt * 16 + l15) * 136 + 32 * kk + quad * 4;
;                     acc[mt] = MFMA16(mk8(*(const uint2*)xp, *(const uint2*)(xp + 16)), pf, acc[mt]);
;                 }
;             }
;         }
.LBB0_543:
	s_barrier
	v_add_u32_e32 v52, 0, v87
	ds_read_b32 v203, v52
	v_add_u32_e32 v52, v85, v176
	ds_read_b128 v[248:251], v52
	s_andn2_b64 vcc, exec, s[0:1]
	ds_read_b128 v[32:35], v253
	ds_read_b128 v[36:39], v253 offset:4096
	ds_read_b128 v[224:227], v253 offset:8192
	ds_read_b128 v[40:43], v253 offset:12288
	ds_read_b128 v[44:47], v253 offset:13312
	ds_read_b128 v[48:51], v253 offset:1024
	ds_read_b128 v[208:211], v253 offset:5120
	ds_read_b128 v[216:219], v253 offset:9216
	ds_read_b128 v[212:215], v253 offset:6144
	ds_read_b128 v[232:235], v253 offset:10240
	ds_read_b128 v[204:207], v253 offset:2048
	ds_read_b128 v[240:243], v253 offset:14336
	s_waitcnt lgkmcnt(11)
	v_mfma_f32_16x16x32_bf16 v[32:35], v[32:35], v[248:251], 0
	s_waitcnt lgkmcnt(10)
	v_mfma_f32_16x16x32_bf16 v[36:39], v[36:39], v[248:251], 0
	s_waitcnt lgkmcnt(9)
	v_mfma_f32_16x16x32_bf16 v[224:227], v[224:227], v[248:251], 0
	s_waitcnt lgkmcnt(8)
	v_mfma_f32_16x16x32_bf16 v[40:43], v[40:43], v[248:251], 0
	ds_read_b128 v[248:251], v52 offset:64
	ds_read_b128 v[228:231], v253 offset:7168
	ds_read_b128 v[236:239], v253 offset:11264
	ds_read_b128 v[220:223], v253 offset:3072
	ds_read_b128 v[244:247], v253 offset:15360
	s_waitcnt lgkmcnt(4)
	v_mfma_f32_16x16x32_bf16 v[40:43], v[44:47], v[248:251], v[40:43]
	ds_read_b128 v[44:47], v52 offset:128
	s_waitcnt lgkmcnt(12)
	v_mfma_f32_16x16x32_bf16 v[32:35], v[48:51], v[248:251], v[32:35]
	s_waitcnt lgkmcnt(11)
	v_mfma_f32_16x16x32_bf16 v[36:39], v[208:211], v[248:251], v[36:39]
	ds_read_b128 v[208:211], v52 offset:192
	s_waitcnt lgkmcnt(11)
	v_mfma_f32_16x16x32_bf16 v[48:51], v[216:219], v[248:251], v[224:227]
	s_waitcnt lgkmcnt(1)
	v_mfma_f32_16x16x32_bf16 v[36:39], v[212:215], v[44:47], v[36:39]
	s_waitcnt lgkmcnt(9)
	v_mfma_f32_16x16x32_bf16 v[48:51], v[232:235], v[44:47], v[48:51]
	s_waitcnt lgkmcnt(8)
	v_mfma_f32_16x16x32_bf16 v[32:35], v[204:207], v[44:47], v[32:35]
	s_waitcnt lgkmcnt(7)
	v_mfma_f32_16x16x32_bf16 v[204:207], v[240:243], v[44:47], v[40:43]
	s_waitcnt lgkmcnt(0)
	v_mfma_f32_16x16x32_bf16 v[40:43], v[228:231], v[208:211], v[36:39]
	s_waitcnt lgkmcnt(4)
	v_mfma_f32_16x16x32_bf16 v[36:39], v[236:239], v[208:211], v[48:51]
	s_nop 2
	v_mul_f32_e32 v48, 0x3fb8aa3b, v203
	v_add_u32_e32 v50, 0, v89
	v_exp_f32_e32 v52, v48
	v_add_u32_e32 v48, 0x22000, v50
	ds_read_b64 v[48:49], v48
	v_add_u32_e32 v50, 0x22800, v50
	ds_read_b64 v[50:51], v50
	s_waitcnt lgkmcnt(5)
	v_mfma_f32_16x16x32_bf16 v[44:47], v[220:223], v[208:211], v[32:35]
	v_mul_f32_e64 v42, v52, v42
	v_mul_f32_e64 v43, v52, v43
	s_waitcnt lgkmcnt(1)
	v_sub_f32_e32 v48, v203, v48
	v_mul_f32_e32 v48, 0x3fb8aa3b, v48
	v_exp_f32_e32 v48, v48
	v_mfma_f32_16x16x32_bf16 v[32:35], v[244:247], v[208:211], v[204:207]
	s_add_i32 s10, s32, 0x8800
	s_mov_b32 m0, s10
	s_nop 0
	global_load_lds_dwordx4 v[254:255], off nt
	s_add_i32 s10, s10, 0x3c0
	s_mov_b32 m0, s10
	s_nop 0
	global_load_lds_dwordx4 v[254:255], off offset:64 nt
	s_xor_b32 s32, s32, 0x4000
	s_mov_b64 s[98:99], 0x16800000
	s_mov_b64 s[100:101], 0x4301000
	v_lshl_add_u64 v[214:215], s[88:89], 0, v[110:111]
	v_lshl_add_u64 v[216:217], s[88:89], 0, v[102:103]
	v_lshl_add_u64 v[218:219], s[88:89], 0, v[108:109]
	v_lshl_add_u64 v[220:221], s[88:89], 0, v[106:107]
	v_lshl_add_u64 v[222:223], s[88:89], 0, v[104:105]
	v_lshl_add_u64 v[214:215], v[214:215], 0, s[98:99]
	v_lshl_add_u64 v[216:217], v[216:217], 0, s[100:101]
	v_lshl_add_u64 v[218:219], v[218:219], 0, s[100:101]
	v_lshl_add_u64 v[220:221], v[220:221], 0, s[100:101]
	v_lshl_add_u64 v[222:223], v[222:223], 0, s[100:101]
	s_add_u32 s10, s96, s90
	s_addc_u32 s11, s6, s91
	global_load_dwordx2 v[224:225], v[214:215], off
	global_load_dwordx2 v[226:227], v[216:217], off offset:2048
	global_load_dword v240, v53, s[10:11]
	global_load_dwordx2 v[228:229], v[214:215], off offset:32
	global_load_dwordx2 v[230:231], v[218:219], off offset:2048
	global_load_dwordx2 v[232:233], v[214:215], off offset:64
	global_load_dwordx2 v[234:235], v[220:221], off offset:2048
	global_load_dwordx2 v[236:237], v[214:215], off offset:96
	global_load_dwordx2 v[238:239], v[222:223], off offset:2048
	v_mul_f32_e64 v46, v52, v46
	v_mul_f32_e64 v47, v52, v47
	v_pk_mul_f32 v[44:45], v[52:53], v[44:45] op_sel_hi:[0,1]
	s_waitcnt lgkmcnt(0)
	v_mul_f32_e32 v48, v50, v48
	v_mul_f32_e32 v48, v0, v48
	v_cndmask_b32_e64 v208, v48, 0, s[20:21]
	v_sub_f32_e32 v48, v203, v49
	v_mul_f32_e32 v48, 0x3fb8aa3b, v48
	v_exp_f32_e32 v48, v48
	v_add_u32_e32 v49, 0, v91
	v_add_u32_e32 v50, 0x22800, v49
	v_pk_mul_f32 v[40:41], v[52:53], v[40:41] op_sel_hi:[0,1]
	v_mul_f32_e32 v48, v51, v48
	v_mul_f32_e32 v48, v1, v48
	v_cndmask_b32_e64 v209, 0, v48, s[22:23]
	v_add_u32_e32 v48, 0x22000, v49
	v_add_u32_e32 v49, 0, v182
	ds_read_b32 v48, v48
	ds_read_b32 v49, v49
	ds_read_b64 v[50:51], v50
	v_pk_mul_f32 v[38:39], v[52:53], v[38:39] op_sel_hi:[0,1]
	v_pk_mul_f32 v[36:37], v[52:53], v[36:37] op_sel_hi:[0,1]
	s_waitcnt lgkmcnt(2)
	v_sub_f32_e32 v48, v203, v48
	s_waitcnt lgkmcnt(1)
	v_sub_f32_e32 v49, v203, v49
	v_mul_f32_e32 v48, 0x3fb8aa3b, v48
	v_mul_f32_e32 v49, 0x3fb8aa3b, v49
	v_exp_f32_e32 v48, v48
	v_exp_f32_e32 v49, v49
	v_pk_mul_f32 v[34:35], v[52:53], v[34:35] op_sel_hi:[0,1]
	v_pk_mul_f32 v[32:33], v[52:53], v[32:33] op_sel_hi:[0,1]
	s_waitcnt lgkmcnt(0)
	v_pk_mul_f32 v[48:49], v[50:51], v[48:49]
	s_nop 0
	v_pk_mul_f32 v[50:51], v[2:3], v[48:49]
	v_add_u32_e32 v49, 0, v93
	v_add_u32_e32 v48, 0x22000, v49
	v_add_u32_e32 v204, 0x22800, v49
	v_add_u32_e32 v49, 0, v183
	ds_read_b32 v48, v48
	ds_read_b32 v49, v49
	ds_read_b64 v[204:205], v204
	s_waitcnt lgkmcnt(2)
	v_sub_f32_e32 v48, v203, v48
	s_waitcnt lgkmcnt(1)
; __device__ __forceinline__ unsigned pk2(float lo, float hi) { f32x2_t v = {lo, hi}; bf16x2_t b = __builtin_convertvector(v, bf16x2_t); return __builtin_bit_cast(unsigned, b); }
; #define MFMA16(a, b, c) __builtin_amdgcn_mfma_f32_16x16x32_bf16((a), (b), (c), 0, 0, 0)
; __device__ __forceinline__ void ssd_s3_unit(const Params& p, int unit, unsigned char* ldsb) {
;     ...
; #pragma unroll
;         for (int kk = 0; kk < 4; ++kk) {
;             if (2 * kk <= wave) {
;                 float mv[8];
; #pragma unroll
;                 for (int j = 0; j < 8; ++j) {
;                     const int tile = 2 * kk + (j >> 2), s = tile * 16 + quad * 4 + (j & 3);
;                     const float cbv = cbt[tile][j & 3];
;                     const float e = __expf(csl - csb[hh * 128 + s]) * dtb[hh * 128 + s];
;                     mv[j] = (s <= lrow) ? cbv * e : 0.f;
;                 }
;                 uint4 pu; pu.x = pk2(mv[0], mv[1]); pu.y = pk2(mv[2], mv[3]); pu.z = pk2(mv[4], mv[5]); pu.w = pk2(mv[6], mv[7]);
;                 const bf16x8 pf = __builtin_bit_cast(bf16x8, pu);
; #pragma unroll
;                 for (int mt = 0; mt < 4; ++mt) {
;                     const bfu* xp = XT + (mt * 16 + l15) * 136 + 32 * kk + quad * 4;
;                     acc[mt] = MFMA16(mk8(*(const uint2*)xp, *(const uint2*)(xp + 16)), pf, acc[mt]);
;                 }
	v_sub_f32_e32 v49, v203, v49
	v_mul_f32_e32 v48, 0x3fb8aa3b, v48
	v_mul_f32_e32 v49, 0x3fb8aa3b, v49
	v_exp_f32_e32 v48, v48
	v_exp_f32_e32 v49, v49
	s_waitcnt lgkmcnt(0)
	v_pk_mul_f32 v[48:49], v[204:205], v[48:49]
	s_nop 0
	v_pk_mul_f32 v[204:205], v[8:9], v[48:49]
	v_add_u32_e32 v49, 0, v95
	v_add_u32_e32 v48, 0x22000, v49
	v_add_u32_e32 v206, 0x22800, v49
	v_add_u32_e32 v49, 0, v184
	ds_read_b32 v48, v48
	ds_read_b32 v49, v49
	ds_read_b64 v[206:207], v206
	s_waitcnt lgkmcnt(2)
	v_sub_f32_e32 v48, v203, v48
	s_waitcnt lgkmcnt(1)
	v_sub_f32_e32 v49, v203, v49
	v_mul_f32_e32 v48, 0x3fb8aa3b, v48
	v_mul_f32_e32 v49, 0x3fb8aa3b, v49
	v_exp_f32_e32 v48, v48
	v_exp_f32_e32 v49, v49
	s_waitcnt lgkmcnt(0)
	v_pk_mul_f32 v[48:49], v[206:207], v[48:49]
	s_nop 0
	v_pk_mul_f32 v[206:207], v[10:11], v[48:49]
	v_cvt_pk_bf16_f32 v49, v50, v51
	v_cndmask_b32_e64 v50, v49, 0, s[26:27]
	v_lshrrev_b32_e32 v49, 16, v49
	v_cndmask_b32_e64 v49, v49, 0, s[24:25]
	v_perm_b32 v49, v49, v50, s33
	v_cvt_pk_bf16_f32 v50, v204, v205
	v_cndmask_b32_e64 v51, v50, 0, s[30:31]
	v_lshrrev_b32_e32 v50, 16, v50
	v_cndmask_b32_e64 v50, v50, 0, s[28:29]
	v_perm_b32 v50, v50, v51, s33
	v_cvt_pk_bf16_f32 v51, v206, v207
	v_cndmask_b32_e64 v204, v51, 0, s[36:37]
	v_lshrrev_b32_e32 v51, 16, v51
	v_cndmask_b32_e64 v51, v51, 0, s[34:35]
	v_perm_b32 v51, v51, v204, s33
	v_add_u32_e32 v204, 0, v200
	v_add_u32_e32 v205, 0x11000, v204
	ds_read_b64 v[206:207], v205
	v_add_u32_e32 v205, 0x11020, v204
	v_cvt_pk_bf16_f32 v48, v208, v209
	ds_read_b64 v[208:209], v205
	v_add_u32_e32 v205, 0, v201
	s_waitcnt lgkmcnt(0)
	v_mfma_f32_16x16x32_bf16 v[44:47], v[206:209], v[48:51], v[44:47]
	v_add_u32_e32 v206, 0x11000, v205
	v_add_u32_e32 v208, 0x11020, v205
	ds_read_b64 v[206:207], v206
	ds_read_b64 v[208:209], v208
	s_waitcnt lgkmcnt(0)
	v_mfma_f32_16x16x32_bf16 v[40:43], v[206:209], v[48:51], v[40:43]
	v_add_u32_e32 v206, 0, v202
	ds_read2_b64 v[208:211], v206 offset1:4
	v_add_u32_e32 v207, 0x1000, v206
	s_waitcnt lgkmcnt(0)
	v_mfma_f32_16x16x32_bf16 v[36:39], v[208:211], v[48:51], v[36:39]
	ds_read2_b64 v[208:211], v207 offset0:32 offset1:36
	s_waitcnt lgkmcnt(0)
	v_mfma_f32_16x16x32_bf16 v[32:35], v[208:211], v[48:51], v[32:35]
	s_cbranch_vccnz .LBB0_546
	v_add_u32_e32 v49, 0, v97
	v_add_u32_e32 v48, 0x22000, v49
	v_add_u32_e32 v50, 0x22800, v49
	v_add_u32_e32 v49, 0, v185
	ds_read_b32 v48, v48
	ds_read_b32 v49, v49
	ds_read_b64 v[50:51], v50
	s_waitcnt lgkmcnt(2)
	v_sub_f32_e32 v48, v203, v48
	s_waitcnt lgkmcnt(1)
	v_sub_f32_e32 v49, v203, v49
	v_mul_f32_e32 v48, 0x3fb8aa3b, v48
	v_mul_f32_e32 v49, 0x3fb8aa3b, v49
	v_exp_f32_e32 v48, v48
	v_exp_f32_e32 v49, v49
	s_waitcnt lgkmcnt(0)
	v_pk_mul_f32 v[48:49], v[50:51], v[48:49]
	v_add_u32_e32 v51, 0, v163
	v_add_u32_e32 v50, 0x22000, v51
	v_add_u32_e32 v52, 0x22800, v51
	v_add_u32_e32 v51, 0, v186
	ds_read_b32 v50, v50
	ds_read_b32 v51, v51
	ds_read_b64 v[208:209], v52
	v_add_u32_e32 v52, 0, v164
	v_pk_mul_f32 v[48:49], v[12:13], v[48:49]
	s_waitcnt lgkmcnt(2)
	v_sub_f32_e32 v50, v203, v50
	s_waitcnt lgkmcnt(1)
	v_sub_f32_e32 v51, v203, v51
	v_mul_f32_e32 v50, 0x3fb8aa3b, v50
	v_mul_f32_e32 v51, 0x3fb8aa3b, v51
	v_exp_f32_e32 v50, v50
	v_exp_f32_e32 v51, v51
	v_cvt_pk_bf16_f32 v48, v48, v49
	v_cndmask_b32_e64 v49, v48, 0, s[40:41]
	v_lshrrev_b32_e32 v48, 16, v48
	s_waitcnt lgkmcnt(0)
	v_pk_mul_f32 v[50:51], v[208:209], v[50:51]
	v_add_u32_e32 v208, 0x22000, v52
	v_add_u32_e32 v209, 0, v187
	ds_read_b32 v208, v208
	ds_read_b32 v209, v209
	v_add_u32_e32 v52, 0x22800, v52
	ds_read_b64 v[210:211], v52
	v_add_u32_e32 v52, 0, v165
	s_waitcnt lgkmcnt(2)
	v_sub_f32_e32 v208, v203, v208
	s_waitcnt lgkmcnt(1)
	v_sub_f32_e32 v209, v203, v209
	v_mul_f32_e32 v208, 0x3fb8aa3b, v208
	v_mul_f32_e32 v209, 0x3fb8aa3b, v209
	v_exp_f32_e32 v208, v208
	v_exp_f32_e32 v209, v209
	v_pk_mul_f32 v[50:51], v[14:15], v[50:51]
	v_cndmask_b32_e64 v48, v48, 0, s[38:39]
	v_perm_b32 v48, v48, v49, s33
	s_waitcnt lgkmcnt(0)
	v_pk_mul_f32 v[208:209], v[210:211], v[208:209]
	v_add_u32_e32 v210, 0x22000, v52
	v_add_u32_e32 v211, 0, v188
	ds_read_b32 v210, v210
	ds_read_b32 v211, v211
	v_add_u32_e32 v52, 0x22800, v52
	ds_read_b64 v[212:213], v52
	v_cvt_pk_bf16_f32 v49, v50, v51
	s_waitcnt lgkmcnt(2)
	v_sub_f32_e32 v210, v203, v210
	s_waitcnt lgkmcnt(1)
	v_sub_f32_e32 v211, v203, v211
	v_mul_f32_e32 v210, 0x3fb8aa3b, v210
	v_mul_f32_e32 v211, 0x3fb8aa3b, v211
	v_exp_f32_e32 v210, v210
	v_exp_f32_e32 v211, v211
	v_cndmask_b32_e64 v50, v49, 0, s[44:45]
	v_lshrrev_b32_e32 v49, 16, v49
	v_pk_mul_f32 v[208:209], v[4:5], v[208:209]
	v_cndmask_b32_e64 v49, v49, 0, s[42:43]
	v_perm_b32 v49, v49, v50, s33
	v_cvt_pk_bf16_f32 v50, v208, v209
	s_waitcnt lgkmcnt(0)
	v_pk_mul_f32 v[210:211], v[212:213], v[210:211]
	v_cndmask_b32_e64 v51, v50, 0, s[48:49]
	v_lshrrev_b32_e32 v50, 16, v50
	v_pk_mul_f32 v[210:211], v[6:7], v[210:211]
	v_cndmask_b32_e64 v50, v50, 0, s[46:47]
	v_perm_b32 v50, v50, v51, s33
	v_cvt_pk_bf16_f32 v51, v210, v211
	v_cndmask_b32_e64 v52, v51, 0, s[52:53]
	v_lshrrev_b32_e32 v51, 16, v51
	v_cndmask_b32_e64 v51, v51, 0, s[50:51]
	v_perm_b32 v51, v51, v52, s33
	v_add_u32_e32 v52, 0x11040, v204
	ds_read_b64 v[208:209], v52
	v_add_u32_e32 v52, 0x11060, v204
	ds_read_b64 v[210:211], v52
	v_add_u32_e32 v52, 0x11040, v205
	s_waitcnt lgkmcnt(0)
	v_mfma_f32_16x16x32_bf16 v[44:47], v[208:211], v[48:51], v[44:47]
	ds_read_b64 v[208:209], v52
	v_add_u32_e32 v52, 0x11060, v205
	ds_read_b64 v[210:211], v52
	s_waitcnt lgkmcnt(0)
	v_mfma_f32_16x16x32_bf16 v[40:43], v[208:211], v[48:51], v[40:43]
	ds_read2_b64 v[208:211], v206 offset0:8 offset1:12
	s_waitcnt lgkmcnt(0)
	v_mfma_f32_16x16x32_bf16 v[36:39], v[208:211], v[48:51], v[36:39]
	ds_read2_b64 v[208:211], v207 offset0:40 offset1:44
	s_waitcnt lgkmcnt(0)
	v_mfma_f32_16x16x32_bf16 v[32:35], v[208:211], v[48:51], v[32:35]
	s_andn2_b64 vcc, exec, s[94:95]
	s_cbranch_vccz .LBB0_547

; #define PG8_LAS __attribute__((address_space(3)))
;     __device__ __forceinline__ void fused(f32x4 (&acc)[2][2][4][2], const Unit& u, int wr, int wc, int fr, int fq, PG8_LAS unsigned char* lds, int wid, int lane) const {
;     ...
; #pragma unroll
;         for (int ai = 0; ai < 2; ++ai)
; #pragma unroll
;             for (int m = 0; m < 4; ++m) {
;                 const int rl = ai * 128 + wr * 64 + m * 16 + fr;
;                 const size_t roff = (size_t)(u.pm * 256 + rl) * 1024 + u.pn * 256 + wc * 32 + fq * 8;
;                 float s1 = 0.f, s2 = 0.f;
; #pragma unroll
;                 for (int bj = 0; bj < 2; ++bj) {
;                     float x[8];
;                     if (RES_BF16) ld8f((const bfu*)res + roff + bj * 128, x);
;                     else ld8f32((const float*)res + roff + bj * 128, x);
; #pragma unroll
;                     for (int n = 0; n < 2; ++n) {
;                         f32x4 v = acc[ai][bj][m][n];
;                         v[0] += ALPHA * x[4 * n]; v[1] += ALPHA * x[4 * n + 1]; v[2] += ALPHA * x[4 * n + 2]; v[3] += ALPHA * x[4 * n + 3];
;                         acc[ai][bj][m][n] = v;
;                         s1 += (v[0] + v[1]) + (v[2] + v[3]); s2 += (v[0] * v[0] + v[1] * v[1]) + (v[2] * v[2] + v[3] * v[3]);
;                     }
;                 }
;                 s1 += __shfl_xor(s1, 16); s1 += __shfl_xor(s1, 32); s2 += __shfl_xor(s2, 16); s2 += __shfl_xor(s2, 32);
;                 {
;                     PG8_LAS float* pd = (fq == 0) ? P + (rl * 4 + wc) * 2 : (PG8_LAS float*)(lds + 12288) + tid * 2;
;                     pd[0] = s1; pd[1] = s2;
.LBB0_1048:
	s_add_u32 s22, s66, 0x38b00000
	s_addc_u32 s23, s67, 0
	s_lshl_b32 s19, s18, 8
	v_add_u32_e32 v142, s19, v129
	s_lshl_b32 s8, s20, 8
	v_ashrrev_i32_e32 v143, 31, v142
	v_readlane_b32 s28, v252, 8
	s_ashr_i32 s9, s8, 31
	v_lshlrev_b64 v[142:143], 11, v[142:143]
	v_readlane_b32 s29, v252, 9
	s_lshl_b64 s[26:27], s[8:9], 1
	s_mov_b32 s25, 0
	v_lshl_add_u64 v[144:145], s[28:29], 0, v[142:143]
	v_lshl_add_u64 v[144:145], v[144:145], 0, s[26:27]
	s_lshl_b32 s24, s11, 6
	v_lshl_add_u64 v[144:145], v[144:145], 0, s[24:25]
	v_mov_b32_e32 v141, 0
	v_lshl_add_u64 v[144:145], v[144:145], 0, v[140:141]
	s_barrier
	global_load_dwordx4 v[146:149], v[144:145], off nt
	global_load_dwordx4 v[150:153], v[144:145], off offset:256 nt
	s_mov_b64 s[98:99], 0x8000
	v_lshl_add_u64 v[250:251], v[144:145], 0, s[98:99]
	global_load_dwordx4 v[210:213], v[250:251], off nt
	global_load_dwordx4 v[214:217], v[250:251], off offset:256 nt
	s_mov_b64 s[98:99], 0x10000
	v_lshl_add_u64 v[250:251], v[144:145], 0, s[98:99]
	global_load_dwordx4 v[218:221], v[250:251], off nt
	global_load_dwordx4 v[222:225], v[250:251], off offset:256 nt
	s_mov_b64 s[98:99], 0x18000
	v_lshl_add_u64 v[250:251], v[144:145], 0, s[98:99]
	global_load_dwordx4 v[226:229], v[250:251], off nt
	global_load_dwordx4 v[230:233], v[250:251], off offset:256 nt
	s_mov_b64 s[98:99], 0x40000
	v_lshl_add_u64 v[250:251], v[144:145], 0, s[98:99]
	global_load_dwordx4 v[234:237], v[250:251], off nt
	global_load_dwordx4 v[238:241], v[250:251], off offset:256 nt
	s_mov_b64 s[98:99], 0x48000
	v_lshl_add_u64 v[250:251], v[144:145], 0, s[98:99]
	global_load_dwordx4 v[242:245], v[250:251], off nt
	global_load_dwordx4 v[246:249], v[250:251], off offset:256 nt
	v_readlane_b32 s98, v252, 6
	v_readlane_b32 s99, v252, 7
	s_nop 3
	s_and_saveexec_b64 s[100:101], s[98:99]
	s_cbranch_execz .Lpub_skip_p7
	s_lshl_b32 s98, s2, 2
	s_andn2_b32 s98, s98, 63
	s_lshl_b32 s98, s98, 2
	s_add_u32 s98, s3, s98
	s_addc_u32 s99, s33, 0
	v_mov_b32_e32 v253, 0
	v_mov_b32_e32 v254, 1
	global_atomic_add v253, v254, s[98:99]
.Lpub_skip_p7:
	s_mov_b64 exec, s[100:101]
	s_mov_b64 s[98:99], 0x50000
	v_lshl_add_u64 v[250:251], v[144:145], 0, s[98:99]
	v_mbcnt_lo_u32_b32 v144, -1, 0
	v_mbcnt_hi_u32_b32 v154, -1, v144
	v_and_b32_e32 v145, 64, v154
	v_or_b32_e32 v178, 16, v129
	v_xor_b32_e32 v155, 16, v154
	v_add_u32_e32 v157, 64, v145
	v_xor_b32_e32 v156, 32, v154
	v_add_u32_e32 v144, s19, v178
	v_cmp_lt_i32_e32 vcc, v155, v157
	v_ashrrev_i32_e32 v145, 31, v144
	v_lshlrev_b64 v[144:145], 11, v[144:145]
	v_cndmask_b32_e32 v155, v154, v155, vcc
	v_cmp_lt_i32_e32 vcc, v156, v157
	v_lshlrev_b32_e32 v181, 2, v155
	s_mov_b32 s6, 0x3f9837f0
	v_cndmask_b32_e32 v154, v154, v156, vcc
	v_lshlrev_b32_e32 v180, 2, v154
	v_lshl_add_u64 v[154:155], s[28:29], 0, v[144:145]
	v_lshl_add_u64 v[154:155], v[154:155], 0, s[26:27]
	v_lshl_add_u64 v[154:155], v[154:155], 0, s[24:25]
	v_lshl_add_u64 v[158:159], v[154:155], 0, v[140:141]
	s_waitcnt vmcnt(0)
	v_mov_b64_e32 v[154:155], v[210:211]
	v_mov_b64_e32 v[156:157], v[212:213]
	s_nop 0
	v_mov_b64_e32 v[158:159], v[214:215]
	v_mov_b64_e32 v[160:161], v[216:217]
	v_or_b32_e32 v179, 32, v129
	v_lshl_add_u32 v177, v172, 3, 0
	v_cmp_eq_u32_e32 vcc, 0, v176
	s_waitcnt vmcnt(0)
	v_lshlrev_b32_e32 v162, 16, v146
	v_and_b32_e32 v163, 0xffff0000, v146
	v_lshlrev_b32_e32 v164, 16, v147
	v_and_b32_e32 v165, 0xffff0000, v147
	v_lshlrev_b32_e32 v166, 16, v148
	v_and_b32_e32 v167, 0xffff0000, v148
	v_lshlrev_b32_e32 v148, 16, v149
	v_and_b32_e32 v149, 0xffff0000, v149
	v_lshlrev_b32_e32 v168, 16, v150
	v_and_b32_e32 v169, 0xffff0000, v150
	v_lshlrev_b32_e32 v150, 16, v151
	v_and_b32_e32 v151, 0xffff0000, v151
	v_lshlrev_b32_e32 v170, 16, v152
	v_and_b32_e32 v171, 0xffff0000, v152
	v_lshlrev_b32_e32 v152, 16, v153
	v_and_b32_e32 v153, 0xffff0000, v153
	v_pk_fma_f32 v[146:147], v[162:163], s[6:7], v[124:125] op_sel_hi:[1,0,1]
	v_pk_fma_f32 v[124:125], v[164:165], s[6:7], v[126:127] op_sel_hi:[1,0,1]
	v_pk_fma_f32 v[126:127], v[166:167], s[6:7], v[120:121] op_sel_hi:[1,0,1]
	v_pk_fma_f32 v[122:123], v[148:149], s[6:7], v[122:123] op_sel_hi:[1,0,1]
	v_pk_fma_f32 v[120:121], v[168:169], s[6:7], v[116:117] op_sel_hi:[1,0,1]
	v_pk_fma_f32 v[116:117], v[150:151], s[6:7], v[118:119] op_sel_hi:[1,0,1]
	v_pk_fma_f32 v[118:119], v[170:171], s[6:7], v[112:113] op_sel_hi:[1,0,1]
	v_pk_fma_f32 v[112:113], v[152:153], s[6:7], v[114:115] op_sel_hi:[1,0,1]
	v_pk_add_f32 v[114:115], v[146:147], v[146:147] op_sel:[0,1] op_sel_hi:[1,0]
	v_pk_add_f32 v[148:149], v[124:125], v[124:125] op_sel:[0,1] op_sel_hi:[1,0]
	v_pk_mul_f32 v[150:151], v[146:147], v[146:147]
	v_pk_mul_f32 v[152:153], v[124:125], v[124:125]
	v_pk_mul_f32 v[162:163], v[126:127], v[126:127]
	v_mul_f32_e32 v164, v122, v122
	v_mov_b32_e32 v182, v126
	v_mov_b32_e32 v184, v122
	v_pk_fma_f32 v[164:165], v[122:123], v[122:123], v[164:165] op_sel_hi:[1,1,0]
	v_mov_b32_e32 v183, v150
	v_mov_b32_e32 v150, v127
	v_mov_b32_e32 v185, v152
	v_mov_b32_e32 v152, v123
	v_mov_b32_e32 v115, v162
	v_mov_b32_e32 v149, v163
	v_pk_add_f32 v[150:151], v[182:183], v[150:151]
	v_pk_add_f32 v[152:153], v[184:185], v[152:153]
	v_pk_add_f32 v[114:115], v[114:115], v[148:149]
	v_mov_b32_e32 v164, v141
	v_pk_mul_f32 v[166:167], v[120:121], v[120:121]
	v_pk_mul_f32 v[168:169], v[116:117], v[116:117]
	v_pk_add_f32 v[150:151], v[150:151], v[152:153]
	v_pk_add_f32 v[114:115], v[114:115], v[164:165]
	v_mov_b32_e32 v188, v120
	v_mov_b32_e32 v189, v166
	v_mov_b32_e32 v166, v121
	v_pk_add_f32 v[114:115], v[150:151], v[114:115]
	v_mov_b32_e32 v150, v116
	v_mov_b32_e32 v151, v168
	v_mov_b32_e32 v168, v117
	v_pk_add_f32 v[148:149], v[188:189], v[166:167]
	v_pk_add_f32 v[150:151], v[150:151], v[168:169]
	v_pk_mul_f32 v[170:171], v[118:119], v[118:119]
	v_pk_mul_f32 v[174:175], v[112:113], v[112:113]
	v_pk_add_f32 v[148:149], v[148:149], v[150:151]
	v_mov_b32_e32 v150, v112
	v_pk_add_f32 v[114:115], v[114:115], v[148:149]
	v_mov_b32_e32 v148, v118
	v_mov_b32_e32 v149, v170
	v_mov_b32_e32 v170, v119
	v_mov_b32_e32 v151, v174
	v_mov_b32_e32 v174, v113
	v_pk_add_f32 v[148:149], v[148:149], v[170:171]
	v_pk_add_f32 v[150:151], v[150:151], v[174:175]
	s_lshl_b32 s7, s11, 3
	v_pk_add_f32 v[148:149], v[148:149], v[150:151]
	s_add_i32 s7, s7, 0
	v_pk_add_f32 v[114:115], v[114:115], v[148:149]
	ds_bpermute_b32 v148, v181, v114
	ds_bpermute_b32 v149, v181, v115
	v_lshlrev_b32_e32 v168, 16, v156
	v_and_b32_e32 v169, 0xffff0000, v156
	v_lshlrev_b32_e32 v156, 16, v157
	v_and_b32_e32 v157, 0xffff0000, v157
	s_waitcnt lgkmcnt(0)
; #define PG8_LAS __attribute__((address_space(3)))
;     __device__ __forceinline__ void fused(f32x4 (&acc)[2][2][4][2], const Unit& u, int wr, int wc, int fr, int fq, PG8_LAS unsigned char* lds, int wid, int lane) const {
;     ...
;             for (int m = 0; m < 4; ++m) {
;                 const int rl = ai * 128 + wr * 64 + m * 16 + fr;
;                 const size_t roff = (size_t)(u.pm * 256 + rl) * 1024 + u.pn * 256 + wc * 32 + fq * 8;
;                 float s1 = 0.f, s2 = 0.f;
; #pragma unroll
;                 for (int bj = 0; bj < 2; ++bj) {
;                     float x[8];
;                     if (RES_BF16) ld8f((const bfu*)res + roff + bj * 128, x);
;                     else ld8f32((const float*)res + roff + bj * 128, x);
; #pragma unroll
;                     for (int n = 0; n < 2; ++n) {
;                         f32x4 v = acc[ai][bj][m][n];
;                         v[0] += ALPHA * x[4 * n]; v[1] += ALPHA * x[4 * n + 1]; v[2] += ALPHA * x[4 * n + 2]; v[3] += ALPHA * x[4 * n + 3];
;                         acc[ai][bj][m][n] = v;
;                         s1 += (v[0] + v[1]) + (v[2] + v[3]); s2 += (v[0] * v[0] + v[1] * v[1]) + (v[2] * v[2] + v[3] * v[3]);
;                     }
;                 }
;                 s1 += __shfl_xor(s1, 16); s1 += __shfl_xor(s1, 32); s2 += __shfl_xor(s2, 16); s2 += __shfl_xor(s2, 32);
;                 {
;                     PG8_LAS float* pd = (fq == 0) ? P + (rl * 4 + wc) * 2 : (PG8_LAS float*)(lds + 12288) + tid * 2;
;                     pd[0] = s1; pd[1] = s2;
	v_pk_add_f32 v[162:163], v[114:115], v[148:149]
	v_add_u32_e32 v148, s19, v179
	v_ashrrev_i32_e32 v149, 31, v148
	v_lshlrev_b64 v[148:149], 11, v[148:149]
	v_lshl_add_u64 v[150:151], s[28:29], 0, v[148:149]
	v_lshl_add_u64 v[150:151], v[150:151], 0, s[26:27]
	v_lshl_add_u64 v[150:151], v[150:151], 0, s[24:25]
	v_lshl_add_u64 v[166:167], v[150:151], 0, v[140:141]
	v_mov_b64_e32 v[150:151], v[218:219]
	v_mov_b64_e32 v[152:153], v[220:221]
	v_lshlrev_b32_e32 v114, 16, v154
	v_and_b32_e32 v115, 0xffff0000, v154
	v_lshlrev_b32_e32 v154, 16, v155
	v_and_b32_e32 v155, 0xffff0000, v155
	v_pk_fma_f32 v[114:115], v[114:115], s[6:7], v[108:109] op_sel_hi:[1,0,1]
	v_pk_fma_f32 v[108:109], v[154:155], s[6:7], v[110:111] op_sel_hi:[1,0,1]
	v_pk_fma_f32 v[106:107], v[156:157], s[6:7], v[106:107] op_sel_hi:[1,0,1]
	v_mov_b64_e32 v[154:155], v[222:223]
	v_mov_b64_e32 v[156:157], v[224:225]
	global_load_dwordx4 v[210:213], v[250:251], off nt
	global_load_dwordx4 v[214:217], v[250:251], off offset:256 nt
	s_mov_b64 s[98:99], 0x8000
	v_lshl_add_u64 v[250:251], v[250:251], 0, s[98:99]
	global_load_dwordx4 v[218:221], v[250:251], off nt
	global_load_dwordx4 v[222:225], v[250:251], off offset:256 nt
	v_pk_fma_f32 v[110:111], v[168:169], s[6:7], v[104:105] op_sel_hi:[1,0,1]
	v_mul_f32_e32 v104, v106, v106
	v_pk_fma_f32 v[190:191], v[106:107], v[106:107], v[104:105] op_sel_hi:[1,1,0]
	v_lshlrev_b32_e32 v104, 16, v158
	v_and_b32_e32 v105, 0xffff0000, v158
	v_pk_add_f32 v[170:171], v[114:115], v[114:115] op_sel:[0,1] op_sel_hi:[1,0]
	v_pk_add_f32 v[174:175], v[108:109], v[108:109] op_sel:[0,1] op_sel_hi:[1,0]
	v_pk_mul_f32 v[168:169], v[110:111], v[110:111]
	v_lshlrev_b32_e32 v158, 16, v159
	v_and_b32_e32 v159, 0xffff0000, v159
	v_pk_fma_f32 v[100:101], v[104:105], s[6:7], v[100:101] op_sel_hi:[1,0,1]
	v_pk_fma_f32 v[102:103], v[158:159], s[6:7], v[102:103] op_sel_hi:[1,0,1]
	v_pk_mul_f32 v[158:159], v[100:101], v[100:101]
	v_mov_b32_e32 v171, v168
	v_mov_b32_e32 v175, v169
	v_pk_mul_f32 v[184:185], v[114:115], v[114:115]
	v_lshlrev_b32_e32 v192, 16, v160
	v_and_b32_e32 v193, 0xffff0000, v160
	v_pk_mul_f32 v[166:167], v[102:103], v[102:103]
	v_pk_add_f32 v[168:169], v[170:171], v[174:175]
	v_mov_b32_e32 v170, v100
	v_mov_b32_e32 v171, v158
	v_mov_b32_e32 v158, v101
	v_pk_mul_f32 v[188:189], v[108:109], v[108:109]
	v_lshlrev_b32_e32 v160, 16, v161
	v_and_b32_e32 v161, 0xffff0000, v161
	v_pk_fma_f32 v[104:105], v[192:193], s[6:7], v[96:97] op_sel_hi:[1,0,1]
	v_mov_b32_e32 v192, v110
	v_mov_b32_e32 v193, v184
	v_mov_b32_e32 v184, v111
	v_pk_add_f32 v[158:159], v[170:171], v[158:159]
	v_mov_b32_e32 v170, v102
	v_mov_b32_e32 v171, v166
	v_mov_b32_e32 v166, v103
	v_pk_fma_f32 v[96:97], v[160:161], s[6:7], v[98:99] op_sel_hi:[1,0,1]
	v_pk_mul_f32 v[98:99], v[104:105], v[104:105]
	v_pk_add_f32 v[184:185], v[192:193], v[184:185]
	v_mov_b32_e32 v192, v106
	v_mov_b32_e32 v193, v188
	v_mov_b32_e32 v188, v107
	v_pk_add_f32 v[166:167], v[170:171], v[166:167]
	v_pk_mul_f32 v[160:161], v[96:97], v[96:97]
	v_pk_add_f32 v[188:189], v[192:193], v[188:189]
	v_mov_b32_e32 v190, v141
	v_pk_add_f32 v[158:159], v[158:159], v[166:167]
	v_mov_b32_e32 v166, v104
	v_mov_b32_e32 v167, v98
	v_mov_b32_e32 v98, v105
	v_pk_add_f32 v[184:185], v[184:185], v[188:189]
	v_pk_add_f32 v[168:169], v[168:169], v[190:191]
	v_pk_add_f32 v[98:99], v[166:167], v[98:99]
	v_mov_b32_e32 v166, v96
	v_mov_b32_e32 v167, v160
	v_mov_b32_e32 v160, v97
	v_pk_add_f32 v[168:169], v[184:185], v[168:169]
	v_pk_add_f32 v[160:161], v[166:167], v[160:161]
	v_pk_add_f32 v[158:159], v[168:169], v[158:159]
	v_pk_add_f32 v[98:99], v[98:99], v[160:161]
	ds_bpermute_b32 v164, v180, v162
	v_pk_add_f32 v[98:99], v[158:159], v[98:99]
	ds_bpermute_b32 v165, v180, v163
	ds_bpermute_b32 v158, v181, v98
	ds_bpermute_b32 v159, v181, v99
	v_or_b32_e32 v182, 48, v129
	v_add_u32_e32 v183, 0x3000, v177
	s_waitcnt lgkmcnt(2)
	v_pk_add_f32 v[162:163], v[162:163], v[164:165]
	v_lshl_add_u32 v160, v129, 5, s7
	s_waitcnt lgkmcnt(0)
	v_pk_add_f32 v[164:165], v[98:99], v[158:159]
	v_add_u32_e32 v98, s19, v182
	v_ashrrev_i32_e32 v99, 31, v98
	v_lshlrev_b64 v[98:99], 11, v[98:99]
	v_lshl_add_u64 v[158:159], s[28:29], 0, v[98:99]
	v_lshl_add_u64 v[158:159], v[158:159], 0, s[26:27]
	v_lshl_add_u64 v[158:159], v[158:159], 0, s[24:25]
	v_lshl_add_u64 v[170:171], v[158:159], 0, v[140:141]
	v_cndmask_b32_e32 v200, v183, v160, vcc
	v_mov_b64_e32 v[158:159], v[226:227]
	v_mov_b64_e32 v[160:161], v[228:229]
	v_lshlrev_b32_e32 v184, 16, v152
	v_and_b32_e32 v185, 0xffff0000, v152
	v_lshlrev_b32_e32 v152, 16, v153
	v_and_b32_e32 v153, 0xffff0000, v153
	v_lshlrev_b32_e32 v168, 16, v150
	v_and_b32_e32 v169, 0xffff0000, v150
	v_lshlrev_b32_e32 v174, 16, v151
	v_and_b32_e32 v175, 0xffff0000, v151
	v_pk_fma_f32 v[90:91], v[152:153], s[6:7], v[90:91] op_sel_hi:[1,0,1]
	v_pk_fma_f32 v[150:151], v[168:169], s[6:7], v[92:93] op_sel_hi:[1,0,1]
	v_pk_fma_f32 v[92:93], v[174:175], s[6:7], v[94:95] op_sel_hi:[1,0,1]
	v_pk_fma_f32 v[94:95], v[184:185], s[6:7], v[88:89] op_sel_hi:[1,0,1]
	v_mul_f32_e32 v88, v90, v90
	v_pk_fma_f32 v[184:185], v[90:91], v[90:91], v[88:89] op_sel_hi:[1,1,0]
	v_lshlrev_b32_e32 v88, 16, v154
	v_and_b32_e32 v89, 0xffff0000, v154
	v_lshlrev_b32_e32 v192, 16, v155
	v_and_b32_e32 v193, 0xffff0000, v155
	v_lshlrev_b32_e32 v196, 16, v156
	v_and_b32_e32 v197, 0xffff0000, v156
	v_lshlrev_b32_e32 v198, 16, v157
	v_and_b32_e32 v199, 0xffff0000, v157
	v_mov_b64_e32 v[154:155], v[230:231]
	v_mov_b64_e32 v[156:157], v[232:233]
	v_pk_add_f32 v[168:169], v[150:151], v[150:151] op_sel:[0,1] op_sel_hi:[1,0]
	v_pk_add_f32 v[174:175], v[92:93], v[92:93] op_sel:[0,1] op_sel_hi:[1,0]
; #define PG8_LAS __attribute__((address_space(3)))
;     __device__ __forceinline__ void fused(f32x4 (&acc)[2][2][4][2], const Unit& u, int wr, int wc, int fr, int fq, PG8_LAS unsigned char* lds, int wid, int lane) const {
;     ...
;             for (int m = 0; m < 4; ++m) {
;                 const int rl = ai * 128 + wr * 64 + m * 16 + fr;
;                 const size_t roff = (size_t)(u.pm * 256 + rl) * 1024 + u.pn * 256 + wc * 32 + fq * 8;
;                 float s1 = 0.f, s2 = 0.f;
; #pragma unroll
;                 for (int bj = 0; bj < 2; ++bj) {
;                     float x[8];
;                     if (RES_BF16) ld8f((const bfu*)res + roff + bj * 128, x);
;                     else ld8f32((const float*)res + roff + bj * 128, x);
; #pragma unroll
;                     for (int n = 0; n < 2; ++n) {
;                         f32x4 v = acc[ai][bj][m][n];
;                         v[0] += ALPHA * x[4 * n]; v[1] += ALPHA * x[4 * n + 1]; v[2] += ALPHA * x[4 * n + 2]; v[3] += ALPHA * x[4 * n + 3];
;                         acc[ai][bj][m][n] = v;
;                         s1 += (v[0] + v[1]) + (v[2] + v[3]); s2 += (v[0] * v[0] + v[1] * v[1]) + (v[2] * v[2] + v[3] * v[3]);
;                     }
;                 }
;                 s1 += __shfl_xor(s1, 16); s1 += __shfl_xor(s1, 32); s2 += __shfl_xor(s2, 16); s2 += __shfl_xor(s2, 32);
;                 {
;                     PG8_LAS float* pd = (fq == 0) ? P + (rl * 4 + wc) * 2 : (PG8_LAS float*)(lds + 12288) + tid * 2;
;                     pd[0] = s1; pd[1] = s2;
	v_pk_mul_f32 v[188:189], v[150:151], v[150:151]
	v_pk_mul_f32 v[152:153], v[94:95], v[94:95]
	v_pk_fma_f32 v[84:85], v[88:89], s[6:7], v[84:85] op_sel_hi:[1,0,1]
	v_pk_mul_f32 v[190:191], v[92:93], v[92:93]
	v_pk_fma_f32 v[86:87], v[192:193], s[6:7], v[86:87] op_sel_hi:[1,0,1]
	v_pk_mul_f32 v[170:171], v[84:85], v[84:85]
	v_pk_fma_f32 v[88:89], v[196:197], s[6:7], v[80:81] op_sel_hi:[1,0,1]
	v_pk_fma_f32 v[80:81], v[198:199], s[6:7], v[82:83] op_sel_hi:[1,0,1]
	v_mov_b32_e32 v198, v94
	v_mov_b32_e32 v199, v188
	v_mov_b32_e32 v188, v95
	v_mov_b32_e32 v169, v152
	v_mov_b32_e32 v175, v153
	v_pk_mul_f32 v[192:193], v[86:87], v[86:87]
	v_pk_add_f32 v[188:189], v[198:199], v[188:189]
	v_mov_b32_e32 v198, v90
	v_mov_b32_e32 v199, v190
	v_mov_b32_e32 v190, v91
	v_pk_add_f32 v[152:153], v[168:169], v[174:175]
	v_mov_b32_e32 v168, v84
	v_mov_b32_e32 v169, v170
	v_mov_b32_e32 v170, v85
	v_pk_add_f32 v[190:191], v[198:199], v[190:191]
	v_mov_b32_e32 v184, v141
	v_pk_add_f32 v[168:169], v[168:169], v[170:171]
	v_mov_b32_e32 v170, v86
	v_mov_b32_e32 v171, v192
	v_mov_b32_e32 v192, v87
	v_pk_add_f32 v[188:189], v[188:189], v[190:191]
	v_pk_add_f32 v[152:153], v[152:153], v[184:185]
	v_pk_add_f32 v[170:171], v[170:171], v[192:193]
	v_pk_mul_f32 v[82:83], v[88:89], v[88:89]
	v_pk_add_f32 v[152:153], v[188:189], v[152:153]
	v_pk_add_f32 v[168:169], v[168:169], v[170:171]
	v_pk_mul_f32 v[196:197], v[80:81], v[80:81]
	v_pk_add_f32 v[152:153], v[152:153], v[168:169]
	v_mov_b32_e32 v168, v88
	v_mov_b32_e32 v169, v82
	v_mov_b32_e32 v82, v89
	v_pk_add_f32 v[82:83], v[168:169], v[82:83]
	v_mov_b32_e32 v168, v80
	v_mov_b32_e32 v169, v196
	v_mov_b32_e32 v196, v81
	v_pk_add_f32 v[168:169], v[168:169], v[196:197]
	v_add_u32_e32 v188, 0x80, v129
	v_pk_add_f32 v[82:83], v[82:83], v[168:169]
	ds_bpermute_b32 v166, v180, v164
	v_pk_add_f32 v[82:83], v[152:153], v[82:83]
	ds_bpermute_b32 v152, v181, v82
	ds_bpermute_b32 v153, v181, v83
	ds_bpermute_b32 v167, v180, v165
	ds_write_b64 v200, v[162:163]
	v_lshl_add_u32 v162, v178, 5, s7
	v_cndmask_b32_e32 v189, v183, v162, vcc
	s_waitcnt lgkmcnt(2)
	v_pk_add_f32 v[168:169], v[82:83], v[152:153]
	v_add_u32_e32 v82, s19, v188
	v_ashrrev_i32_e32 v83, 31, v82
	v_lshlrev_b32_e32 v184, 16, v160
	v_and_b32_e32 v185, 0xffff0000, v160
	v_lshlrev_b32_e32 v160, 16, v161
	v_and_b32_e32 v161, 0xffff0000, v161
	v_lshlrev_b32_e32 v152, 16, v158
	v_lshlrev_b64 v[82:83], 11, v[82:83]
	v_and_b32_e32 v153, 0xffff0000, v158
	v_lshlrev_b32_e32 v158, 16, v159
	v_and_b32_e32 v159, 0xffff0000, v159
	v_pk_fma_f32 v[74:75], v[160:161], s[6:7], v[74:75] op_sel_hi:[1,0,1]
	v_lshl_add_u64 v[162:163], s[28:29], 0, v[82:83]
	v_pk_fma_f32 v[152:153], v[152:153], s[6:7], v[76:77] op_sel_hi:[1,0,1]
	v_pk_fma_f32 v[76:77], v[158:159], s[6:7], v[78:79] op_sel_hi:[1,0,1]
	v_pk_fma_f32 v[78:79], v[184:185], s[6:7], v[72:73] op_sel_hi:[1,0,1]
	v_mul_f32_e32 v72, v74, v74
	v_lshl_add_u64 v[162:163], v[162:163], 0, s[26:27]
	v_pk_add_f32 v[190:191], v[152:153], v[152:153] op_sel:[0,1] op_sel_hi:[1,0]
	v_pk_add_f32 v[192:193], v[76:77], v[76:77] op_sel:[0,1] op_sel_hi:[1,0]
	v_pk_mul_f32 v[160:161], v[78:79], v[78:79]
	v_pk_fma_f32 v[184:185], v[74:75], v[74:75], v[72:73] op_sel_hi:[1,1,0]
	v_lshlrev_b32_e32 v72, 16, v154
	v_and_b32_e32 v73, 0xffff0000, v154
	v_lshl_add_u64 v[162:163], v[162:163], 0, s[24:25]
	v_pk_mul_f32 v[196:197], v[152:153], v[152:153]
	v_lshlrev_b32_e32 v154, 16, v155
	v_and_b32_e32 v155, 0xffff0000, v155
	v_lshlrev_b32_e32 v200, 16, v156
	v_and_b32_e32 v201, 0xffff0000, v156
	v_lshlrev_b32_e32 v202, 16, v157
	v_and_b32_e32 v203, 0xffff0000, v157
	v_pk_fma_f32 v[68:69], v[72:73], s[6:7], v[68:69] op_sel_hi:[1,0,1]
	v_mov_b32_e32 v191, v160
	v_mov_b32_e32 v193, v161
	v_lshl_add_u64 v[174:175], v[162:163], 0, v[140:141]
	v_pk_mul_f32 v[198:199], v[76:77], v[76:77]
	v_pk_fma_f32 v[70:71], v[154:155], s[6:7], v[70:71] op_sel_hi:[1,0,1]
	v_pk_mul_f32 v[154:155], v[68:69], v[68:69]
	v_pk_fma_f32 v[72:73], v[200:201], s[6:7], v[64:65] op_sel_hi:[1,0,1]
	v_pk_fma_f32 v[64:65], v[202:203], s[6:7], v[66:67] op_sel_hi:[1,0,1]
	v_mov_b32_e32 v202, v78
	v_mov_b32_e32 v203, v196
	v_mov_b32_e32 v196, v79
	v_pk_add_f32 v[160:161], v[190:191], v[192:193]
	v_mov_b32_e32 v184, v141
	s_waitcnt lgkmcnt(1)
	v_pk_add_f32 v[166:167], v[164:165], v[166:167]
	v_mov_b64_e32 v[162:163], v[234:235]
	v_mov_b64_e32 v[164:165], v[236:237]
	v_mov_b64_e32 v[156:157], v[238:239]
	v_mov_b64_e32 v[158:159], v[240:241]
	v_pk_mul_f32 v[174:175], v[70:71], v[70:71]
	v_pk_add_f32 v[196:197], v[202:203], v[196:197]
	v_mov_b32_e32 v202, v74
	v_mov_b32_e32 v203, v198
	v_mov_b32_e32 v198, v75
	v_pk_add_f32 v[160:161], v[160:161], v[184:185]
	v_mov_b32_e32 v184, v68
	v_mov_b32_e32 v185, v154
	v_mov_b32_e32 v154, v69
	v_pk_add_f32 v[198:199], v[202:203], v[198:199]
	v_pk_add_f32 v[154:155], v[184:185], v[154:155]
	v_mov_b32_e32 v184, v70
	v_mov_b32_e32 v185, v174
	v_mov_b32_e32 v174, v71
	v_pk_add_f32 v[196:197], v[196:197], v[198:199]
	v_pk_add_f32 v[174:175], v[184:185], v[174:175]
	v_pk_mul_f32 v[66:67], v[72:73], v[72:73]
	v_pk_add_f32 v[160:161], v[196:197], v[160:161]
	v_pk_add_f32 v[154:155], v[154:155], v[174:175]
	v_pk_mul_f32 v[200:201], v[64:65], v[64:65]
	v_pk_add_f32 v[154:155], v[160:161], v[154:155]
	v_mov_b32_e32 v160, v72
	v_mov_b32_e32 v161, v66
	v_mov_b32_e32 v66, v73
	v_pk_add_f32 v[66:67], v[160:161], v[66:67]
	v_mov_b32_e32 v160, v64
	v_mov_b32_e32 v161, v200
	v_mov_b32_e32 v200, v65
	v_pk_add_f32 v[160:161], v[160:161], v[200:201]
	ds_write_b64 v189, v[166:167]
	v_pk_add_f32 v[66:67], v[66:67], v[160:161]
	v_add_u32_e32 v189, 0x90, v129
	v_pk_add_f32 v[66:67], v[154:155], v[66:67]
	ds_bpermute_b32 v154, v181, v66
	ds_bpermute_b32 v155, v181, v67
	ds_bpermute_b32 v170, v180, v168
	ds_bpermute_b32 v171, v180, v169
	v_lshl_add_u32 v160, v179, 5, s7
	v_cndmask_b32_e32 v206, v183, v160, vcc
	s_waitcnt lgkmcnt(2)
; #define PG8_LAS __attribute__((address_space(3)))
;     __device__ __forceinline__ void fused(f32x4 (&acc)[2][2][4][2], const Unit& u, int wr, int wc, int fr, int fq, PG8_LAS unsigned char* lds, int wid, int lane) const {
;     ...
;             for (int m = 0; m < 4; ++m) {
;                 const int rl = ai * 128 + wr * 64 + m * 16 + fr;
;                 const size_t roff = (size_t)(u.pm * 256 + rl) * 1024 + u.pn * 256 + wc * 32 + fq * 8;
;                 float s1 = 0.f, s2 = 0.f;
; #pragma unroll
;                 for (int bj = 0; bj < 2; ++bj) {
;                     float x[8];
;                     if (RES_BF16) ld8f((const bfu*)res + roff + bj * 128, x);
;                     else ld8f32((const float*)res + roff + bj * 128, x);
; #pragma unroll
;                     for (int n = 0; n < 2; ++n) {
;                         f32x4 v = acc[ai][bj][m][n];
;                         v[0] += ALPHA * x[4 * n]; v[1] += ALPHA * x[4 * n + 1]; v[2] += ALPHA * x[4 * n + 2]; v[3] += ALPHA * x[4 * n + 3];
;                         acc[ai][bj][m][n] = v;
;                         s1 += (v[0] + v[1]) + (v[2] + v[3]); s2 += (v[0] * v[0] + v[1] * v[1]) + (v[2] * v[2] + v[3] * v[3]);
;                     }
;                 }
;                 s1 += __shfl_xor(s1, 16); s1 += __shfl_xor(s1, 32); s2 += __shfl_xor(s2, 16); s2 += __shfl_xor(s2, 32);
;                 {
;                     PG8_LAS float* pd = (fq == 0) ? P + (rl * 4 + wc) * 2 : (PG8_LAS float*)(lds + 12288) + tid * 2;
;                     pd[0] = s1; pd[1] = s2;
	v_pk_add_f32 v[174:175], v[66:67], v[154:155]
	v_add_u32_e32 v66, s19, v189
	v_ashrrev_i32_e32 v67, 31, v66
	v_lshlrev_b64 v[66:67], 11, v[66:67]
	v_lshl_add_u64 v[160:161], s[28:29], 0, v[66:67]
	v_lshl_add_u64 v[160:161], v[160:161], 0, s[26:27]
	v_lshl_add_u64 v[160:161], v[160:161], 0, s[24:25]
	v_lshl_add_u64 v[160:161], v[160:161], 0, v[140:141]
	s_waitcnt lgkmcnt(0)
	v_pk_add_f32 v[170:171], v[168:169], v[170:171]
	v_mov_b64_e32 v[166:167], v[242:243]
	v_mov_b64_e32 v[168:169], v[244:245]
	ds_bpermute_b32 v184, v180, v174
	ds_bpermute_b32 v185, v180, v175
	ds_write_b64 v206, v[170:171]
	s_waitcnt lgkmcnt(1)
	v_pk_add_f32 v[170:171], v[174:175], v[184:185]
	v_lshlrev_b32_e32 v190, 16, v164
	v_and_b32_e32 v191, 0xffff0000, v164
	v_lshlrev_b32_e32 v164, 16, v165
	v_and_b32_e32 v165, 0xffff0000, v165
	v_lshlrev_b32_e32 v154, 16, v162
	v_and_b32_e32 v155, 0xffff0000, v162
	v_lshlrev_b32_e32 v162, 16, v163
	v_and_b32_e32 v163, 0xffff0000, v163
	v_pk_fma_f32 v[58:59], v[164:165], s[6:7], v[58:59] op_sel_hi:[1,0,1]
	v_pk_fma_f32 v[154:155], v[154:155], s[6:7], v[60:61] op_sel_hi:[1,0,1]
	v_pk_fma_f32 v[60:61], v[162:163], s[6:7], v[62:63] op_sel_hi:[1,0,1]
	v_pk_fma_f32 v[62:63], v[190:191], s[6:7], v[56:57] op_sel_hi:[1,0,1]
	v_mul_f32_e32 v56, v58, v58
	v_pk_fma_f32 v[190:191], v[58:59], v[58:59], v[56:57] op_sel_hi:[1,1,0]
	v_lshlrev_b32_e32 v56, 16, v156
	v_and_b32_e32 v57, 0xffff0000, v156
	v_lshlrev_b32_e32 v200, 16, v158
	v_and_b32_e32 v201, 0xffff0000, v158
	v_lshlrev_b32_e32 v202, 16, v159
	v_and_b32_e32 v203, 0xffff0000, v159
	v_mov_b64_e32 v[158:159], v[246:247]
	v_mov_b64_e32 v[160:161], v[248:249]
	v_pk_mul_f32 v[196:197], v[154:155], v[154:155]
	v_lshlrev_b32_e32 v156, 16, v157
	v_and_b32_e32 v157, 0xffff0000, v157
	v_pk_fma_f32 v[52:53], v[56:57], s[6:7], v[52:53] op_sel_hi:[1,0,1]
	v_pk_add_f32 v[162:163], v[154:155], v[154:155] op_sel:[0,1] op_sel_hi:[1,0]
	v_pk_add_f32 v[192:193], v[60:61], v[60:61] op_sel:[0,1] op_sel_hi:[1,0]
	v_pk_mul_f32 v[198:199], v[60:61], v[60:61]
	v_pk_mul_f32 v[164:165], v[62:63], v[62:63]
	v_pk_fma_f32 v[54:55], v[156:157], s[6:7], v[54:55] op_sel_hi:[1,0,1]
	v_pk_mul_f32 v[156:157], v[52:53], v[52:53]
	v_pk_fma_f32 v[56:57], v[200:201], s[6:7], v[48:49] op_sel_hi:[1,0,1]
	v_pk_fma_f32 v[48:49], v[202:203], s[6:7], v[50:51] op_sel_hi:[1,0,1]
	v_mov_b32_e32 v202, v62
	v_mov_b32_e32 v203, v196
	v_mov_b32_e32 v196, v63
	v_pk_mul_f32 v[204:205], v[54:55], v[54:55]
	v_pk_add_f32 v[196:197], v[202:203], v[196:197]
	v_mov_b32_e32 v202, v58
	v_mov_b32_e32 v203, v198
	v_mov_b32_e32 v198, v59
	v_mov_b32_e32 v163, v164
	v_mov_b32_e32 v193, v165
	v_mov_b32_e32 v164, v52
	v_mov_b32_e32 v165, v156
	v_mov_b32_e32 v156, v53
	v_pk_add_f32 v[198:199], v[202:203], v[198:199]
	v_pk_add_f32 v[162:163], v[162:163], v[192:193]
	v_mov_b32_e32 v190, v141
	v_pk_add_f32 v[156:157], v[164:165], v[156:157]
	v_mov_b32_e32 v164, v54
	v_mov_b32_e32 v165, v204
	v_mov_b32_e32 v204, v55
	v_pk_add_f32 v[196:197], v[196:197], v[198:199]
	v_pk_add_f32 v[162:163], v[162:163], v[190:191]
	v_pk_add_f32 v[164:165], v[164:165], v[204:205]
	v_pk_mul_f32 v[50:51], v[56:57], v[56:57]
	v_pk_add_f32 v[162:163], v[196:197], v[162:163]
	v_pk_add_f32 v[156:157], v[156:157], v[164:165]
	v_pk_mul_f32 v[200:201], v[48:49], v[48:49]
	v_pk_add_f32 v[156:157], v[162:163], v[156:157]
	v_mov_b32_e32 v162, v56
	v_mov_b32_e32 v163, v50
	v_mov_b32_e32 v50, v57
	v_pk_add_f32 v[50:51], v[162:163], v[50:51]
	v_mov_b32_e32 v162, v48
	v_mov_b32_e32 v163, v200
	v_mov_b32_e32 v200, v49
	v_pk_add_f32 v[162:163], v[162:163], v[200:201]
	v_add_u32_e32 v190, 0xa0, v129
	v_pk_add_f32 v[50:51], v[50:51], v[162:163]
	v_lshl_add_u32 v162, v182, 5, s7
	v_pk_add_f32 v[50:51], v[156:157], v[50:51]
	ds_bpermute_b32 v156, v181, v50
	ds_bpermute_b32 v157, v181, v51
	v_cndmask_b32_e32 v191, v183, v162, vcc
	v_lshlrev_b32_e32 v162, 16, v168
	v_and_b32_e32 v163, 0xffff0000, v168
	ds_write_b64 v191, v[170:171]
	s_waitcnt lgkmcnt(1)
	v_pk_add_f32 v[174:175], v[50:51], v[156:157]
	v_lshlrev_b32_e32 v50, 16, v166
	v_and_b32_e32 v51, 0xffff0000, v166
	v_lshlrev_b32_e32 v156, 16, v167
	v_and_b32_e32 v157, 0xffff0000, v167
	v_pk_fma_f32 v[50:51], v[50:51], s[6:7], v[44:45] op_sel_hi:[1,0,1]
	v_pk_fma_f32 v[44:45], v[156:157], s[6:7], v[46:47] op_sel_hi:[1,0,1]
	v_pk_fma_f32 v[46:47], v[162:163], s[6:7], v[40:41] op_sel_hi:[1,0,1]
	v_add_u32_e32 v40, s19, v190
	v_ashrrev_i32_e32 v41, 31, v40
	v_lshlrev_b64 v[156:157], 11, v[40:41]
	v_lshl_add_u64 v[40:41], s[28:29], 0, v[156:157]
	v_lshl_add_u64 v[40:41], v[40:41], 0, s[26:27]
	v_lshl_add_u64 v[40:41], v[40:41], 0, s[24:25]
	v_lshlrev_b32_e32 v166, 16, v169
	v_and_b32_e32 v167, 0xffff0000, v169
	v_lshl_add_u64 v[168:169], v[40:41], 0, v[140:141]
	s_waitcnt vmcnt(0)
	v_mov_b64_e32 v[162:163], v[210:211]
	v_mov_b64_e32 v[164:165], v[212:213]
	v_pk_fma_f32 v[42:43], v[166:167], s[6:7], v[42:43] op_sel_hi:[1,0,1]
	v_pk_add_f32 v[192:193], v[50:51], v[50:51] op_sel:[0,1] op_sel_hi:[1,0]
	v_mul_f32_e32 v40, v42, v42
	v_pk_fma_f32 v[204:205], v[42:43], v[42:43], v[40:41] op_sel_hi:[1,1,0]
	s_waitcnt vmcnt(1)
; #define PG8_LAS __attribute__((address_space(3)))
;     __device__ __forceinline__ void fused(f32x4 (&acc)[2][2][4][2], const Unit& u, int wr, int wc, int fr, int fq, PG8_LAS unsigned char* lds, int wid, int lane) const {
;     ...
;             for (int m = 0; m < 4; ++m) {
;                 const int rl = ai * 128 + wr * 64 + m * 16 + fr;
;                 const size_t roff = (size_t)(u.pm * 256 + rl) * 1024 + u.pn * 256 + wc * 32 + fq * 8;
;                 float s1 = 0.f, s2 = 0.f;
; #pragma unroll
;                 for (int bj = 0; bj < 2; ++bj) {
;                     float x[8];
;                     if (RES_BF16) ld8f((const bfu*)res + roff + bj * 128, x);
;                     else ld8f32((const float*)res + roff + bj * 128, x);
; #pragma unroll
;                     for (int n = 0; n < 2; ++n) {
;                         f32x4 v = acc[ai][bj][m][n];
;                         v[0] += ALPHA * x[4 * n]; v[1] += ALPHA * x[4 * n + 1]; v[2] += ALPHA * x[4 * n + 2]; v[3] += ALPHA * x[4 * n + 3];
;                         acc[ai][bj][m][n] = v;
;                         s1 += (v[0] + v[1]) + (v[2] + v[3]); s2 += (v[0] * v[0] + v[1] * v[1]) + (v[2] * v[2] + v[3] * v[3]);
;                     }
;                 }
;                 s1 += __shfl_xor(s1, 16); s1 += __shfl_xor(s1, 32); s2 += __shfl_xor(s2, 16); s2 += __shfl_xor(s2, 32);
;                 {
;                     PG8_LAS float* pd = (fq == 0) ? P + (rl * 4 + wc) * 2 : (PG8_LAS float*)(lds + 12288) + tid * 2;
;                     pd[0] = s1; pd[1] = s2;
;                 }
	v_lshlrev_b32_e32 v40, 16, v158
	v_and_b32_e32 v41, 0xffff0000, v158
	v_pk_add_f32 v[196:197], v[44:45], v[44:45] op_sel:[0,1] op_sel_hi:[1,0]
	v_pk_mul_f32 v[198:199], v[50:51], v[50:51]
	v_pk_mul_f32 v[202:203], v[46:47], v[46:47]
	v_lshlrev_b32_e32 v158, 16, v159
	v_and_b32_e32 v159, 0xffff0000, v159
	v_pk_fma_f32 v[40:41], v[40:41], s[6:7], v[36:37] op_sel_hi:[1,0,1]
	v_pk_mul_f32 v[200:201], v[44:45], v[44:45]
	v_pk_fma_f32 v[36:37], v[158:159], s[6:7], v[38:39] op_sel_hi:[1,0,1]
	v_pk_mul_f32 v[158:159], v[40:41], v[40:41]
	v_mov_b32_e32 v208, v46
	v_mov_b32_e32 v209, v198
	v_mov_b32_e32 v198, v47
	v_mov_b32_e32 v193, v202
	v_mov_b32_e32 v197, v203
	v_pk_mul_f32 v[206:207], v[36:37], v[36:37]
	v_pk_add_f32 v[198:199], v[208:209], v[198:199]
	v_mov_b32_e32 v208, v42
	v_mov_b32_e32 v209, v200
	v_mov_b32_e32 v200, v43
	v_pk_add_f32 v[192:193], v[192:193], v[196:197]
	v_mov_b32_e32 v196, v40
	v_mov_b32_e32 v197, v158
	v_mov_b32_e32 v158, v41
	v_lshlrev_b32_e32 v166, 16, v160
	v_and_b32_e32 v167, 0xffff0000, v160
	v_pk_add_f32 v[200:201], v[208:209], v[200:201]
	v_mov_b32_e32 v204, v141
	v_pk_add_f32 v[158:159], v[196:197], v[158:159]
	v_mov_b32_e32 v196, v36
	v_mov_b32_e32 v197, v206
	v_mov_b32_e32 v206, v37
	v_lshlrev_b32_e32 v160, 16, v161
	v_and_b32_e32 v161, 0xffff0000, v161
	v_pk_fma_f32 v[38:39], v[166:167], s[6:7], v[32:33] op_sel_hi:[1,0,1]
	v_pk_add_f32 v[198:199], v[198:199], v[200:201]
	v_pk_add_f32 v[192:193], v[192:193], v[204:205]
	v_pk_add_f32 v[196:197], v[196:197], v[206:207]
	v_pk_fma_f32 v[32:33], v[160:161], s[6:7], v[34:35] op_sel_hi:[1,0,1]
	v_pk_mul_f32 v[34:35], v[38:39], v[38:39]
	v_pk_add_f32 v[192:193], v[198:199], v[192:193]
	v_pk_add_f32 v[158:159], v[158:159], v[196:197]
	v_pk_mul_f32 v[160:161], v[32:33], v[32:33]
	v_pk_add_f32 v[158:159], v[192:193], v[158:159]
	v_mov_b32_e32 v192, v38
	v_mov_b32_e32 v193, v34
	v_mov_b32_e32 v34, v39
	v_pk_add_f32 v[34:35], v[192:193], v[34:35]
	v_mov_b32_e32 v192, v32
	v_mov_b32_e32 v193, v160
	v_mov_b32_e32 v160, v33
	v_pk_add_f32 v[160:161], v[192:193], v[160:161]
	s_nop 1
	v_mov_b64_e32 v[166:167], v[214:215]
	v_mov_b64_e32 v[168:169], v[216:217]
	v_pk_add_f32 v[34:35], v[34:35], v[160:161]
	ds_bpermute_b32 v184, v180, v174
	v_pk_add_f32 v[34:35], v[158:159], v[34:35]
	ds_bpermute_b32 v158, v181, v34
	ds_bpermute_b32 v159, v181, v35
	ds_bpermute_b32 v185, v180, v175
	v_add_u32_e32 v191, 0xb0, v129
	v_lshl_add_u32 v160, v188, 5, s7
	v_cndmask_b32_e32 v192, v183, v160, vcc
	s_waitcnt lgkmcnt(1)
	v_pk_add_f32 v[158:159], v[34:35], v[158:159]
	v_add_u32_e32 v34, s19, v191
	v_ashrrev_i32_e32 v35, 31, v34
	ds_bpermute_b32 v170, v180, v158
	ds_bpermute_b32 v171, v180, v159
	v_lshlrev_b64 v[34:35], 11, v[34:35]
	s_waitcnt lgkmcnt(2)
	v_pk_add_f32 v[160:161], v[174:175], v[184:185]
	v_lshl_add_u64 v[174:175], s[28:29], 0, v[34:35]
	v_lshl_add_u64 v[174:175], v[174:175], 0, s[26:27]
	v_lshl_add_u64 v[174:175], v[174:175], 0, s[24:25]
	v_lshl_add_u64 v[174:175], v[174:175], 0, v[140:141]
	v_lshl_add_u32 v140, v189, 5, s7
	s_nop 1
	v_mov_b64_e32 v[196:197], v[218:219]
	v_mov_b64_e32 v[198:199], v[220:221]
	v_cndmask_b32_e32 v140, v183, v140, vcc
	s_waitcnt lgkmcnt(0)
	v_pk_add_f32 v[158:159], v[158:159], v[170:171]
	ds_write_b64 v192, v[160:161]
	ds_write_b64 v140, v[158:159]
	s_waitcnt vmcnt(2)
	v_lshlrev_b32_e32 v158, 16, v162
	v_and_b32_e32 v159, 0xffff0000, v162
	v_lshlrev_b32_e32 v162, 16, v163
	v_and_b32_e32 v163, 0xffff0000, v163
	v_pk_fma_f32 v[160:161], v[158:159], s[6:7], v[28:29] op_sel_hi:[1,0,1]
	v_pk_fma_f32 v[158:159], v[162:163], s[6:7], v[30:31] op_sel_hi:[1,0,1]
	s_nop 1
	v_mov_b64_e32 v[28:29], v[222:223]
	v_mov_b64_e32 v[30:31], v[224:225]
	v_lshlrev_b32_e32 v184, 16, v165
	v_and_b32_e32 v185, 0xffff0000, v165
	v_lshlrev_b32_e32 v170, 16, v164
	v_and_b32_e32 v171, 0xffff0000, v164
	v_pk_fma_f32 v[162:163], v[184:185], s[6:7], v[26:27] op_sel_hi:[1,0,1]
	v_pk_fma_f32 v[164:165], v[170:171], s[6:7], v[24:25] op_sel_hi:[1,0,1]
	v_mul_f32_e32 v24, v162, v162
	v_pk_add_f32 v[192:193], v[160:161], v[160:161] op_sel:[0,1] op_sel_hi:[1,0]
	v_pk_add_f32 v[200:201], v[158:159], v[158:159] op_sel:[0,1] op_sel_hi:[1,0]
	v_pk_mul_f32 v[26:27], v[164:165], v[164:165]
	v_pk_fma_f32 v[170:171], v[162:163], v[162:163], v[24:25] op_sel_hi:[1,1,0]
	v_pk_mul_f32 v[202:203], v[160:161], v[160:161]
	v_mov_b32_e32 v193, v26
	v_mov_b32_e32 v201, v27
	v_pk_mul_f32 v[174:175], v[158:159], v[158:159]
	v_pk_add_f32 v[26:27], v[192:193], v[200:201]
	v_mov_b32_e32 v170, v141
	v_pk_add_f32 v[26:27], v[26:27], v[170:171]
	v_lshl_add_u32 v140, v190, 5, s7
	s_waitcnt vmcnt(2)
; #define PG8_LAS __attribute__((address_space(3)))
;     __device__ __forceinline__ void fused(f32x4 (&acc)[2][2][4][2], const Unit& u, int wr, int wc, int fr, int fq, PG8_LAS unsigned char* lds, int wid, int lane) const {
;     ...
;             for (int m = 0; m < 4; ++m) {
;                 const int rl = ai * 128 + wr * 64 + m * 16 + fr;
;                 const size_t roff = (size_t)(u.pm * 256 + rl) * 1024 + u.pn * 256 + wc * 32 + fq * 8;
;                 float s1 = 0.f, s2 = 0.f;
; #pragma unroll
;                 for (int bj = 0; bj < 2; ++bj) {
;                     float x[8];
;                     if (RES_BF16) ld8f((const bfu*)res + roff + bj * 128, x);
;                     else ld8f32((const float*)res + roff + bj * 128, x);
; #pragma unroll
;                     for (int n = 0; n < 2; ++n) {
;                         f32x4 v = acc[ai][bj][m][n];
;                         v[0] += ALPHA * x[4 * n]; v[1] += ALPHA * x[4 * n + 1]; v[2] += ALPHA * x[4 * n + 2]; v[3] += ALPHA * x[4 * n + 3];
;                         acc[ai][bj][m][n] = v;
;                         s1 += (v[0] + v[1]) + (v[2] + v[3]); s2 += (v[0] * v[0] + v[1] * v[1]) + (v[2] * v[2] + v[3] * v[3]);
;                     }
;                 }
;                 s1 += __shfl_xor(s1, 16); s1 += __shfl_xor(s1, 32); s2 += __shfl_xor(s2, 16); s2 += __shfl_xor(s2, 32);
;                 {
;                     PG8_LAS float* pd = (fq == 0) ? P + (rl * 4 + wc) * 2 : (PG8_LAS float*)(lds + 12288) + tid * 2;
;                     pd[0] = s1; pd[1] = s2;
;                 }
;             }
;         __syncthreads();
;         if (tid < 256) {
;             const float a = P[tid * 8] + P[tid * 8 + 2] + P[tid * 8 + 4] + P[tid * 8 + 6], b = P[tid * 8 + 1] + P[tid * 8 + 3] + P[tid * 8 + 5] + P[tid * 8 + 7];
;             const unsigned long long pk = (unsigned long long)__float_as_uint(a) | ((unsigned long long)__float_as_uint(b) << 32);
;             __hip_atomic_store(xch + ((size_t)(u.pm * 256 + tid) * 4 + u.pn), pk, __ATOMIC_RELAXED, __HIP_MEMORY_SCOPE_AGENT);
;         }
	v_lshlrev_b32_e32 v24, 16, v166
	v_and_b32_e32 v25, 0xffff0000, v166
	v_lshlrev_b32_e32 v166, 16, v167
	v_and_b32_e32 v167, 0xffff0000, v167
	v_lshlrev_b32_e32 v184, 16, v168
	v_and_b32_e32 v185, 0xffff0000, v168
	v_pk_fma_f32 v[24:25], v[24:25], s[6:7], v[20:21] op_sel_hi:[1,0,1]
	v_pk_fma_f32 v[20:21], v[166:167], s[6:7], v[22:23] op_sel_hi:[1,0,1]
	v_pk_mul_f32 v[166:167], v[24:25], v[24:25]
	v_pk_fma_f32 v[22:23], v[184:185], s[6:7], v[16:17] op_sel_hi:[1,0,1]
	v_mov_b32_e32 v184, v164
	v_mov_b32_e32 v185, v202
	v_mov_b32_e32 v202, v165
	v_pk_mul_f32 v[204:205], v[20:21], v[20:21]
	v_pk_add_f32 v[184:185], v[184:185], v[202:203]
	v_mov_b32_e32 v202, v162
	v_mov_b32_e32 v203, v174
	v_mov_b32_e32 v174, v163
	v_mov_b32_e32 v170, v24
	v_mov_b32_e32 v171, v166
	v_mov_b32_e32 v166, v25
	v_pk_add_f32 v[174:175], v[202:203], v[174:175]
	v_pk_add_f32 v[166:167], v[170:171], v[166:167]
	v_mov_b32_e32 v170, v20
	v_mov_b32_e32 v171, v204
	v_mov_b32_e32 v204, v21
	v_lshlrev_b32_e32 v168, 16, v169
	v_and_b32_e32 v169, 0xffff0000, v169
	v_pk_add_f32 v[174:175], v[184:185], v[174:175]
	v_pk_add_f32 v[170:171], v[170:171], v[204:205]
	v_pk_fma_f32 v[16:17], v[168:169], s[6:7], v[18:19] op_sel_hi:[1,0,1]
	v_pk_mul_f32 v[18:19], v[22:23], v[22:23]
	v_pk_add_f32 v[26:27], v[174:175], v[26:27]
	v_pk_add_f32 v[166:167], v[166:167], v[170:171]
	v_pk_mul_f32 v[168:169], v[16:17], v[16:17]
	v_pk_add_f32 v[26:27], v[26:27], v[166:167]
	v_mov_b32_e32 v166, v22
	v_mov_b32_e32 v167, v18
	v_mov_b32_e32 v18, v23
	v_pk_add_f32 v[18:19], v[166:167], v[18:19]
	v_mov_b32_e32 v166, v16
	v_mov_b32_e32 v167, v168
	v_mov_b32_e32 v168, v17
	v_pk_add_f32 v[166:167], v[166:167], v[168:169]
	s_waitcnt vmcnt(1)
	v_lshlrev_b32_e32 v168, 16, v198
	v_pk_add_f32 v[18:19], v[18:19], v[166:167]
	v_and_b32_e32 v169, 0xffff0000, v198
	v_pk_add_f32 v[184:185], v[26:27], v[18:19]
	v_lshlrev_b32_e32 v18, 16, v196
	v_and_b32_e32 v19, 0xffff0000, v196
	v_lshlrev_b32_e32 v26, 16, v197
	v_and_b32_e32 v27, 0xffff0000, v197
	v_lshlrev_b32_e32 v196, 16, v199
	v_and_b32_e32 v197, 0xffff0000, v199
	v_pk_fma_f32 v[170:171], v[18:19], s[6:7], v[12:13] op_sel_hi:[1,0,1]
	v_pk_fma_f32 v[166:167], v[26:27], s[6:7], v[14:15] op_sel_hi:[1,0,1]
	v_pk_fma_f32 v[174:175], v[168:169], s[6:7], v[8:9] op_sel_hi:[1,0,1]
	v_pk_fma_f32 v[168:169], v[196:197], s[6:7], v[10:11] op_sel_hi:[1,0,1]
	v_pk_add_f32 v[12:13], v[170:171], v[170:171] op_sel:[0,1] op_sel_hi:[1,0]
	v_pk_add_f32 v[14:15], v[166:167], v[166:167] op_sel:[0,1] op_sel_hi:[1,0]
	v_pk_mul_f32 v[8:9], v[174:175], v[174:175]
	v_mul_f32_e32 v10, v168, v168
	s_waitcnt vmcnt(0)
	v_lshlrev_b32_e32 v18, 16, v28
	v_and_b32_e32 v19, 0xffff0000, v28
	v_pk_fma_f32 v[10:11], v[168:169], v[168:169], v[10:11] op_sel_hi:[1,1,0]
	v_lshlrev_b32_e32 v28, 16, v29
	v_and_b32_e32 v29, 0xffff0000, v29
	v_pk_fma_f32 v[26:27], v[18:19], s[6:7], v[4:5] op_sel_hi:[1,0,1]
	v_mov_b32_e32 v13, v8
	v_mov_b32_e32 v15, v9
	v_pk_fma_f32 v[18:19], v[28:29], s[6:7], v[6:7] op_sel_hi:[1,0,1]
	v_pk_mul_f32 v[4:5], v[26:27], v[26:27]
	v_pk_add_f32 v[8:9], v[12:13], v[14:15]
	v_mov_b32_e32 v10, v141
	v_pk_mul_f32 v[198:199], v[170:171], v[170:171]
	v_lshlrev_b32_e32 v196, 16, v30
	v_and_b32_e32 v197, 0xffff0000, v30
	v_pk_mul_f32 v[6:7], v[18:19], v[18:19]
	v_pk_add_f32 v[8:9], v[8:9], v[10:11]
	v_mov_b32_e32 v10, v26
	v_mov_b32_e32 v11, v4
	v_mov_b32_e32 v4, v27
	v_pk_mul_f32 v[200:201], v[166:167], v[166:167]
	v_lshlrev_b32_e32 v202, 16, v31
	v_and_b32_e32 v203, 0xffff0000, v31
	v_pk_fma_f32 v[30:31], v[196:197], s[6:7], v[0:1] op_sel_hi:[1,0,1]
	v_mov_b32_e32 v196, v174
	v_mov_b32_e32 v197, v198
	v_mov_b32_e32 v198, v175
	v_pk_add_f32 v[4:5], v[10:11], v[4:5]
	v_mov_b32_e32 v10, v18
	v_mov_b32_e32 v11, v6
	v_mov_b32_e32 v6, v19
	v_pk_fma_f32 v[28:29], v[202:203], s[6:7], v[2:3] op_sel_hi:[1,0,1]
	v_pk_mul_f32 v[0:1], v[30:31], v[30:31]
	v_pk_add_f32 v[196:197], v[196:197], v[198:199]
	v_mov_b32_e32 v198, v168
	v_mov_b32_e32 v199, v200
	v_mov_b32_e32 v200, v169
	v_pk_add_f32 v[6:7], v[10:11], v[6:7]
	v_pk_mul_f32 v[2:3], v[28:29], v[28:29]
	v_pk_add_f32 v[198:199], v[198:199], v[200:201]
	v_pk_add_f32 v[4:5], v[4:5], v[6:7]
	v_mov_b32_e32 v6, v30
	v_mov_b32_e32 v7, v0
	v_mov_b32_e32 v0, v31
	v_pk_add_f32 v[196:197], v[196:197], v[198:199]
	v_pk_add_f32 v[0:1], v[6:7], v[0:1]
	v_mov_b32_e32 v6, v28
	v_mov_b32_e32 v7, v2
	v_mov_b32_e32 v2, v29
	v_pk_add_f32 v[8:9], v[196:197], v[8:9]
	v_pk_add_f32 v[2:3], v[6:7], v[2:3]
	ds_bpermute_b32 v192, v181, v184
	ds_bpermute_b32 v193, v181, v185
	v_pk_add_f32 v[4:5], v[8:9], v[4:5]
	v_pk_add_f32 v[0:1], v[0:1], v[2:3]
	v_cndmask_b32_e32 v8, v183, v140, vcc
	v_pk_add_f32 v[0:1], v[4:5], v[0:1]
	ds_bpermute_b32 v2, v181, v0
	ds_bpermute_b32 v3, v181, v1
	s_waitcnt lgkmcnt(2)
	v_pk_add_f32 v[4:5], v[184:185], v[192:193]
	ds_bpermute_b32 v6, v180, v4
	ds_bpermute_b32 v7, v180, v5
	s_movk_i32 s6, 0x100
	s_waitcnt lgkmcnt(2)
	v_pk_add_f32 v[0:1], v[0:1], v[2:3]
	ds_bpermute_b32 v2, v180, v0
	ds_bpermute_b32 v3, v180, v1
	s_waitcnt lgkmcnt(2)
	v_pk_add_f32 v[4:5], v[4:5], v[6:7]
	ds_write_b64 v8, v[4:5]
	v_lshl_add_u32 v4, v191, 5, s7
	v_cndmask_b32_e32 v4, v183, v4, vcc
	s_waitcnt lgkmcnt(1)
	v_pk_add_f32 v[0:1], v[0:1], v[2:3]
	ds_write_b64 v4, v[0:1]
	v_or_b32_e32 v0, s19, v172
	v_cmp_gt_u32_e64 s[6:7], s6, v172
	v_ashrrev_i32_e32 v1, 31, v0
	s_waitcnt lgkmcnt(0)
	s_barrier
	s_and_saveexec_b64 s[24:25], s[6:7]
	s_cbranch_execz .LBB0_1050
	v_lshl_add_u32 v6, v172, 5, 0
	ds_read_b128 v[2:5], v6
	ds_read_b128 v[6:9], v6 offset:16
	s_ashr_i32 s21, s20, 31
	s_waitcnt lgkmcnt(1)
	v_add_f32_e32 v2, v2, v4
	v_add_f32_e32 v3, v3, v5
	v_lshlrev_b64 v[4:5], 5, v[0:1]
	s_waitcnt lgkmcnt(0)
	v_add_f32_e32 v2, v2, v6
	v_add_f32_e32 v3, v3, v7
	v_lshl_add_u64 v[4:5], s[22:23], 0, v[4:5]
	v_add_f32_e32 v2, v2, v8
	v_add_f32_e32 v3, v3, v9
	v_lshl_add_u64 v[4:5], s[20:21], 3, v[4:5]
	global_store_dwordx2 v[4:5], v[2:3], off sc1

; __device__ __forceinline__ unsigned pk2(float lo, float hi) { f32x2_t v = {lo, hi}; bf16x2_t b = __builtin_convertvector(v, bf16x2_t); return __builtin_bit_cast(unsigned, b); }
; template <bool BATCH>
; __device__ __forceinline__ void transpose_tile(const float* __restrict__ src, int ld, int N, int K, int k0, int n0, bfu* __restrict__ dst,
;                                                int blk, int stride, int off, float* tl  ) {
;     ...
;         } else {
; #pragma unroll
;             for (int i = 0; i < 4; ++i) v[i] = (n0 + n4 < N) ? *(const float4*)(src + (size_t)(k0 + kk + 16 * i) * ld + n0 + n4) : make_float4(0.f, 0.f, 0.f, 0.f);
;         }
; #pragma unroll
;         for (int i = 0; i < 4; ++i) { float* t = tl + (kk + 16 * i) * 129 + n4; t[0] = v[i].x; t[1] = v[i].y; t[2] = v[i].z; t[3] = v[i].w; }
;     }
;     __syncthreads();
;     {
;         const int k2 = (tid & 31) * 2, nn = tid >> 5;
; #pragma unroll
;         for (int i = 0; i < 8; ++i) {
;             const int nl = nn + 16 * i, ng = n0 + nl;
;             if (ng < N) { const int row = (ng / blk) * stride + (ng % blk) + off; *(unsigned*)(dst + (size_t)row * K + k0 + k2) = pk2(tl[k2 * 129 + nl], tl[(k2 + 1) * 129 + nl]); }
;         }
;     }
; template <bool BATCH>
; __device__ __forceinline__ void weight_job(const Params& p, int job, float* ldsf) {
;     ...
;     transpose_tile<BATCH>(p.w_down, 1024, 1024, DFF, (j / 8) * 64, (j % 8) * 128, (bfu*)(ws + WS_WDN), BIG, 0, 0, ldsf);
.LBB0_1167:
	s_cmpk_gt_u32 s3, 0x6cf
	s_mov_b64 s[6:7], -1
	s_cbranch_scc0 .LBB0_1171
	s_load_dwordx2 s[6:7], s[0:1], 0x98
	s_and_b32 s34, s9, 0x380
	s_and_b32 s4, s8, 0x7fffffc0
	s_lshl_b32 s35, s34, 2
	v_or_b32_e32 v28, s4, v8
	s_waitcnt lgkmcnt(0)
	s_add_u32 s6, s6, s35
	s_addc_u32 s7, s7, 0
	v_lshl_add_u64 v[6:7], s[6:7], 0, v[0:1]
	v_lshlrev_b32_e32 v28, 10, v28
	v_mov_b32_e32 v29, v1
	v_lshl_add_u64 v[6:7], v[28:29], 2, v[6:7]
	v_add_co_u32_e32 v28, vcc, s11, v6
	v_or_b32_e32 v46, s34, v11
	s_nop 0
	v_addc_co_u32_e32 v29, vcc, 0, v7, vcc
	global_load_dwordx4 v[30:33], v[6:7], off nt
	global_load_dwordx4 v[34:37], v[28:29], off nt
	v_add_co_u32_e32 v28, vcc, s22, v6
	v_or_b32_e32 v48, s34, v13
	s_nop 0
	v_addc_co_u32_e32 v29, vcc, 0, v7, vcc
	global_load_dwordx4 v[38:41], v[28:29], off nt
	v_add_co_u32_e32 v6, vcc, s23, v6
	v_or_b32_e32 v50, s34, v14
	s_nop 0
	v_addc_co_u32_e32 v7, vcc, 0, v7, vcc
	global_load_dwordx4 v[42:45], v[6:7], off nt
	v_or_b32_e32 v6, s34, v8
	v_or_b32_e32 v7, s34, v9
	v_or_b32_e32 v29, s34, v10
	v_or_b32_e32 v52, s34, v15
	v_mul_u32_u24_e32 v6, 0xb00, v6
	v_mul_u32_u24_e32 v7, 0xb00, v7
	s_lshl_b32 s4, s4, 1
	v_mov_b32_e32 v47, v1
	v_add_u32_e32 v28, s34, v16
	v_mul_u32_u24_e32 v29, 0xb00, v29
	v_mul_u32_u24_e32 v54, 0xb00, v46
	v_mul_u32_u24_e32 v56, 0xb00, v48
	v_mul_u32_u24_e32 v58, 0xb00, v50
	v_mul_u32_u24_e32 v60, 0xb00, v52
	v_lshlrev_b32_e32 v46, 1, v6
	v_lshlrev_b32_e32 v48, 1, v7
	v_lshl_add_u64 v[6:7], v[2:3], 0, s[4:5]
	v_mov_b32_e32 v49, v1
	v_mov_b32_e32 v51, v1
	v_mov_b32_e32 v53, v1
	v_mov_b32_e32 v55, v1
	v_mov_b32_e32 v57, v1
	v_mov_b32_e32 v59, v1
	v_lshlrev_b32_e32 v50, 1, v29
	v_lshlrev_b32_e32 v52, 1, v54
	v_lshlrev_b32_e32 v54, 1, v56
	v_lshlrev_b32_e32 v56, 1, v58
	v_lshlrev_b32_e32 v58, 1, v60
	v_lshl_add_u64 v[46:47], v[6:7], 0, v[46:47]
	v_cmp_gt_u32_e32 vcc, s25, v28
	v_lshl_add_u64 v[48:49], v[6:7], 0, v[48:49]
	v_lshl_add_u64 v[50:51], v[6:7], 0, v[50:51]
	v_lshl_add_u64 v[52:53], v[6:7], 0, v[52:53]
	v_lshl_add_u64 v[54:55], v[6:7], 0, v[54:55]
	v_lshl_add_u64 v[56:57], v[6:7], 0, v[56:57]
	v_lshl_add_u64 v[58:59], v[6:7], 0, v[58:59]
	s_waitcnt vmcnt(0)
	ds_write2_b32 v20, v30, v31 offset1:1
	ds_write2_b32 v20, v32, v33 offset0:2 offset1:3
	ds_write2_b32 v21, v34, v35 offset1:1
	ds_write2_b32 v22, v36, v37 offset1:1
	ds_write2_b32 v23, v38, v39 offset1:1
	ds_write2_b32 v24, v40, v41 offset1:1
	ds_write2_b32 v25, v42, v43 offset1:1
	ds_write2_b32 v26, v44, v45 offset1:1
	s_waitcnt lgkmcnt(0)
	s_barrier
	ds_read2_b32 v[30:31], v12 offset1:16
	ds_read2_b32 v[32:33], v12 offset0:96 offset1:129
	ds_read2_b32 v[34:35], v12 offset0:145 offset1:161
	ds_read2_b32 v[36:37], v12 offset0:32 offset1:48
	ds_read2_b32 v[38:39], v12 offset0:177 offset1:193
	ds_read2_b32 v[40:41], v12 offset0:64 offset1:80
	ds_read2_b32 v[42:43], v12 offset0:209 offset1:225
	s_waitcnt lgkmcnt(5)
	v_cvt_pk_bf16_f32 v29, v30, v33
	s_waitcnt lgkmcnt(4)
	v_cvt_pk_bf16_f32 v30, v31, v34
	s_waitcnt lgkmcnt(3)
	v_cvt_pk_bf16_f32 v31, v36, v35
	s_waitcnt lgkmcnt(2)
	v_cvt_pk_bf16_f32 v33, v37, v38
	s_waitcnt lgkmcnt(1)
	v_cvt_pk_bf16_f32 v34, v40, v39
	s_waitcnt lgkmcnt(0)
	v_cvt_pk_bf16_f32 v35, v41, v42
	v_cvt_pk_bf16_f32 v32, v32, v43
	global_store_dword v[46:47], v29, off
	global_store_dword v[48:49], v30, off
	global_store_dword v[50:51], v31, off
	global_store_dword v[52:53], v33, off
	global_store_dword v[54:55], v34, off
	global_store_dword v[56:57], v35, off
	global_store_dword v[58:59], v32, off
	s_and_saveexec_b64 s[6:7], vcc
	s_cbranch_execz .LBB0_1170
	ds_read2_b32 v[30:31], v12 offset0:112 offset1:241
	v_mul_u32_u24_e32 v28, 0xb00, v28
	v_mov_b32_e32 v29, v1
	v_lshlrev_b32_e32 v28, 1, v28
	v_lshl_add_u64 v[6:7], v[6:7], 0, v[28:29]
	s_waitcnt lgkmcnt(0)
	v_cvt_pk_bf16_f32 v30, v30, v31
	global_store_dword v[6:7], v30, off

; __device__ __forceinline__ unsigned pk2(float lo, float hi) { f32x2_t v = {lo, hi}; bf16x2_t b = __builtin_convertvector(v, bf16x2_t); return __builtin_bit_cast(unsigned, b); }
; template <bool BATCH>
; __device__ __forceinline__ void transpose_tile(const float* __restrict__ src, int ld, int N, int K, int k0, int n0, bfu* __restrict__ dst,
;                                                int blk, int stride, int off, float* tl  ) {
;     ...
;         } else {
; #pragma unroll
;             for (int i = 0; i < 4; ++i) v[i] = (n0 + n4 < N) ? *(const float4*)(src + (size_t)(k0 + kk + 16 * i) * ld + n0 + n4) : make_float4(0.f, 0.f, 0.f, 0.f);
;         }
; #pragma unroll
;         for (int i = 0; i < 4; ++i) { float* t = tl + (kk + 16 * i) * 129 + n4; t[0] = v[i].x; t[1] = v[i].y; t[2] = v[i].z; t[3] = v[i].w; }
;     }
;     __syncthreads();
;     {
;         const int k2 = (tid & 31) * 2, nn = tid >> 5;
; #pragma unroll
;         for (int i = 0; i < 8; ++i) {
;             const int nl = nn + 16 * i, ng = n0 + nl;
;             if (ng < N) { const int row = (ng / blk) * stride + (ng % blk) + off; *(unsigned*)(dst + (size_t)row * K + k0 + k2) = pk2(tl[k2 * 129 + nl], tl[(k2 + 1) * 129 + nl]); }
;         }
;     }
; template <bool BATCH>
; __device__ __forceinline__ void weight_job(const Params& p, int job, float* ldsf) {
;     ...
;     if (j < J_U) { transpose_tile<BATCH>(p.w_up, DFF, DFF, 1024, (j / 22) * 64, (j % 22) * 128, (bfu*)(ws + WS_WGU), 128, 256, 128, ldsf); return; }
.LBB0_1171:
	s_and_b64 vcc, exec, s[6:7]
	s_cbranch_vccz .LBB0_1166
	s_add_i32 s4, s3, 0xfa90
	s_and_b32 s34, s4, 0xffff
	s_mul_i32 s34, s34, 0xba2f
	s_lshr_b32 s34, s34, 20
	s_load_dwordx2 s[6:7], s[0:1], 0x90
	s_mul_i32 s35, s34, 22
	s_sub_i32 s35, s4, s35
	s_lshl_b32 s4, s35, 7
	s_and_b32 s36, s4, 0xff80
	s_lshl_b32 s4, s36, 2
	v_lshl_or_b32 v28, s34, 6, v8
	s_waitcnt lgkmcnt(0)
	s_add_u32 s6, s6, s4
	s_addc_u32 s7, s7, 0
	v_mul_u32_u24_e32 v28, 0xb00, v28
	v_lshl_add_u64 v[6:7], s[6:7], 0, v[0:1]
	v_lshlrev_b32_e32 v28, 2, v28
	v_mov_b32_e32 v29, v1
	v_lshl_add_u64 v[6:7], v[6:7], 0, v[28:29]
	v_add_co_u32_e32 v36, vcc, s26, v6
	s_lshl_b32 s4, s34, 7
	s_nop 0
	v_addc_co_u32_e32 v37, vcc, 0, v7, vcc
	global_load_dwordx4 v[28:31], v[6:7], off nt
	global_load_dwordx4 v[32:35], v[36:37], off nt
	v_add_co_u32_e32 v36, vcc, s27, v6
	s_lshl_b32 s6, s35, 8
	s_nop 0
	v_addc_co_u32_e32 v37, vcc, 0, v7, vcc
	global_load_dwordx4 v[36:39], v[36:37], off nt
	v_add_co_u32_e32 v6, vcc, s28, v6
	v_mov_b32_e32 v45, v1
	s_nop 0
	v_addc_co_u32_e32 v7, vcc, 0, v7, vcc
	global_load_dwordx4 v[40:43], v[6:7], off nt
	v_lshl_add_u64 v[6:7], v[4:5], 0, s[4:5]
	s_and_b32 s4, s6, 0xff00
	v_or_b32_e32 v44, s4, v8
	v_lshlrev_b32_e32 v44, 11, v44
	v_lshl_add_u64 v[44:45], v[6:7], 0, v[44:45]
	v_add_co_u32_e32 v52, vcc, s29, v44
	v_or_b32_e32 v46, s4, v17
	s_nop 0
	v_addc_co_u32_e32 v53, vcc, 0, v45, vcc
	v_add_co_u32_e32 v54, vcc, s30, v44
	v_or_b32_e32 v48, s4, v18
	s_nop 0
	v_addc_co_u32_e32 v55, vcc, 0, v45, vcc
	v_add_co_u32_e32 v56, vcc, s31, v44
	v_or_b32_e32 v50, s4, v19
	s_nop 0
	v_addc_co_u32_e32 v57, vcc, 0, v45, vcc
	v_mov_b32_e32 v47, v1
	v_mov_b32_e32 v49, v1
	v_mov_b32_e32 v51, v1
	v_lshlrev_b32_e32 v46, 11, v46
	v_lshlrev_b32_e32 v48, 11, v48
	v_lshlrev_b32_e32 v50, 11, v50
	v_add_co_u32_e32 v44, vcc, 0x70000, v44
	v_lshl_add_u64 v[46:47], v[6:7], 0, v[46:47]
	v_lshl_add_u64 v[48:49], v[6:7], 0, v[48:49]
	v_lshl_add_u64 v[50:51], v[6:7], 0, v[50:51]
	v_addc_co_u32_e32 v45, vcc, 0, v45, vcc
	s_waitcnt vmcnt(0)
	ds_write2_b32 v20, v28, v29 offset1:1
	ds_write2_b32 v20, v30, v31 offset0:2 offset1:3
	ds_write2_b32 v21, v32, v33 offset1:1
	ds_write2_b32 v22, v34, v35 offset1:1
	ds_write2_b32 v23, v36, v37 offset1:1
	ds_write2_b32 v24, v38, v39 offset1:1
	ds_write2_b32 v25, v40, v41 offset1:1
	ds_write2_b32 v26, v42, v43 offset1:1
	s_waitcnt lgkmcnt(0)
	s_barrier
	ds_read2_b32 v[28:29], v12 offset1:16
	ds_read2_b32 v[30:31], v12 offset0:96 offset1:129
	ds_read2_b32 v[32:33], v12 offset0:145 offset1:161
	ds_read2_b32 v[34:35], v12 offset0:32 offset1:48
	ds_read2_b32 v[36:37], v12 offset0:177 offset1:193
	ds_read2_b32 v[38:39], v12 offset0:64 offset1:80
	ds_read2_b32 v[40:41], v12 offset0:209 offset1:225
	s_waitcnt lgkmcnt(5)
	v_cvt_pk_bf16_f32 v28, v28, v31
	s_waitcnt lgkmcnt(4)
	v_cvt_pk_bf16_f32 v29, v29, v32
	s_waitcnt lgkmcnt(3)
	v_cvt_pk_bf16_f32 v31, v34, v33
	s_waitcnt lgkmcnt(2)
	v_cvt_pk_bf16_f32 v32, v35, v36
	s_waitcnt lgkmcnt(1)
	v_cvt_pk_bf16_f32 v33, v38, v37
	s_waitcnt lgkmcnt(0)
	v_cvt_pk_bf16_f32 v34, v39, v40
	global_store_dword v[52:53], v28, off
	global_store_dword v[46:47], v29, off
	global_store_dword v[54:55], v31, off
	global_store_dword v[48:49], v32, off
	global_store_dword v[56:57], v33, off
	global_store_dword v[50:51], v34, off
	v_add_u32_e32 v28, s36, v16
	v_cvt_pk_bf16_f32 v30, v30, v41
	v_cmp_gt_u32_e32 vcc, s24, v28
	global_store_dword v[44:45], v30, off
	s_and_saveexec_b64 s[6:7], vcc
	s_cbranch_execz .LBB0_1165
	ds_read2_b32 v[30:31], v12 offset0:112 offset1:241
	v_lshlrev_b32_e32 v28, 1, v28
	v_and_or_b32 v28, v28, s33, v16
	v_mov_b32_e32 v29, v1
	v_lshl_or_b32 v28, v28, 11, v27
	s_waitcnt lgkmcnt(0)
	v_cvt_pk_bf16_f32 v30, v30, v31
	v_lshl_add_u64 v[6:7], v[6:7], 0, v[28:29]
	global_store_dword v[6:7], v30, off
	s_branch .LBB0_1165

; #define PG8_LAS __attribute__((address_space(3)))
;     __device__ __forceinline__ void fused(f32x4 (&acc)[2][2][4][2], const Unit& u, int wr, int wc, int fr, int fq, PG8_LAS unsigned char* lds, int wid, int lane) const {
;     ...
; #pragma unroll
;         for (int ai = 0; ai < 2; ++ai)
; #pragma unroll
;             for (int m = 0; m < 4; ++m) {
;                 const int rl = ai * 128 + wr * 64 + m * 16 + fr;
;                 const size_t roff = (size_t)(u.pm * 256 + rl) * 1024 + u.pn * 256 + wc * 32 + fq * 8;
;                 float s1 = 0.f, s2 = 0.f;
; #pragma unroll
;                 for (int bj = 0; bj < 2; ++bj) {
;                     float x[8];
;                     if (RES_BF16) ld8f((const bfu*)res + roff + bj * 128, x);
;                     else ld8f32((const float*)res + roff + bj * 128, x);
; #pragma unroll
;                     for (int n = 0; n < 2; ++n) {
;                         f32x4 v = acc[ai][bj][m][n];
;                         v[0] += ALPHA * x[4 * n]; v[1] += ALPHA * x[4 * n + 1]; v[2] += ALPHA * x[4 * n + 2]; v[3] += ALPHA * x[4 * n + 3];
;                         acc[ai][bj][m][n] = v;
;                         s1 += (v[0] + v[1]) + (v[2] + v[3]); s2 += (v[0] * v[0] + v[1] * v[1]) + (v[2] * v[2] + v[3] * v[3]);
;                     }
;                 }
;                 s1 += __shfl_xor(s1, 16); s1 += __shfl_xor(s1, 32); s2 += __shfl_xor(s2, 16); s2 += __shfl_xor(s2, 32);
;                 {
;                     PG8_LAS float* pd = (fq == 0) ? P + (rl * 4 + wc) * 2 : (PG8_LAS float*)(lds + 12288) + tid * 2;
;                     pd[0] = s1; pd[1] = s2;
.LBB0_1255:
	s_add_u32 s10, s66, 0x38b80000
	s_addc_u32 s11, s67, 0
	s_lshl_b32 s23, s43, 8
	v_add_u32_e32 v130, s23, v152
	s_lshl_b32 s8, s22, 8
	v_ashrrev_i32_e32 v131, 31, v130
	s_ashr_i32 s9, s8, 31
	v_lshlrev_b64 v[132:133], 11, v[130:131]
	v_lshl_add_u64 v[132:133], s[14:15], 0, v[132:133]
	s_lshl_b64 s[24:25], s[8:9], 1
	s_mov_b32 s21, 0
	v_lshl_add_u64 v[132:133], v[132:133], 0, s[24:25]
	s_lshl_b32 s20, s42, 6
	v_lshl_add_u64 v[132:133], v[132:133], 0, s[20:21]
	v_mov_b32_e32 v129, 0
	v_lshl_add_u64 v[132:133], v[132:133], 0, v[128:129]
	s_barrier
	global_load_dwordx4 v[134:137], v[132:133], off nt
	global_load_dwordx4 v[138:141], v[132:133], off offset:256 nt
	s_mov_b64 s[98:99], 0x8000
	v_lshl_add_u64 v[250:251], v[132:133], 0, s[98:99]
	global_load_dwordx4 v[196:199], v[250:251], off nt
	global_load_dwordx4 v[200:203], v[250:251], off offset:256 nt
	s_mov_b64 s[98:99], 0x10000
	v_lshl_add_u64 v[250:251], v[132:133], 0, s[98:99]
	global_load_dwordx4 v[204:207], v[250:251], off nt
	global_load_dwordx4 v[208:211], v[250:251], off offset:256 nt
	s_mov_b64 s[98:99], 0x18000
	v_lshl_add_u64 v[250:251], v[132:133], 0, s[98:99]
	global_load_dwordx4 v[212:215], v[250:251], off nt
	global_load_dwordx4 v[216:219], v[250:251], off offset:256 nt
	s_mov_b64 s[98:99], 0x40000
	v_lshl_add_u64 v[250:251], v[132:133], 0, s[98:99]
	global_load_dwordx4 v[220:223], v[250:251], off nt
	global_load_dwordx4 v[224:227], v[250:251], off offset:256 nt
	s_mov_b64 s[98:99], 0x48000
	v_lshl_add_u64 v[250:251], v[132:133], 0, s[98:99]
	global_load_dwordx4 v[228:231], v[250:251], off nt
	global_load_dwordx4 v[232:235], v[250:251], off offset:256 nt
	s_mov_b64 s[98:99], 0x50000
	v_lshl_add_u64 v[250:251], v[132:133], 0, s[98:99]
	global_load_dwordx4 v[236:239], v[250:251], off nt
	global_load_dwordx4 v[240:243], v[250:251], off offset:256 nt
	v_readlane_b32 s98, v252, 6
	v_readlane_b32 s99, v252, 7
	s_nop 3
	s_and_saveexec_b64 s[100:101], s[98:99]
	s_cbranch_execz .Lpub_skip_p10
	s_lshl_b32 s98, s2, 2
	s_andn2_b32 s98, s98, 63
	s_lshl_b32 s98, s98, 2
	s_add_u32 s98, s3, s98
	s_addc_u32 s99, s33, 0
	v_mov_b32_e32 v253, 0
	v_mov_b32_e32 v254, 1
	global_atomic_add v253, v254, s[98:99]
.Lpub_skip_p10:
	s_mov_b64 exec, s[100:101]
	s_mov_b64 s[98:99], 0x58000
	v_lshl_add_u64 v[244:245], v[132:133], 0, s[98:99]
	v_lshl_add_u64 v[248:249], v[132:133], 0, s[98:99]
	global_load_dwordx4 v[244:247], v[244:245], off nt
	global_load_dwordx4 v[248:251], v[248:249], off offset:256 nt
	v_mbcnt_lo_u32_b32 v132, -1, 0
	v_mbcnt_hi_u32_b32 v142, -1, v132
	v_and_b32_e32 v133, 64, v142
	v_or_b32_e32 v153, 16, v152
	v_xor_b32_e32 v143, 16, v142
	v_add_u32_e32 v145, 64, v133
	v_xor_b32_e32 v144, 32, v142
	v_add_u32_e32 v132, s23, v153
	v_cmp_lt_i32_e32 vcc, v143, v145
	v_ashrrev_i32_e32 v133, 31, v132
	s_mov_b32 s6, 0x3f9837f0
	v_cndmask_b32_e32 v146, v142, v143, vcc
	v_cmp_lt_i32_e32 vcc, v144, v145
	v_lshlrev_b32_e32 v151, 2, v146
	s_waitcnt vmcnt(0)
	v_lshlrev_b32_e32 v154, 16, v135
	v_cndmask_b32_e32 v144, v142, v144, vcc
	v_lshlrev_b64 v[142:143], 11, v[132:133]
	v_lshl_add_u64 v[142:143], s[14:15], 0, v[142:143]
	v_lshl_add_u64 v[142:143], v[142:143], 0, s[24:25]
	v_lshl_add_u64 v[142:143], v[142:143], 0, s[20:21]
	v_lshl_add_u64 v[146:147], v[142:143], 0, v[128:129]
	v_lshlrev_b32_e32 v149, 2, v144
	s_waitcnt vmcnt(0)
	v_mov_b64_e32 v[142:143], v[196:197]
	v_mov_b64_e32 v[144:145], v[198:199]
	v_mov_b64_e32 v[158:159], v[200:201]
	v_mov_b64_e32 v[160:161], v[202:203]
	v_lshlrev_b32_e32 v146, 16, v134
	v_and_b32_e32 v147, 0xffff0000, v134
	v_and_b32_e32 v155, 0xffff0000, v135
	v_lshlrev_b32_e32 v156, 16, v136
	v_and_b32_e32 v157, 0xffff0000, v136
	v_lshlrev_b32_e32 v136, 16, v137
	v_and_b32_e32 v137, 0xffff0000, v137
	v_lshlrev_b32_e32 v162, 16, v138
	v_and_b32_e32 v163, 0xffff0000, v138
	v_lshlrev_b32_e32 v138, 16, v139
	v_and_b32_e32 v139, 0xffff0000, v139
	v_lshlrev_b32_e32 v164, 16, v140
	v_and_b32_e32 v165, 0xffff0000, v140
	v_lshlrev_b32_e32 v140, 16, v141
	v_and_b32_e32 v141, 0xffff0000, v141
	v_pk_fma_f32 v[134:135], v[146:147], s[6:7], v[124:125] op_sel_hi:[1,0,1]
	v_pk_fma_f32 v[126:127], v[154:155], s[6:7], v[126:127] op_sel_hi:[1,0,1]
	v_pk_fma_f32 v[124:125], v[156:157], s[6:7], v[120:121] op_sel_hi:[1,0,1]
	v_pk_fma_f32 v[122:123], v[136:137], s[6:7], v[122:123] op_sel_hi:[1,0,1]
	v_pk_fma_f32 v[120:121], v[162:163], s[6:7], v[116:117] op_sel_hi:[1,0,1]
	v_pk_fma_f32 v[118:119], v[138:139], s[6:7], v[118:119] op_sel_hi:[1,0,1]
	v_pk_fma_f32 v[116:117], v[164:165], s[6:7], v[112:113] op_sel_hi:[1,0,1]
	v_pk_fma_f32 v[112:113], v[140:141], s[6:7], v[114:115] op_sel_hi:[1,0,1]
	v_pk_add_f32 v[114:115], v[134:135], v[134:135] op_sel:[0,1] op_sel_hi:[1,0]
	v_pk_add_f32 v[136:137], v[126:127], v[126:127] op_sel:[0,1] op_sel_hi:[1,0]
	v_pk_mul_f32 v[138:139], v[134:135], v[134:135]
	v_pk_mul_f32 v[140:141], v[126:127], v[126:127]
	v_pk_mul_f32 v[146:147], v[124:125], v[124:125]
	v_mul_f32_e32 v148, v122, v122
	v_mov_b32_e32 v166, v124
	v_mov_b32_e32 v168, v122
	v_pk_fma_f32 v[174:175], v[122:123], v[122:123], v[148:149] op_sel_hi:[1,1,0]
	v_mov_b32_e32 v167, v138
	v_mov_b32_e32 v138, v125
	v_mov_b32_e32 v169, v140
	v_mov_b32_e32 v140, v123
	v_mov_b32_e32 v115, v146
	v_mov_b32_e32 v137, v147
	v_pk_add_f32 v[138:139], v[166:167], v[138:139]
	v_pk_add_f32 v[140:141], v[168:169], v[140:141]
	v_pk_add_f32 v[114:115], v[114:115], v[136:137]
	v_mov_b32_e32 v174, v129
	v_pk_mul_f32 v[154:155], v[120:121], v[120:121]
	v_pk_mul_f32 v[156:157], v[118:119], v[118:119]
	v_pk_add_f32 v[138:139], v[138:139], v[140:141]
	v_pk_add_f32 v[114:115], v[114:115], v[174:175]
	v_mov_b32_e32 v170, v120
	v_mov_b32_e32 v171, v154
	v_mov_b32_e32 v154, v121
	v_pk_add_f32 v[114:115], v[138:139], v[114:115]
	v_mov_b32_e32 v138, v118
	v_mov_b32_e32 v139, v156
	v_mov_b32_e32 v156, v119
	v_pk_add_f32 v[136:137], v[170:171], v[154:155]
	v_pk_add_f32 v[138:139], v[138:139], v[156:157]
	v_pk_mul_f32 v[162:163], v[116:117], v[116:117]
	v_pk_mul_f32 v[164:165], v[112:113], v[112:113]
	v_pk_add_f32 v[136:137], v[136:137], v[138:139]
	v_mov_b32_e32 v138, v112
	v_pk_add_f32 v[114:115], v[114:115], v[136:137]
	v_mov_b32_e32 v136, v116
	v_mov_b32_e32 v137, v162
	v_mov_b32_e32 v162, v117
	v_mov_b32_e32 v139, v164
	v_mov_b32_e32 v164, v113
	v_pk_add_f32 v[136:137], v[136:137], v[162:163]
	v_pk_add_f32 v[138:139], v[138:139], v[164:165]
	v_or_b32_e32 v154, 32, v152
	v_pk_add_f32 v[136:137], v[136:137], v[138:139]
	s_lshl_b32 s7, s42, 3
	v_pk_add_f32 v[114:115], v[114:115], v[136:137]
	ds_bpermute_b32 v136, v151, v114
	ds_bpermute_b32 v137, v151, v115
	s_add_i32 s7, s7, 0
	v_lshl_add_u32 v148, v172, 3, 0
	v_add_u32_e32 v156, 0x3000, v148
	v_lshl_add_u32 v155, v152, 5, s7
	s_waitcnt lgkmcnt(0)
; #define PG8_LAS __attribute__((address_space(3)))
;     __device__ __forceinline__ void fused(f32x4 (&acc)[2][2][4][2], const Unit& u, int wr, int wc, int fr, int fq, PG8_LAS unsigned char* lds, int wid, int lane) const {
;     ...
;             for (int m = 0; m < 4; ++m) {
;                 const int rl = ai * 128 + wr * 64 + m * 16 + fr;
;                 const size_t roff = (size_t)(u.pm * 256 + rl) * 1024 + u.pn * 256 + wc * 32 + fq * 8;
;                 float s1 = 0.f, s2 = 0.f;
; #pragma unroll
;                 for (int bj = 0; bj < 2; ++bj) {
;                     float x[8];
;                     if (RES_BF16) ld8f((const bfu*)res + roff + bj * 128, x);
;                     else ld8f32((const float*)res + roff + bj * 128, x);
; #pragma unroll
;                     for (int n = 0; n < 2; ++n) {
;                         f32x4 v = acc[ai][bj][m][n];
;                         v[0] += ALPHA * x[4 * n]; v[1] += ALPHA * x[4 * n + 1]; v[2] += ALPHA * x[4 * n + 2]; v[3] += ALPHA * x[4 * n + 3];
;                         acc[ai][bj][m][n] = v;
;                         s1 += (v[0] + v[1]) + (v[2] + v[3]); s2 += (v[0] * v[0] + v[1] * v[1]) + (v[2] * v[2] + v[3] * v[3]);
;                     }
;                 }
;                 s1 += __shfl_xor(s1, 16); s1 += __shfl_xor(s1, 32); s2 += __shfl_xor(s2, 16); s2 += __shfl_xor(s2, 32);
;                 {
;                     PG8_LAS float* pd = (fq == 0) ? P + (rl * 4 + wc) * 2 : (PG8_LAS float*)(lds + 12288) + tid * 2;
;                     pd[0] = s1; pd[1] = s2;
	v_pk_add_f32 v[138:139], v[114:115], v[136:137]
	v_add_u32_e32 v136, s23, v154
	v_ashrrev_i32_e32 v137, 31, v136
	v_lshlrev_b64 v[140:141], 11, v[136:137]
	v_lshl_add_u64 v[140:141], s[14:15], 0, v[140:141]
	v_lshl_add_u64 v[140:141], v[140:141], 0, s[24:25]
	v_lshl_add_u64 v[140:141], v[140:141], 0, s[20:21]
	v_lshl_add_u64 v[140:141], v[140:141], 0, v[128:129]
	v_mov_b64_e32 v[162:163], v[204:205]
	v_mov_b64_e32 v[164:165], v[206:207]
	s_waitcnt vmcnt(2)
	v_lshlrev_b32_e32 v166, 16, v144
	v_and_b32_e32 v167, 0xffff0000, v144
	v_lshlrev_b32_e32 v144, 16, v145
	v_and_b32_e32 v145, 0xffff0000, v145
	v_lshlrev_b32_e32 v114, 16, v142
	v_and_b32_e32 v115, 0xffff0000, v142
	v_lshlrev_b32_e32 v142, 16, v143
	v_and_b32_e32 v143, 0xffff0000, v143
	v_pk_fma_f32 v[106:107], v[144:145], s[6:7], v[106:107] op_sel_hi:[1,0,1]
	v_pk_fma_f32 v[114:115], v[114:115], s[6:7], v[108:109] op_sel_hi:[1,0,1]
	v_pk_fma_f32 v[110:111], v[142:143], s[6:7], v[110:111] op_sel_hi:[1,0,1]
	v_pk_fma_f32 v[108:109], v[166:167], s[6:7], v[104:105] op_sel_hi:[1,0,1]
	v_mul_f32_e32 v104, v106, v106
	v_pk_add_f32 v[168:169], v[114:115], v[114:115] op_sel:[0,1] op_sel_hi:[1,0]
	v_pk_add_f32 v[170:171], v[110:111], v[110:111] op_sel:[0,1] op_sel_hi:[1,0]
	v_pk_mul_f32 v[144:145], v[108:109], v[108:109]
	v_pk_fma_f32 v[166:167], v[106:107], v[106:107], v[104:105] op_sel_hi:[1,1,0]
	s_waitcnt vmcnt(1)
	v_lshlrev_b32_e32 v104, 16, v158
	v_and_b32_e32 v105, 0xffff0000, v158
	v_pk_mul_f32 v[174:175], v[114:115], v[114:115]
	v_lshlrev_b32_e32 v158, 16, v159
	v_and_b32_e32 v159, 0xffff0000, v159
	v_lshlrev_b32_e32 v178, 16, v160
	v_and_b32_e32 v179, 0xffff0000, v160
	v_pk_fma_f32 v[100:101], v[104:105], s[6:7], v[100:101] op_sel_hi:[1,0,1]
	v_mov_b32_e32 v169, v144
	v_mov_b32_e32 v171, v145
	v_pk_mul_f32 v[176:177], v[110:111], v[110:111]
	v_pk_fma_f32 v[104:105], v[158:159], s[6:7], v[102:103] op_sel_hi:[1,0,1]
	v_pk_mul_f32 v[158:159], v[100:101], v[100:101]
	v_pk_fma_f32 v[102:103], v[178:179], s[6:7], v[96:97] op_sel_hi:[1,0,1]
	v_mov_b32_e32 v178, v108
	v_mov_b32_e32 v179, v174
	v_mov_b32_e32 v174, v109
	v_pk_add_f32 v[144:145], v[168:169], v[170:171]
	v_mov_b32_e32 v166, v129
	v_pk_mul_f32 v[180:181], v[104:105], v[104:105]
	v_pk_add_f32 v[174:175], v[178:179], v[174:175]
	v_mov_b32_e32 v178, v106
	v_mov_b32_e32 v179, v176
	v_mov_b32_e32 v176, v107
	v_pk_add_f32 v[144:145], v[144:145], v[166:167]
	v_mov_b32_e32 v166, v100
	v_mov_b32_e32 v167, v158
	v_mov_b32_e32 v158, v101
	v_pk_add_f32 v[176:177], v[178:179], v[176:177]
	v_pk_add_f32 v[158:159], v[166:167], v[158:159]
	v_mov_b32_e32 v166, v104
	v_mov_b32_e32 v167, v180
	v_mov_b32_e32 v180, v105
	v_lshlrev_b32_e32 v160, 16, v161
	v_and_b32_e32 v161, 0xffff0000, v161
	v_pk_add_f32 v[174:175], v[174:175], v[176:177]
	v_pk_add_f32 v[166:167], v[166:167], v[180:181]
	v_pk_fma_f32 v[96:97], v[160:161], s[6:7], v[98:99] op_sel_hi:[1,0,1]
	v_pk_mul_f32 v[98:99], v[102:103], v[102:103]
	v_pk_add_f32 v[144:145], v[174:175], v[144:145]
	v_pk_add_f32 v[158:159], v[158:159], v[166:167]
	v_pk_mul_f32 v[160:161], v[96:97], v[96:97]
	v_pk_add_f32 v[144:145], v[144:145], v[158:159]
	v_mov_b32_e32 v158, v102
	v_mov_b32_e32 v159, v98
	v_mov_b32_e32 v98, v103
	v_pk_add_f32 v[98:99], v[158:159], v[98:99]
	v_mov_b32_e32 v158, v96
	v_mov_b32_e32 v159, v160
	v_mov_b32_e32 v160, v97
	v_pk_add_f32 v[158:159], v[158:159], v[160:161]
	ds_bpermute_b32 v146, v149, v138
	ds_bpermute_b32 v147, v149, v139
	v_pk_add_f32 v[98:99], v[98:99], v[158:159]
	v_cmp_eq_u32_e32 vcc, 0, v150
	v_pk_add_f32 v[98:99], v[144:145], v[98:99]
	ds_bpermute_b32 v144, v151, v98
	ds_bpermute_b32 v145, v151, v99
	v_cndmask_b32_e32 v157, v156, v155, vcc
	v_or_b32_e32 v155, 48, v152
	s_waitcnt lgkmcnt(2)
	v_pk_add_f32 v[166:167], v[138:139], v[146:147]
	v_add_u32_e32 v138, s23, v155
	v_ashrrev_i32_e32 v139, 31, v138
	s_waitcnt lgkmcnt(0)
	v_pk_add_f32 v[168:169], v[98:99], v[144:145]
	v_lshlrev_b64 v[144:145], 11, v[138:139]
	v_lshl_add_u64 v[144:145], s[14:15], 0, v[144:145]
	v_lshl_add_u64 v[144:145], v[144:145], 0, s[24:25]
	v_lshl_add_u64 v[144:145], v[144:145], 0, s[20:21]
	v_lshl_add_u64 v[158:159], v[144:145], 0, v[128:129]
	v_mov_b64_e32 v[144:145], v[212:213]
	v_mov_b64_e32 v[146:147], v[214:215]
	s_waitcnt vmcnt(1)
	v_lshlrev_b32_e32 v160, 16, v163
	v_mov_b64_e32 v[140:141], v[208:209]
	v_mov_b64_e32 v[142:143], v[210:211]
	v_and_b32_e32 v161, 0xffff0000, v163
	v_pk_fma_f32 v[94:95], v[160:161], s[6:7], v[94:95] op_sel_hi:[1,0,1]
	v_mov_b64_e32 v[158:159], v[216:217]
	v_mov_b64_e32 v[160:161], v[218:219]
	v_lshlrev_b32_e32 v98, 16, v162
	v_and_b32_e32 v99, 0xffff0000, v162
	v_lshlrev_b32_e32 v162, 16, v164
	v_and_b32_e32 v163, 0xffff0000, v164
	v_lshlrev_b32_e32 v164, 16, v165
	v_and_b32_e32 v165, 0xffff0000, v165
	v_pk_fma_f32 v[90:91], v[164:165], s[6:7], v[90:91] op_sel_hi:[1,0,1]
	v_pk_fma_f32 v[98:99], v[98:99], s[6:7], v[92:93] op_sel_hi:[1,0,1]
	v_pk_fma_f32 v[92:93], v[162:163], s[6:7], v[88:89] op_sel_hi:[1,0,1]
	v_mul_f32_e32 v88, v90, v90
	v_pk_add_f32 v[174:175], v[98:99], v[98:99] op_sel:[0,1] op_sel_hi:[1,0]
	v_pk_add_f32 v[176:177], v[94:95], v[94:95] op_sel:[0,1] op_sel_hi:[1,0]
	v_pk_mul_f32 v[162:163], v[92:93], v[92:93]
	v_pk_fma_f32 v[164:165], v[90:91], v[90:91], v[88:89] op_sel_hi:[1,1,0]
	v_pk_mul_f32 v[178:179], v[98:99], v[98:99]
	v_mov_b32_e32 v175, v162
	v_mov_b32_e32 v177, v163
	v_pk_mul_f32 v[180:181], v[94:95], v[94:95]
	v_pk_add_f32 v[162:163], v[174:175], v[176:177]
	v_mov_b32_e32 v164, v129
	v_pk_add_f32 v[162:163], v[162:163], v[164:165]
	ds_write_b64 v157, v[166:167]
	v_add_u32_e32 v157, 0x80, v152
	ds_bpermute_b32 v170, v149, v168
	ds_bpermute_b32 v171, v149, v169
	s_waitcnt vmcnt(2)
; #define PG8_LAS __attribute__((address_space(3)))
;     __device__ __forceinline__ void fused(f32x4 (&acc)[2][2][4][2], const Unit& u, int wr, int wc, int fr, int fq, PG8_LAS unsigned char* lds, int wid, int lane) const {
;     ...
;                 for (int bj = 0; bj < 2; ++bj) {
;                     float x[8];
;                     if (RES_BF16) ld8f((const bfu*)res + roff + bj * 128, x);
;                     else ld8f32((const float*)res + roff + bj * 128, x);
; #pragma unroll
;                     for (int n = 0; n < 2; ++n) {
;                         f32x4 v = acc[ai][bj][m][n];
;                         v[0] += ALPHA * x[4 * n]; v[1] += ALPHA * x[4 * n + 1]; v[2] += ALPHA * x[4 * n + 2]; v[3] += ALPHA * x[4 * n + 3];
;                         acc[ai][bj][m][n] = v;
;                         s1 += (v[0] + v[1]) + (v[2] + v[3]); s2 += (v[0] * v[0] + v[1] * v[1]) + (v[2] * v[2] + v[3] * v[3]);
;                     }
;                 }
;                 s1 += __shfl_xor(s1, 16); s1 += __shfl_xor(s1, 32); s2 += __shfl_xor(s2, 16); s2 += __shfl_xor(s2, 32);
;                 {
;                     PG8_LAS float* pd = (fq == 0) ? P + (rl * 4 + wc) * 2 : (PG8_LAS float*)(lds + 12288) + tid * 2;
;                     pd[0] = s1; pd[1] = s2;
;                 }
	v_lshlrev_b32_e32 v174, 16, v146
	v_and_b32_e32 v175, 0xffff0000, v146
	s_waitcnt vmcnt(1)
	v_lshlrev_b32_e32 v88, 16, v140
	v_and_b32_e32 v89, 0xffff0000, v140
	v_lshlrev_b32_e32 v140, 16, v141
	v_and_b32_e32 v141, 0xffff0000, v141
	v_lshlrev_b32_e32 v182, 16, v142
	v_and_b32_e32 v183, 0xffff0000, v142
	v_pk_fma_f32 v[84:85], v[88:89], s[6:7], v[84:85] op_sel_hi:[1,0,1]
	v_pk_fma_f32 v[88:89], v[140:141], s[6:7], v[86:87] op_sel_hi:[1,0,1]
	v_pk_mul_f32 v[140:141], v[84:85], v[84:85]
	v_pk_fma_f32 v[86:87], v[182:183], s[6:7], v[80:81] op_sel_hi:[1,0,1]
	v_mov_b32_e32 v182, v92
	v_mov_b32_e32 v183, v178
	v_mov_b32_e32 v178, v93
	v_pk_mul_f32 v[184:185], v[88:89], v[88:89]
	v_pk_add_f32 v[178:179], v[182:183], v[178:179]
	v_mov_b32_e32 v182, v90
	v_mov_b32_e32 v183, v180
	v_mov_b32_e32 v180, v91
	v_mov_b32_e32 v164, v84
	v_mov_b32_e32 v165, v140
	v_mov_b32_e32 v140, v85
	v_pk_add_f32 v[180:181], v[182:183], v[180:181]
	v_pk_add_f32 v[140:141], v[164:165], v[140:141]
	v_mov_b32_e32 v164, v88
	v_mov_b32_e32 v165, v184
	v_mov_b32_e32 v184, v89
	v_lshlrev_b32_e32 v142, 16, v143
	v_and_b32_e32 v143, 0xffff0000, v143
	v_pk_add_f32 v[178:179], v[178:179], v[180:181]
	v_pk_add_f32 v[164:165], v[164:165], v[184:185]
	v_pk_fma_f32 v[80:81], v[142:143], s[6:7], v[82:83] op_sel_hi:[1,0,1]
	v_pk_mul_f32 v[82:83], v[86:87], v[86:87]
	v_pk_add_f32 v[162:163], v[178:179], v[162:163]
	v_pk_add_f32 v[140:141], v[140:141], v[164:165]
	v_pk_mul_f32 v[142:143], v[80:81], v[80:81]
	v_pk_add_f32 v[140:141], v[162:163], v[140:141]
	v_mov_b32_e32 v162, v86
	v_mov_b32_e32 v163, v82
	v_mov_b32_e32 v82, v87
	v_pk_add_f32 v[82:83], v[162:163], v[82:83]
	v_mov_b32_e32 v162, v80
	v_mov_b32_e32 v163, v142
	v_mov_b32_e32 v142, v81
	v_pk_add_f32 v[142:143], v[162:163], v[142:143]
	v_lshlrev_b32_e32 v146, 16, v147
	v_pk_add_f32 v[82:83], v[82:83], v[142:143]
	v_and_b32_e32 v147, 0xffff0000, v147
	v_pk_add_f32 v[82:83], v[140:141], v[82:83]
	ds_bpermute_b32 v140, v151, v82
	ds_bpermute_b32 v141, v151, v83
	v_pk_fma_f32 v[74:75], v[146:147], s[6:7], v[74:75] op_sel_hi:[1,0,1]
	v_lshl_add_u32 v142, v153, 5, s7
	v_cndmask_b32_e32 v173, v156, v142, vcc
	s_waitcnt lgkmcnt(2)
	v_pk_add_f32 v[142:143], v[168:169], v[170:171]
	s_waitcnt lgkmcnt(0)
	v_pk_add_f32 v[166:167], v[82:83], v[140:141]
	v_add_u32_e32 v140, s23, v157
	v_ashrrev_i32_e32 v141, 31, v140
	v_lshlrev_b32_e32 v82, 16, v144
	v_lshlrev_b64 v[162:163], 11, v[140:141]
	v_and_b32_e32 v83, 0xffff0000, v144
	v_lshl_add_u64 v[162:163], s[14:15], 0, v[162:163]
	v_lshlrev_b32_e32 v144, 16, v145
	v_and_b32_e32 v145, 0xffff0000, v145
	v_pk_fma_f32 v[82:83], v[82:83], s[6:7], v[76:77] op_sel_hi:[1,0,1]
	v_pk_fma_f32 v[76:77], v[174:175], s[6:7], v[72:73] op_sel_hi:[1,0,1]
	v_mul_f32_e32 v72, v74, v74
	v_lshl_add_u64 v[162:163], v[162:163], 0, s[24:25]
	v_pk_fma_f32 v[78:79], v[144:145], s[6:7], v[78:79] op_sel_hi:[1,0,1]
	v_pk_fma_f32 v[184:185], v[74:75], v[74:75], v[72:73] op_sel_hi:[1,1,0]
	s_waitcnt vmcnt(0)
	v_lshlrev_b32_e32 v72, 16, v158
	v_and_b32_e32 v73, 0xffff0000, v158
	v_lshl_add_u64 v[162:163], v[162:163], 0, s[20:21]
	v_pk_add_f32 v[176:177], v[82:83], v[82:83] op_sel:[0,1] op_sel_hi:[1,0]
	v_pk_add_f32 v[178:179], v[78:79], v[78:79] op_sel:[0,1] op_sel_hi:[1,0]
	v_pk_mul_f32 v[174:175], v[76:77], v[76:77]
	v_lshlrev_b32_e32 v158, 16, v159
	v_and_b32_e32 v159, 0xffff0000, v159
	v_pk_fma_f32 v[68:69], v[72:73], s[6:7], v[68:69] op_sel_hi:[1,0,1]
	v_lshl_add_u64 v[170:171], v[162:163], 0, v[128:129]
	v_pk_fma_f32 v[72:73], v[158:159], s[6:7], v[70:71] op_sel_hi:[1,0,1]
	v_pk_mul_f32 v[158:159], v[68:69], v[68:69]
	v_mov_b32_e32 v177, v174
	v_mov_b32_e32 v179, v175
	v_mov_b64_e32 v[162:163], v[220:221]
	v_mov_b64_e32 v[164:165], v[222:223]
	v_mov_b64_e32 v[144:145], v[224:225]
	v_mov_b64_e32 v[146:147], v[226:227]
	v_pk_mul_f32 v[180:181], v[82:83], v[82:83]
	v_lshlrev_b32_e32 v186, 16, v160
	v_and_b32_e32 v187, 0xffff0000, v160
	v_pk_mul_f32 v[170:171], v[72:73], v[72:73]
	v_pk_add_f32 v[174:175], v[176:177], v[178:179]
	v_mov_b32_e32 v176, v68
	v_mov_b32_e32 v177, v158
	v_mov_b32_e32 v158, v69
	v_pk_mul_f32 v[182:183], v[78:79], v[78:79]
	v_lshlrev_b32_e32 v160, 16, v161
	v_and_b32_e32 v161, 0xffff0000, v161
	v_pk_fma_f32 v[70:71], v[186:187], s[6:7], v[64:65] op_sel_hi:[1,0,1]
	v_mov_b32_e32 v186, v76
	v_mov_b32_e32 v187, v180
	v_mov_b32_e32 v180, v77
	v_pk_add_f32 v[158:159], v[176:177], v[158:159]
	v_mov_b32_e32 v176, v72
	v_mov_b32_e32 v177, v170
	v_mov_b32_e32 v170, v73
	v_pk_fma_f32 v[64:65], v[160:161], s[6:7], v[66:67] op_sel_hi:[1,0,1]
	v_pk_mul_f32 v[66:67], v[70:71], v[70:71]
	v_pk_add_f32 v[180:181], v[186:187], v[180:181]
	v_mov_b32_e32 v186, v74
	v_mov_b32_e32 v187, v182
	v_mov_b32_e32 v182, v75
	v_pk_add_f32 v[170:171], v[176:177], v[170:171]
	v_pk_mul_f32 v[160:161], v[64:65], v[64:65]
	v_pk_add_f32 v[182:183], v[186:187], v[182:183]
	v_mov_b32_e32 v184, v129
	v_pk_add_f32 v[158:159], v[158:159], v[170:171]
	v_mov_b32_e32 v170, v70
	v_mov_b32_e32 v171, v66
	v_mov_b32_e32 v66, v71
	v_pk_add_f32 v[180:181], v[180:181], v[182:183]
	v_pk_add_f32 v[174:175], v[174:175], v[184:185]
	v_pk_add_f32 v[66:67], v[170:171], v[66:67]
	v_mov_b32_e32 v170, v64
	v_mov_b32_e32 v171, v160
	v_mov_b32_e32 v160, v65
	v_pk_add_f32 v[174:175], v[180:181], v[174:175]
	v_pk_add_f32 v[160:161], v[170:171], v[160:161]
	v_pk_add_f32 v[158:159], v[174:175], v[158:159]
	v_pk_add_f32 v[66:67], v[66:67], v[160:161]
	ds_write_b64 v173, v[142:143]
	v_pk_add_f32 v[66:67], v[158:159], v[66:67]
	ds_bpermute_b32 v158, v151, v66
	ds_bpermute_b32 v159, v151, v67
	v_lshl_add_u32 v142, v154, 5, s7
	v_cndmask_b32_e32 v173, v156, v142, vcc
	ds_bpermute_b32 v168, v149, v166
	ds_bpermute_b32 v169, v149, v167
	s_waitcnt lgkmcnt(2)
; #define PG8_LAS __attribute__((address_space(3)))
;     __device__ __forceinline__ void fused(f32x4 (&acc)[2][2][4][2], const Unit& u, int wr, int wc, int fr, int fq, PG8_LAS unsigned char* lds, int wid, int lane) const {
;     ...
;                 for (int bj = 0; bj < 2; ++bj) {
;                     float x[8];
;                     if (RES_BF16) ld8f((const bfu*)res + roff + bj * 128, x);
;                     else ld8f32((const float*)res + roff + bj * 128, x);
; #pragma unroll
;                     for (int n = 0; n < 2; ++n) {
;                         f32x4 v = acc[ai][bj][m][n];
;                         v[0] += ALPHA * x[4 * n]; v[1] += ALPHA * x[4 * n + 1]; v[2] += ALPHA * x[4 * n + 2]; v[3] += ALPHA * x[4 * n + 3];
;                         acc[ai][bj][m][n] = v;
;                         s1 += (v[0] + v[1]) + (v[2] + v[3]); s2 += (v[0] * v[0] + v[1] * v[1]) + (v[2] * v[2] + v[3] * v[3]);
;                     }
;                 }
;                 s1 += __shfl_xor(s1, 16); s1 += __shfl_xor(s1, 32); s2 += __shfl_xor(s2, 16); s2 += __shfl_xor(s2, 32);
;                 {
;                     PG8_LAS float* pd = (fq == 0) ? P + (rl * 4 + wc) * 2 : (PG8_LAS float*)(lds + 12288) + tid * 2;
;                     pd[0] = s1; pd[1] = s2;
;                 }
	v_pk_add_f32 v[174:175], v[66:67], v[158:159]
	v_add_u32_e32 v158, 0x90, v152
	v_add_u32_e32 v142, s23, v158
	v_ashrrev_i32_e32 v143, 31, v142
	v_lshlrev_b64 v[160:161], 11, v[142:143]
	v_lshl_add_u64 v[160:161], s[14:15], 0, v[160:161]
	v_lshl_add_u64 v[160:161], v[160:161], 0, s[24:25]
	v_lshl_add_u64 v[160:161], v[160:161], 0, s[20:21]
	v_lshl_add_u64 v[160:161], v[160:161], 0, v[128:129]
	s_waitcnt lgkmcnt(0)
	v_pk_add_f32 v[170:171], v[166:167], v[168:169]
	v_mov_b64_e32 v[166:167], v[228:229]
	v_mov_b64_e32 v[168:169], v[230:231]
	ds_bpermute_b32 v176, v149, v174
	ds_bpermute_b32 v177, v149, v175
	ds_write_b64 v173, v[170:171]
	v_add_u32_e32 v159, 0xa0, v152
	s_waitcnt vmcnt(2)
	v_lshlrev_b32_e32 v178, 16, v164
	v_and_b32_e32 v179, 0xffff0000, v164
	v_lshlrev_b32_e32 v164, 16, v165
	v_and_b32_e32 v165, 0xffff0000, v165
	v_lshlrev_b32_e32 v66, 16, v162
	v_and_b32_e32 v67, 0xffff0000, v162
	v_lshlrev_b32_e32 v162, 16, v163
	v_and_b32_e32 v163, 0xffff0000, v163
	v_pk_fma_f32 v[58:59], v[164:165], s[6:7], v[58:59] op_sel_hi:[1,0,1]
	v_pk_fma_f32 v[66:67], v[66:67], s[6:7], v[60:61] op_sel_hi:[1,0,1]
	v_pk_fma_f32 v[62:63], v[162:163], s[6:7], v[62:63] op_sel_hi:[1,0,1]
	v_pk_fma_f32 v[60:61], v[178:179], s[6:7], v[56:57] op_sel_hi:[1,0,1]
	v_mul_f32_e32 v56, v58, v58
	v_mov_b64_e32 v[160:161], v[232:233]
	v_mov_b64_e32 v[162:163], v[234:235]
	v_pk_add_f32 v[180:181], v[66:67], v[66:67] op_sel:[0,1] op_sel_hi:[1,0]
	v_pk_add_f32 v[182:183], v[62:63], v[62:63] op_sel:[0,1] op_sel_hi:[1,0]
	v_pk_mul_f32 v[164:165], v[60:61], v[60:61]
	v_pk_fma_f32 v[178:179], v[58:59], v[58:59], v[56:57] op_sel_hi:[1,1,0]
	s_waitcnt vmcnt(2)
	v_lshlrev_b32_e32 v56, 16, v144
	v_and_b32_e32 v57, 0xffff0000, v144
	v_pk_mul_f32 v[184:185], v[66:67], v[66:67]
	v_lshlrev_b32_e32 v144, 16, v145
	v_and_b32_e32 v145, 0xffff0000, v145
	v_lshlrev_b32_e32 v188, 16, v146
	v_and_b32_e32 v189, 0xffff0000, v146
	v_pk_fma_f32 v[52:53], v[56:57], s[6:7], v[52:53] op_sel_hi:[1,0,1]
	v_mov_b32_e32 v181, v164
	v_mov_b32_e32 v183, v165
	v_pk_mul_f32 v[186:187], v[62:63], v[62:63]
	v_pk_fma_f32 v[56:57], v[144:145], s[6:7], v[54:55] op_sel_hi:[1,0,1]
	v_pk_mul_f32 v[144:145], v[52:53], v[52:53]
	v_pk_fma_f32 v[54:55], v[188:189], s[6:7], v[48:49] op_sel_hi:[1,0,1]
	v_mov_b32_e32 v188, v60
	v_mov_b32_e32 v189, v184
	v_mov_b32_e32 v184, v61
	v_pk_add_f32 v[164:165], v[180:181], v[182:183]
	v_mov_b32_e32 v178, v129
	v_pk_mul_f32 v[190:191], v[56:57], v[56:57]
	v_pk_add_f32 v[184:185], v[188:189], v[184:185]
	v_mov_b32_e32 v188, v58
	v_mov_b32_e32 v189, v186
	v_mov_b32_e32 v186, v59
	v_pk_add_f32 v[164:165], v[164:165], v[178:179]
	v_mov_b32_e32 v178, v52
	v_mov_b32_e32 v179, v144
	v_mov_b32_e32 v144, v53
	v_pk_add_f32 v[186:187], v[188:189], v[186:187]
	v_pk_add_f32 v[144:145], v[178:179], v[144:145]
	v_mov_b32_e32 v178, v56
	v_mov_b32_e32 v179, v190
	v_mov_b32_e32 v190, v57
	v_lshlrev_b32_e32 v146, 16, v147
	v_and_b32_e32 v147, 0xffff0000, v147
	v_pk_add_f32 v[184:185], v[184:185], v[186:187]
	v_pk_add_f32 v[178:179], v[178:179], v[190:191]
	v_pk_fma_f32 v[48:49], v[146:147], s[6:7], v[50:51] op_sel_hi:[1,0,1]
	v_pk_mul_f32 v[50:51], v[54:55], v[54:55]
	v_pk_add_f32 v[164:165], v[184:185], v[164:165]
	v_pk_add_f32 v[144:145], v[144:145], v[178:179]
	v_pk_mul_f32 v[146:147], v[48:49], v[48:49]
	v_pk_add_f32 v[144:145], v[164:165], v[144:145]
	v_mov_b32_e32 v164, v54
	v_mov_b32_e32 v165, v50
	v_mov_b32_e32 v50, v55
	v_pk_add_f32 v[50:51], v[164:165], v[50:51]
	v_mov_b32_e32 v164, v48
	v_mov_b32_e32 v165, v146
	v_mov_b32_e32 v146, v49
	v_pk_add_f32 v[146:147], v[164:165], v[146:147]
	s_waitcnt vmcnt(1)
	v_lshlrev_b32_e32 v164, 16, v168
	v_pk_add_f32 v[50:51], v[50:51], v[146:147]
	v_lshl_add_u32 v146, v155, 5, s7
	v_pk_add_f32 v[50:51], v[144:145], v[50:51]
	ds_bpermute_b32 v144, v151, v50
	ds_bpermute_b32 v145, v151, v51
	v_cndmask_b32_e32 v173, v156, v146, vcc
	s_waitcnt lgkmcnt(3)
	v_pk_add_f32 v[146:147], v[174:175], v[176:177]
	v_and_b32_e32 v165, 0xffff0000, v168
	v_lshlrev_b32_e32 v168, 16, v169
	s_waitcnt lgkmcnt(0)
	v_pk_add_f32 v[174:175], v[50:51], v[144:145]
	v_lshlrev_b32_e32 v144, 16, v167
	v_and_b32_e32 v145, 0xffff0000, v167
	v_pk_fma_f32 v[46:47], v[144:145], s[6:7], v[46:47] op_sel_hi:[1,0,1]
	v_add_u32_e32 v144, s23, v159
	v_lshlrev_b32_e32 v50, 16, v166
	v_and_b32_e32 v51, 0xffff0000, v166
	v_ashrrev_i32_e32 v145, 31, v144
	v_pk_fma_f32 v[50:51], v[50:51], s[6:7], v[44:45] op_sel_hi:[1,0,1]
	v_pk_fma_f32 v[44:45], v[164:165], s[6:7], v[40:41] op_sel_hi:[1,0,1]
	v_lshlrev_b64 v[40:41], 11, v[144:145]
	v_lshl_add_u64 v[40:41], s[14:15], 0, v[40:41]
	v_lshl_add_u64 v[40:41], v[40:41], 0, s[24:25]
	v_lshl_add_u64 v[40:41], v[40:41], 0, s[20:21]
	v_lshl_add_u64 v[170:171], v[40:41], 0, v[128:129]
	v_mov_b64_e32 v[164:165], v[236:237]
	v_mov_b64_e32 v[166:167], v[238:239]
	v_and_b32_e32 v169, 0xffff0000, v169
	v_pk_fma_f32 v[42:43], v[168:169], s[6:7], v[42:43] op_sel_hi:[1,0,1]
	v_pk_add_f32 v[178:179], v[50:51], v[50:51] op_sel:[0,1] op_sel_hi:[1,0]
	v_mul_f32_e32 v40, v42, v42
	v_pk_fma_f32 v[188:189], v[42:43], v[42:43], v[40:41] op_sel_hi:[1,1,0]
	s_waitcnt vmcnt(1)
; #define PG8_LAS __attribute__((address_space(3)))
;     __device__ __forceinline__ void fused(f32x4 (&acc)[2][2][4][2], const Unit& u, int wr, int wc, int fr, int fq, PG8_LAS unsigned char* lds, int wid, int lane) const {
;     ...
;                 for (int bj = 0; bj < 2; ++bj) {
;                     float x[8];
;                     if (RES_BF16) ld8f((const bfu*)res + roff + bj * 128, x);
;                     else ld8f32((const float*)res + roff + bj * 128, x);
; #pragma unroll
;                     for (int n = 0; n < 2; ++n) {
;                         f32x4 v = acc[ai][bj][m][n];
;                         v[0] += ALPHA * x[4 * n]; v[1] += ALPHA * x[4 * n + 1]; v[2] += ALPHA * x[4 * n + 2]; v[3] += ALPHA * x[4 * n + 3];
;                         acc[ai][bj][m][n] = v;
;                         s1 += (v[0] + v[1]) + (v[2] + v[3]); s2 += (v[0] * v[0] + v[1] * v[1]) + (v[2] * v[2] + v[3] * v[3]);
;                     }
;                 }
;                 s1 += __shfl_xor(s1, 16); s1 += __shfl_xor(s1, 32); s2 += __shfl_xor(s2, 16); s2 += __shfl_xor(s2, 32);
;                 {
;                     PG8_LAS float* pd = (fq == 0) ? P + (rl * 4 + wc) * 2 : (PG8_LAS float*)(lds + 12288) + tid * 2;
;                     pd[0] = s1; pd[1] = s2;
;                 }
	v_lshlrev_b32_e32 v40, 16, v160
	v_and_b32_e32 v41, 0xffff0000, v160
	v_pk_add_f32 v[180:181], v[46:47], v[46:47] op_sel:[0,1] op_sel_hi:[1,0]
	v_pk_mul_f32 v[182:183], v[50:51], v[50:51]
	v_pk_mul_f32 v[186:187], v[44:45], v[44:45]
	v_lshlrev_b32_e32 v160, 16, v161
	v_and_b32_e32 v161, 0xffff0000, v161
	v_pk_fma_f32 v[40:41], v[40:41], s[6:7], v[36:37] op_sel_hi:[1,0,1]
	v_pk_mul_f32 v[184:185], v[46:47], v[46:47]
	v_pk_fma_f32 v[38:39], v[160:161], s[6:7], v[38:39] op_sel_hi:[1,0,1]
	v_pk_mul_f32 v[160:161], v[40:41], v[40:41]
	v_mov_b32_e32 v192, v44
	v_mov_b32_e32 v193, v182
	v_mov_b32_e32 v182, v45
	v_mov_b32_e32 v179, v186
	v_mov_b32_e32 v181, v187
	v_pk_mul_f32 v[190:191], v[38:39], v[38:39]
	v_pk_add_f32 v[182:183], v[192:193], v[182:183]
	v_mov_b32_e32 v192, v42
	v_mov_b32_e32 v193, v184
	v_mov_b32_e32 v184, v43
	v_pk_add_f32 v[178:179], v[178:179], v[180:181]
	v_mov_b32_e32 v180, v40
	v_mov_b32_e32 v181, v160
	v_mov_b32_e32 v160, v41
	v_lshlrev_b32_e32 v168, 16, v162
	v_and_b32_e32 v169, 0xffff0000, v162
	v_pk_add_f32 v[184:185], v[192:193], v[184:185]
	v_mov_b32_e32 v188, v129
	v_pk_add_f32 v[160:161], v[180:181], v[160:161]
	v_mov_b32_e32 v180, v38
	v_mov_b32_e32 v181, v190
	v_mov_b32_e32 v190, v39
	v_lshlrev_b32_e32 v162, 16, v163
	v_and_b32_e32 v163, 0xffff0000, v163
	v_pk_fma_f32 v[36:37], v[168:169], s[6:7], v[32:33] op_sel_hi:[1,0,1]
	v_pk_add_f32 v[182:183], v[182:183], v[184:185]
	v_pk_add_f32 v[178:179], v[178:179], v[188:189]
	v_pk_add_f32 v[180:181], v[180:181], v[190:191]
	v_pk_fma_f32 v[32:33], v[162:163], s[6:7], v[34:35] op_sel_hi:[1,0,1]
	v_pk_mul_f32 v[34:35], v[36:37], v[36:37]
	v_pk_add_f32 v[178:179], v[182:183], v[178:179]
	v_pk_add_f32 v[160:161], v[160:161], v[180:181]
	v_pk_mul_f32 v[162:163], v[32:33], v[32:33]
	v_pk_add_f32 v[160:161], v[178:179], v[160:161]
	v_mov_b32_e32 v178, v36
	v_mov_b32_e32 v179, v34
	v_mov_b32_e32 v34, v37
	v_pk_add_f32 v[34:35], v[178:179], v[34:35]
	v_mov_b32_e32 v178, v32
	v_mov_b32_e32 v179, v162
	v_mov_b32_e32 v162, v33
	v_pk_add_f32 v[162:163], v[178:179], v[162:163]
	ds_bpermute_b32 v176, v149, v174
	v_pk_add_f32 v[34:35], v[34:35], v[162:163]
	ds_bpermute_b32 v177, v149, v175
	v_pk_add_f32 v[34:35], v[160:161], v[34:35]
	ds_bpermute_b32 v160, v151, v34
	ds_bpermute_b32 v161, v151, v35
	v_mov_b64_e32 v[168:169], v[240:241]
	v_mov_b64_e32 v[170:171], v[242:243]
	ds_write_b64 v173, v[146:147]
	v_lshl_add_u32 v146, v157, 5, s7
	v_cndmask_b32_e32 v173, v156, v146, vcc
	s_waitcnt lgkmcnt(1)
	v_pk_add_f32 v[34:35], v[34:35], v[160:161]
	v_add_u32_e32 v160, 0xb0, v152
	v_add_u32_e32 v146, s23, v160
	v_ashrrev_i32_e32 v147, 31, v146
	v_pk_add_f32 v[162:163], v[174:175], v[176:177]
	ds_bpermute_b32 v178, v149, v34
	ds_bpermute_b32 v179, v149, v35
	v_lshlrev_b64 v[174:175], 11, v[146:147]
	v_lshl_add_u64 v[174:175], s[14:15], 0, v[174:175]
	v_lshl_add_u64 v[174:175], v[174:175], 0, s[24:25]
	v_lshl_add_u64 v[174:175], v[174:175], 0, s[20:21]
	v_lshl_add_u64 v[180:181], v[174:175], 0, v[128:129]
	v_lshl_add_u32 v128, v158, 5, s7
	v_cndmask_b32_e32 v128, v156, v128, vcc
	s_waitcnt lgkmcnt(0)
	v_pk_add_f32 v[34:35], v[34:35], v[178:179]
	s_nop 1
	v_mov_b64_e32 v[174:175], v[244:245]
	v_mov_b64_e32 v[176:177], v[246:247]
	ds_write_b64 v173, v[162:163]
	ds_write_b64 v128, v[34:35]
	s_waitcnt vmcnt(2)
	v_lshlrev_b32_e32 v34, 16, v164
	v_and_b32_e32 v35, 0xffff0000, v164
	v_lshlrev_b32_e32 v162, 16, v165
	v_and_b32_e32 v163, 0xffff0000, v165
	v_pk_fma_f32 v[34:35], v[34:35], s[6:7], v[28:29] op_sel_hi:[1,0,1]
	v_pk_fma_f32 v[28:29], v[162:163], s[6:7], v[30:31] op_sel_hi:[1,0,1]
	s_nop 1
	v_mov_b64_e32 v[162:163], v[248:249]
	v_mov_b64_e32 v[164:165], v[250:251]
	v_lshlrev_b32_e32 v178, 16, v166
	v_and_b32_e32 v179, 0xffff0000, v166
	v_lshlrev_b32_e32 v166, 16, v167
	v_and_b32_e32 v167, 0xffff0000, v167
	v_pk_fma_f32 v[26:27], v[166:167], s[6:7], v[26:27] op_sel_hi:[1,0,1]
	v_pk_fma_f32 v[30:31], v[178:179], s[6:7], v[24:25] op_sel_hi:[1,0,1]
	v_mul_f32_e32 v24, v26, v26
	v_pk_add_f32 v[182:183], v[34:35], v[34:35] op_sel:[0,1] op_sel_hi:[1,0]
	v_pk_add_f32 v[184:185], v[28:29], v[28:29] op_sel:[0,1] op_sel_hi:[1,0]
	v_pk_mul_f32 v[166:167], v[30:31], v[30:31]
	v_pk_fma_f32 v[178:179], v[26:27], v[26:27], v[24:25] op_sel_hi:[1,1,0]
	v_pk_mul_f32 v[186:187], v[34:35], v[34:35]
	v_mov_b32_e32 v183, v166
	v_mov_b32_e32 v185, v167
	v_pk_mul_f32 v[180:181], v[28:29], v[28:29]
	v_pk_add_f32 v[166:167], v[182:183], v[184:185]
	v_mov_b32_e32 v178, v129
	v_pk_add_f32 v[166:167], v[166:167], v[178:179]
	v_lshl_add_u32 v161, v159, 5, s7
	s_waitcnt vmcnt(2)
; #define PG8_LAS __attribute__((address_space(3)))
;     __device__ __forceinline__ void fused(f32x4 (&acc)[2][2][4][2], const Unit& u, int wr, int wc, int fr, int fq, PG8_LAS unsigned char* lds, int wid, int lane) const {
;     ...
;                 for (int bj = 0; bj < 2; ++bj) {
;                     float x[8];
;                     if (RES_BF16) ld8f((const bfu*)res + roff + bj * 128, x);
;                     else ld8f32((const float*)res + roff + bj * 128, x);
; #pragma unroll
;                     for (int n = 0; n < 2; ++n) {
;                         f32x4 v = acc[ai][bj][m][n];
;                         v[0] += ALPHA * x[4 * n]; v[1] += ALPHA * x[4 * n + 1]; v[2] += ALPHA * x[4 * n + 2]; v[3] += ALPHA * x[4 * n + 3];
;                         acc[ai][bj][m][n] = v;
;                         s1 += (v[0] + v[1]) + (v[2] + v[3]); s2 += (v[0] * v[0] + v[1] * v[1]) + (v[2] * v[2] + v[3] * v[3]);
;                     }
;                 }
;                 s1 += __shfl_xor(s1, 16); s1 += __shfl_xor(s1, 32); s2 += __shfl_xor(s2, 16); s2 += __shfl_xor(s2, 32);
;                 {
;                     PG8_LAS float* pd = (fq == 0) ? P + (rl * 4 + wc) * 2 : (PG8_LAS float*)(lds + 12288) + tid * 2;
;                     pd[0] = s1; pd[1] = s2;
;                 }
;             }
;         __syncthreads();
;         if (tid < 256) {
;             const float a = P[tid * 8] + P[tid * 8 + 2] + P[tid * 8 + 4] + P[tid * 8 + 6], b = P[tid * 8 + 1] + P[tid * 8 + 3] + P[tid * 8 + 5] + P[tid * 8 + 7];
;             const unsigned long long pk = (unsigned long long)__float_as_uint(a) | ((unsigned long long)__float_as_uint(b) << 32);
;             __hip_atomic_store(xch + ((size_t)(u.pm * 256 + tid) * 4 + u.pn), pk, __ATOMIC_RELAXED, __HIP_MEMORY_SCOPE_AGENT);
	v_lshlrev_b32_e32 v24, 16, v168
	v_and_b32_e32 v25, 0xffff0000, v168
	v_lshlrev_b32_e32 v168, 16, v169
	v_and_b32_e32 v169, 0xffff0000, v169
	v_lshlrev_b32_e32 v188, 16, v170
	v_and_b32_e32 v189, 0xffff0000, v170
	v_pk_fma_f32 v[24:25], v[24:25], s[6:7], v[20:21] op_sel_hi:[1,0,1]
	v_pk_fma_f32 v[22:23], v[168:169], s[6:7], v[22:23] op_sel_hi:[1,0,1]
	v_pk_mul_f32 v[168:169], v[24:25], v[24:25]
	v_pk_fma_f32 v[20:21], v[188:189], s[6:7], v[16:17] op_sel_hi:[1,0,1]
	v_mov_b32_e32 v188, v30
	v_mov_b32_e32 v189, v186
	v_mov_b32_e32 v186, v31
	v_pk_mul_f32 v[190:191], v[22:23], v[22:23]
	v_pk_add_f32 v[186:187], v[188:189], v[186:187]
	v_mov_b32_e32 v188, v26
	v_mov_b32_e32 v189, v180
	v_mov_b32_e32 v180, v27
	v_mov_b32_e32 v178, v24
	v_mov_b32_e32 v179, v168
	v_mov_b32_e32 v168, v25
	v_pk_add_f32 v[180:181], v[188:189], v[180:181]
	v_pk_add_f32 v[168:169], v[178:179], v[168:169]
	v_mov_b32_e32 v178, v22
	v_mov_b32_e32 v179, v190
	v_mov_b32_e32 v190, v23
	v_lshlrev_b32_e32 v170, 16, v171
	v_and_b32_e32 v171, 0xffff0000, v171
	v_pk_add_f32 v[180:181], v[186:187], v[180:181]
	v_pk_add_f32 v[178:179], v[178:179], v[190:191]
	v_pk_fma_f32 v[16:17], v[170:171], s[6:7], v[18:19] op_sel_hi:[1,0,1]
	v_pk_mul_f32 v[18:19], v[20:21], v[20:21]
	v_pk_add_f32 v[166:167], v[180:181], v[166:167]
	v_pk_add_f32 v[168:169], v[168:169], v[178:179]
	v_pk_mul_f32 v[170:171], v[16:17], v[16:17]
	v_pk_add_f32 v[166:167], v[166:167], v[168:169]
	v_mov_b32_e32 v168, v20
	v_mov_b32_e32 v169, v18
	v_mov_b32_e32 v18, v21
	v_pk_add_f32 v[18:19], v[168:169], v[18:19]
	v_mov_b32_e32 v168, v16
	v_mov_b32_e32 v169, v170
	v_mov_b32_e32 v170, v17
	v_pk_add_f32 v[168:169], v[168:169], v[170:171]
	s_waitcnt vmcnt(1)
	v_lshlrev_b32_e32 v170, 16, v175
	v_pk_add_f32 v[18:19], v[18:19], v[168:169]
	v_and_b32_e32 v171, 0xffff0000, v175
	v_pk_add_f32 v[166:167], v[166:167], v[18:19]
	v_lshlrev_b32_e32 v18, 16, v174
	v_and_b32_e32 v19, 0xffff0000, v174
	v_lshlrev_b32_e32 v174, 16, v176
	v_and_b32_e32 v175, 0xffff0000, v176
	v_lshlrev_b32_e32 v176, 16, v177
	v_and_b32_e32 v177, 0xffff0000, v177
	v_pk_fma_f32 v[18:19], v[18:19], s[6:7], v[12:13] op_sel_hi:[1,0,1]
	v_pk_fma_f32 v[12:13], v[170:171], s[6:7], v[14:15] op_sel_hi:[1,0,1]
	v_pk_fma_f32 v[14:15], v[174:175], s[6:7], v[8:9] op_sel_hi:[1,0,1]
	v_pk_fma_f32 v[8:9], v[176:177], s[6:7], v[10:11] op_sel_hi:[1,0,1]
	s_waitcnt vmcnt(0)
	v_lshlrev_b32_e32 v176, 16, v162
	v_and_b32_e32 v177, 0xffff0000, v162
	v_pk_mul_f32 v[180:181], v[18:19], v[18:19]
	v_mul_f32_e32 v128, v8, v8
	v_lshlrev_b32_e32 v162, 16, v163
	v_and_b32_e32 v163, 0xffff0000, v163
	v_pk_fma_f32 v[4:5], v[176:177], s[6:7], v[4:5] op_sel_hi:[1,0,1]
	v_pk_add_f32 v[170:171], v[18:19], v[18:19] op_sel:[0,1] op_sel_hi:[1,0]
	v_pk_add_f32 v[178:179], v[12:13], v[12:13] op_sel:[0,1] op_sel_hi:[1,0]
	v_pk_mul_f32 v[182:183], v[12:13], v[12:13]
	v_pk_mul_f32 v[10:11], v[14:15], v[14:15]
	v_pk_fma_f32 v[174:175], v[8:9], v[8:9], v[128:129] op_sel_hi:[1,1,0]
	v_pk_fma_f32 v[6:7], v[162:163], s[6:7], v[6:7] op_sel_hi:[1,0,1]
	v_pk_mul_f32 v[162:163], v[4:5], v[4:5]
	v_mov_b32_e32 v186, v14
	v_mov_b32_e32 v187, v180
	v_mov_b32_e32 v180, v15
	v_pk_mul_f32 v[176:177], v[6:7], v[6:7]
	v_pk_add_f32 v[180:181], v[186:187], v[180:181]
	v_mov_b32_e32 v186, v8
	v_mov_b32_e32 v187, v182
	v_mov_b32_e32 v182, v9
	v_mov_b32_e32 v171, v10
	v_mov_b32_e32 v179, v11
	v_mov_b32_e32 v174, v129
	v_mov_b32_e32 v128, v4
	v_mov_b32_e32 v129, v162
	v_mov_b32_e32 v162, v5
	v_lshlrev_b32_e32 v184, 16, v164
	v_and_b32_e32 v185, 0xffff0000, v164
	v_lshlrev_b32_e32 v164, 16, v165
	v_and_b32_e32 v165, 0xffff0000, v165
	v_pk_add_f32 v[182:183], v[186:187], v[182:183]
	v_pk_add_f32 v[10:11], v[170:171], v[178:179]
	v_pk_add_f32 v[128:129], v[128:129], v[162:163]
	v_mov_b32_e32 v162, v6
	v_mov_b32_e32 v163, v176
	v_mov_b32_e32 v176, v7
	v_pk_fma_f32 v[0:1], v[184:185], s[6:7], v[0:1] op_sel_hi:[1,0,1]
	v_pk_fma_f32 v[2:3], v[164:165], s[6:7], v[2:3] op_sel_hi:[1,0,1]
	v_pk_add_f32 v[180:181], v[180:181], v[182:183]
	v_pk_add_f32 v[10:11], v[10:11], v[174:175]
	v_pk_add_f32 v[162:163], v[162:163], v[176:177]
	v_pk_mul_f32 v[164:165], v[0:1], v[0:1]
	v_pk_mul_f32 v[184:185], v[2:3], v[2:3]
	v_pk_add_f32 v[10:11], v[180:181], v[10:11]
	v_pk_add_f32 v[128:129], v[128:129], v[162:163]
	v_mov_b32_e32 v162, v2
	v_pk_add_f32 v[10:11], v[10:11], v[128:129]
	v_mov_b32_e32 v128, v0
	v_mov_b32_e32 v129, v164
	v_mov_b32_e32 v164, v1
	v_mov_b32_e32 v163, v184
	v_mov_b32_e32 v184, v3
	v_pk_add_f32 v[128:129], v[128:129], v[164:165]
	v_pk_add_f32 v[162:163], v[162:163], v[184:185]
	ds_bpermute_b32 v168, v151, v166
	v_pk_add_f32 v[128:129], v[128:129], v[162:163]
	ds_bpermute_b32 v169, v151, v167
	v_pk_add_f32 v[10:11], v[10:11], v[128:129]
	ds_bpermute_b32 v128, v151, v10
	ds_bpermute_b32 v129, v151, v11
	v_cndmask_b32_e32 v151, v156, v161, vcc
	s_waitcnt lgkmcnt(2)
	v_pk_add_f32 v[162:163], v[166:167], v[168:169]
	ds_bpermute_b32 v164, v149, v162
	ds_bpermute_b32 v165, v149, v163
	s_waitcnt lgkmcnt(2)
	v_pk_add_f32 v[10:11], v[10:11], v[128:129]
	ds_bpermute_b32 v128, v149, v10
	ds_bpermute_b32 v129, v149, v11
	v_lshl_add_u32 v149, v160, 5, s7
	s_waitcnt lgkmcnt(2)
	v_pk_add_f32 v[162:163], v[162:163], v[164:165]
	v_cndmask_b32_e32 v149, v156, v149, vcc
	ds_write_b64 v151, v[162:163]
	s_waitcnt lgkmcnt(1)
	v_pk_add_f32 v[10:11], v[10:11], v[128:129]
	ds_write_b64 v149, v[10:11]
	s_movk_i32 s6, 0x100
	v_or_b32_e32 v10, s23, v172
	v_cmp_gt_u32_e64 s[6:7], s6, v172
	v_ashrrev_i32_e32 v11, 31, v10
	s_waitcnt lgkmcnt(0)
	s_barrier
	s_and_saveexec_b64 s[14:15], s[6:7]
	s_cbranch_execz .LBB0_1257
	v_lshl_add_u32 v128, v172, 5, 0
	ds_read_b128 v[162:165], v128
	ds_read_b128 v[166:169], v128 offset:16
	s_ashr_i32 s23, s22, 31
	s_waitcnt lgkmcnt(1)
	v_add_f32_e32 v128, v162, v164
	v_add_f32_e32 v129, v163, v165
	v_lshlrev_b64 v[162:163], 5, v[10:11]
	s_waitcnt lgkmcnt(0)
	v_add_f32_e32 v128, v128, v166
	v_add_f32_e32 v129, v129, v167
	v_lshl_add_u64 v[162:163], s[10:11], 0, v[162:163]
	v_add_f32_e32 v128, v128, v168
	v_add_f32_e32 v129, v129, v169
	v_lshl_add_u64 v[162:163], s[22:23], 3, v[162:163]
	global_store_dwordx2 v[162:163], v[128:129], off sc1
